# stack: mixing wait fixes + GEMM prologue load de-serialization + cross-attention 12 stage bodies with hoisted reads (QK kk-major), hazard-safe padding kept
# baseline (speedup 1.0000x reference)
.LBB0_29:
	s_or_b64 exec, exec, s[10:11]
	s_movk_i32 s10, 0x3c00
	v_cmp_gt_i32_e32 vcc, s10, v0
	v_mov_b32_e32 v12, 1.0
	v_mov_b32_e32 v16, 1.0
	v_mov_b32_e32 v17, 1.0
	v_mov_b32_e32 v18, 1.0
	v_mov_b32_e32 v19, 1.0
	s_and_saveexec_b64 s[10:11], vcc
	s_cbranch_execz .LBB0_31
	v_lshl_add_u64 v[14:15], v[0:1], 4, s[8:9]
	v_add_co_u32_e32 v14, vcc, 0x4000, v14
	s_nop 1
	v_addc_co_u32_e32 v15, vcc, 0, v15, vcc
	global_load_dwordx4 v[16:19], v[14:15], off

.LBB0_33:
	s_or_b64 exec, exec, s[10:11]
	v_ashrrev_i32_e32 v0, 31, v24
	v_lshrrev_b32_e32 v0, 26, v0
	v_add_u32_e32 v0, v24, v0
	v_ashrrev_i32_e32 v25, 6, v0
	v_bfe_i32 v0, v24, 27, 1
	v_lshlrev_b32_e32 v1, 4, v24
	v_lshrrev_b32_e32 v0, 22, v0
	v_add_u32_e32 v0, v1, v0
	v_and_b32_e32 v0, 0xfffffc00, v0
	v_sub_u32_e32 v0, v1, v0
	v_lshrrev_b32_e32 v3, 4, v0
	v_bitop3_b32 v0, v3, v0, 32 bitop3:0x6c
	v_ashrrev_i32_e32 v20, 31, v0
	v_lshrrev_b32_e32 v20, 26, v20
	v_add_u32_e32 v20, v0, v20
	v_lshlrev_b32_e32 v3, 3, v25
	v_ashrrev_i32_e32 v26, 6, v20
	v_and_b32_e32 v20, 0xc0, v20
	v_and_b32_e32 v3, -16, v3
	v_sub_u32_e32 v0, v0, v20
	v_mov_b32_e32 v23, 1
	s_and_b64 s[6:7], s[6:7], exec
	v_add_u32_e32 v3, v26, v3
	v_lshlrev_b32_e32 v21, 5, v25
	v_ashrrev_i16_sdwa v0, v23, sext(v0) dst_sel:DWORD dst_unused:UNUSED_PAD src0_sel:DWORD src1_sel:BYTE_0
	v_and_b32_e32 v21, 32, v21
	v_bfe_i32 v27, v0, 0, 16
	v_lshlrev_b32_e32 v0, 1, v3
	v_lshrrev_b32_e32 v20, 2, v3
	v_and_b32_e32 v22, 3, v26
	s_mov_b32 s7, 0x1fffe0
	v_and_b32_e32 v0, 24, v0
	v_and_b32_e32 v20, 4, v20
	v_and_or_b32 v22, v3, s7, v22
	v_add_lshl_u32 v21, v21, v27, 1
	v_add_u32_e32 v1, 0x2000, v1
	v_or3_b32 v20, v22, v20, v0
	v_lshl_add_u32 v0, v3, 11, v21
	v_ashrrev_i32_e32 v3, 31, v1
	v_lshrrev_b32_e32 v3, 22, v3
	v_add_u32_e32 v3, v1, v3
	v_ashrrev_i32_e32 v28, 10, v3
	v_mul_i32_i24_e32 v3, 0x400, v28
	v_sub_u32_e32 v1, v1, v3
	v_lshrrev_b32_e32 v3, 4, v1
	v_bitop3_b32 v1, v3, v1, 32 bitop3:0x6c
	v_lshl_add_u32 v180, v20, 11, v21
	v_ashrrev_i32_e32 v20, 31, v1
	v_lshrrev_b32_e32 v20, 26, v20
	s_mov_b32 s6, 0x2080000
	v_lshlrev_b32_e32 v3, 3, v28
	v_add_u32_e32 v20, v1, v20
	s_cselect_b32 s6, 0x300000, s6
	v_and_b32_e32 v3, -16, v3
	v_ashrrev_i32_e32 v29, 6, v20
	s_add_u32 s48, s20, s6
	v_add_u32_e32 v3, v29, v3
	v_and_b32_e32 v22, 3, v29
	s_addc_u32 s49, s21, 0
	v_and_b32_e32 v20, 0xc0, v20
	v_and_or_b32 v22, v3, s7, v22
	s_ashr_i32 s7, s14, 6
	s_ashr_i32 s6, s14, 8
	v_sub_u32_e32 v1, v1, v20
	s_lshl_b32 s50, s7, 10
	v_readlane_b32 s8, v252, 54
	v_ashrrev_i16_sdwa v1, v23, sext(v1) dst_sel:DWORD dst_unused:UNUSED_PAD src0_sel:DWORD src1_sel:BYTE_0
	v_readlane_b32 s9, v252, 55
	s_add_u32 s44, s48, s8
	v_lshlrev_b32_e32 v21, 5, v28
	v_bfe_i32 v30, v1, 0, 16
	v_lshlrev_b32_e32 v1, 1, v3
	v_lshrrev_b32_e32 v20, 2, v3
	s_addc_u32 s45, s49, s9
	s_add_i32 s51, s50, 0
	v_and_b32_e32 v21, 32, v21
	v_and_b32_e32 v1, 24, v1
	v_and_b32_e32 v20, 4, v20
	s_add_i32 m0, s51, 0x10000
	v_or3_b32 v1, v22, v20, v1
	v_add_lshl_u32 v20, v21, v30, 1
	global_load_lds_dwordx4 v180, s[44:45]
	s_add_i32 m0, s51, 0x12000
	v_lshl_add_u32 v134, v1, 11, v20
	s_add_u32 s8, s44, 0x40000
	global_load_lds_dwordx4 v134, s[44:45]
	s_addc_u32 s9, s45, 0
	s_add_i32 m0, s51, 0x14000
	s_add_i32 s52, s51, 0x2000
	global_load_lds_dwordx4 v180, s[8:9]
	s_add_i32 m0, s51, 0x16000
	v_lshl_add_u32 v132, v3, 11, v20
	global_load_lds_dwordx4 v134, s[8:9]
	v_readlane_b32 s8, v252, 58
	s_mov_b32 m0, s51
	v_readlane_b32 s9, v252, 59
	s_add_i32 s53, s51, 0x4000
	s_add_i32 s54, s51, 0x6000
	s_nop 4
	global_load_lds_dwordx4 v0, s[8:9]
	s_mov_b32 m0, s52
	s_nop 0
	global_load_lds_dwordx4 v132, s[8:9]
	v_readlane_b32 s8, v252, 60
	s_mov_b32 m0, s53
	v_readlane_b32 s9, v252, 61
	s_nop 4
	global_load_lds_dwordx4 v0, s[8:9]
	s_mov_b32 m0, s54
	s_nop 0
	global_load_lds_dwordx4 v132, s[8:9]
	s_waitcnt vmcnt(8)
	v_add_f32_e32 v1, v8, v9
	v_add_f32_e32 v3, v10, v11
	v_add_f32_e32 v1, v1, v3
	v_add_f32_e32 v3, v4, v5
	v_add_f32_e32 v4, v6, v7
	v_add_f32_e32 v3, v3, v4
	v_add_f32_e32 v4, v16, v17
	v_add_f32_e32 v5, v18, v19
	v_add_f32_e32 v4, v4, v5
	v_add_f32_e32 v5, v12, v13
	v_add_f32_e32 v6, v14, v15
	v_fmamk_f32 v1, v1, 0x3a800000, v213
	v_fmamk_f32 v3, v3, 0x3a800000, v213
	v_add_f32_e32 v5, v5, v6
	v_rsq_f32_e32 v1, v1
	v_rsq_f32_e32 v3, v3
	v_fmamk_f32 v4, v4, 0x3a800000, v213
	v_fmamk_f32 v5, v5, 0x3a800000, v213
	v_rsq_f32_e32 v4, v4
	v_rsq_f32_e32 v5, v5
	v_lshl_add_u32 v6, v24, 2, 0
	v_add_u32_e32 v6, 0x22000, v6
	ds_write2st64_b32 v6, v1, v3 offset1:8
	ds_write2st64_b32 v6, v4, v5 offset0:16 offset1:24
	s_waitcnt lgkmcnt(0)
	v_mov_b32_e32 v135, v181
	s_cmp_eq_u32 s6, 1
	v_lshl_add_u64 v[22:23], s[44:45], 0, v[180:181]
	v_lshl_add_u64 v[20:21], s[44:45], 0, v[134:135]
	s_cselect_b64 s[8:9], -1, 0
	s_cmp_lg_u32 s6, 1
	s_cbranch_scc1 .LBB0_35
	s_barrier

.LBB0_134:
	s_or_b64 exec, exec, s[6:7]
	v_ashrrev_i32_e32 v0, 31, v21
	v_lshrrev_b32_e32 v0, 26, v0
	v_add_u32_e32 v0, v21, v0
	v_ashrrev_i32_e32 v20, 6, v0
	v_bfe_i32 v0, v21, 27, 1
	v_lshlrev_b32_e32 v1, 4, v21
	v_lshrrev_b32_e32 v0, 22, v0
	v_add_u32_e32 v0, v1, v0
	v_and_b32_e32 v0, 0xfffffc00, v0
	v_sub_u32_e32 v0, v1, v0
	v_lshrrev_b32_e32 v3, 4, v0
	v_bitop3_b32 v0, v3, v0, 32 bitop3:0x6c
	v_ashrrev_i32_e32 v22, 31, v0
	v_lshrrev_b32_e32 v22, 26, v22
	v_add_u32_e32 v23, v0, v22
	v_lshlrev_b32_e32 v3, 3, v20
	v_ashrrev_i32_e32 v22, 6, v23
	v_and_b32_e32 v23, 0xc0, v23
	v_and_b32_e32 v3, -16, v3
	v_sub_u32_e32 v0, v0, v23
	v_mov_b32_e32 v28, 1
	v_add_u32_e32 v3, v22, v3
	v_lshlrev_b32_e32 v24, 5, v20
	v_ashrrev_i16_sdwa v0, v28, sext(v0) dst_sel:DWORD dst_unused:UNUSED_PAD src0_sel:DWORD src1_sel:BYTE_0
	v_and_b32_e32 v24, 32, v24
	v_bfe_i32 v23, v0, 0, 16
	v_lshlrev_b32_e32 v0, 1, v3
	v_lshrrev_b32_e32 v25, 2, v3
	v_and_b32_e32 v26, 3, v22
	s_mov_b32 s6, 0x1fffe0
	v_and_b32_e32 v0, 24, v0
	v_and_b32_e32 v25, 4, v25
	v_and_or_b32 v26, v3, s6, v26
	v_add_lshl_u32 v24, v24, v23, 1
	v_add_u32_e32 v1, 0x2000, v1
	v_or3_b32 v25, v26, v25, v0
	v_lshl_add_u32 v0, v3, 11, v24
	v_ashrrev_i32_e32 v3, 31, v1
	v_lshrrev_b32_e32 v3, 22, v3
	v_add_u32_e32 v3, v1, v3
	v_lshl_add_u32 v180, v25, 11, v24
	v_ashrrev_i32_e32 v24, 10, v3
	v_mul_i32_i24_e32 v3, 0x400, v24
	v_sub_u32_e32 v1, v1, v3
	v_lshrrev_b32_e32 v3, 4, v1
	v_bitop3_b32 v1, v3, v1, 32 bitop3:0x6c
	v_ashrrev_i32_e32 v25, 31, v1
	v_lshrrev_b32_e32 v25, 26, v25
	v_add_u32_e32 v26, v1, v25
	v_lshlrev_b32_e32 v3, 3, v24
	v_ashrrev_i32_e32 v25, 6, v26
	v_and_b32_e32 v26, 0xc0, v26
	v_and_b32_e32 v3, -16, v3
	v_sub_u32_e32 v1, v1, v26
	v_add_u32_e32 v3, v25, v3
	v_ashrrev_i16_sdwa v1, v28, sext(v1) dst_sel:DWORD dst_unused:UNUSED_PAD src0_sel:DWORD src1_sel:BYTE_0
	s_ashr_i32 s7, s12, 6
	v_lshlrev_b32_e32 v27, 5, v24
	v_bfe_i32 v26, v1, 0, 16
	v_lshlrev_b32_e32 v1, 1, v3
	v_lshrrev_b32_e32 v28, 2, v3
	v_and_b32_e32 v29, 3, v25
	s_lshl_b32 s48, s7, 10
	v_and_b32_e32 v27, 32, v27
	v_and_b32_e32 v1, 24, v1
	v_and_b32_e32 v28, 4, v28
	v_and_or_b32 v29, v3, s6, v29
	s_add_i32 s49, s48, 0
	v_readlane_b32 s8, v253, 10
	v_or3_b32 v1, v29, v28, v1
	v_add_lshl_u32 v27, v27, v26, 1
	s_add_i32 m0, s49, 0x10000
	v_readlane_b32 s9, v253, 11
	v_lshl_add_u32 v134, v1, 11, v27
	s_add_i32 s50, s49, 0x2000
	v_lshl_add_u32 v132, v3, 11, v27
	s_add_i32 s51, s49, 0x4000
	s_add_i32 s52, s49, 0x6000
	global_load_lds_dwordx4 v180, s[8:9]
	s_add_i32 m0, s49, 0x12000
	s_nop 0
	global_load_lds_dwordx4 v134, s[8:9]
	v_readlane_b32 s8, v253, 4
	s_add_i32 m0, s49, 0x14000
	v_readlane_b32 s9, v253, 5
	s_nop 4
	global_load_lds_dwordx4 v180, s[8:9]
	s_add_i32 m0, s49, 0x16000
	s_nop 0
	global_load_lds_dwordx4 v134, s[8:9]
	v_readlane_b32 s8, v253, 6
	s_mov_b32 m0, s49
	v_readlane_b32 s9, v253, 7
	s_nop 4
	global_load_lds_dwordx4 v0, s[8:9]
	s_mov_b32 m0, s50
	s_nop 0
	global_load_lds_dwordx4 v132, s[8:9]
	v_readlane_b32 s8, v253, 8
	s_mov_b32 m0, s51
	v_readlane_b32 s9, v253, 9
	s_nop 4
	global_load_lds_dwordx4 v0, s[8:9]
	s_mov_b32 m0, s52
	s_nop 0
	global_load_lds_dwordx4 v132, s[8:9]
	s_waitcnt vmcnt(8)
	v_add_f32_e32 v1, v8, v9
	v_add_f32_e32 v3, v10, v11
	v_add_f32_e32 v1, v1, v3
	v_add_f32_e32 v3, v4, v5
	v_add_f32_e32 v4, v6, v7
	v_add_f32_e32 v3, v3, v4
	v_add_f32_e32 v4, v16, v17
	v_add_f32_e32 v5, v18, v19
	v_add_f32_e32 v4, v4, v5
	v_add_f32_e32 v5, v12, v13
	v_add_f32_e32 v6, v14, v15
	v_fmamk_f32 v1, v1, 0x3a800000, v213
	v_fmamk_f32 v3, v3, 0x3a800000, v213
	v_add_f32_e32 v5, v5, v6
	v_rsq_f32_e32 v1, v1
	v_rsq_f32_e32 v3, v3
	v_fmamk_f32 v4, v4, 0x3a800000, v213
	v_fmamk_f32 v5, v5, 0x3a800000, v213
	v_rsq_f32_e32 v4, v4
	v_rsq_f32_e32 v5, v5
	v_lshl_add_u32 v6, v21, 2, 0
	v_add_u32_e32 v6, 0x22000, v6
	ds_write2st64_b32 v6, v1, v3 offset1:8
	ds_write2st64_b32 v6, v4, v5 offset0:16 offset1:24
	s_ashr_i32 s6, s12, 8
	s_waitcnt lgkmcnt(0)
	s_cmp_eq_u32 s6, 1
	s_cselect_b64 s[8:9], -1, 0
	s_cmp_lg_u32 s6, 1
	s_cbranch_scc1 .LBB0_136
	s_barrier

.LBB0_318:
	s_or_b64 exec, exec, s[6:7]
	s_lshl_b32 s6, s52, 7
	s_add_u32 s6, s71, s6
	s_waitcnt lgkmcnt(0)
	s_barrier
	s_addc_u32 s7, s72, 0
	v_lshlrev_b32_e32 v1, 5, v144
	global_load_dwordx4 v[136:139], v1, s[6:7] offset:16
	global_load_dwordx4 v[144:147], v1, s[6:7]
	s_waitcnt lgkmcnt(0)
	global_load_dwordx4 v[132:135], v1, s[6:7] offset:528
	global_load_dwordx4 v[140:143], v1, s[6:7] offset:512
	s_lshl_b32 s6, s55, 10
	s_add_i32 s6, s6, 0
	v_lshl_add_u32 v3, v3, 4, s6
	v_add_u32_e32 v1, 0x20000, v3
	ds_read_b128 v[154:157], v1
	s_lshl_b32 s8, s52, 6
	s_add_i32 s15, s8, 0
	s_movk_i32 s16, 0x210
	s_ashr_i32 s6, s54, 3
	s_waitcnt lgkmcnt(0)
	v_mov_b32_e32 v158, v155
	v_mov_b32_e32 v159, v156
	v_mov_b32_e32 v155, v157
	v_pk_add_f32 v[154:155], v[158:159], v[154:155]
	v_readlane_b32 s10, v254, 18
	v_add_f32_e32 v1, v154, v155
	v_fmamk_f32 v1, v1, 0x3b800000, v213
	v_rsq_f32_e32 v1, v1
	v_readlane_b32 s11, v254, 19
	v_readlane_b32 s48, v254, 41
	v_readlane_b32 s49, v254, 42
	v_mul_f32_e32 v160, v0, v1
	v_add_u32_e32 v0, 0x20100, v3
	ds_read_b128 v[154:157], v0
	v_pk_mul_f32 v[128:129], v[128:129], v[160:161] op_sel_hi:[1,0]
	v_pk_mul_f32 v[120:121], v[120:121], v[160:161] op_sel_hi:[1,0]
	v_pk_mul_f32 v[124:125], v[124:125], v[160:161] op_sel_hi:[1,0]
	v_pk_mul_f32 v[126:127], v[126:127], v[160:161] op_sel_hi:[1,0]
	s_waitcnt lgkmcnt(0)
	v_mov_b32_e32 v0, v155
	v_mov_b32_e32 v1, v156
	v_mov_b32_e32 v155, v157
	v_pk_add_f32 v[0:1], v[0:1], v[154:155]
	v_pk_mul_f32 v[116:117], v[116:117], v[160:161] op_sel_hi:[1,0]
	v_add_f32_e32 v0, v0, v1
	v_fmamk_f32 v0, v0, 0x3b800000, v213
	v_rsq_f32_e32 v0, v0
	v_pk_mul_f32 v[118:119], v[118:119], v[160:161] op_sel_hi:[1,0]
	v_pk_mul_f32 v[130:131], v[130:131], v[160:161] op_sel_hi:[1,0]
	v_pk_mul_f32 v[122:123], v[122:123], v[160:161] op_sel_hi:[1,0]
	v_mul_f32_e32 v158, v148, v0
	v_add_u32_e32 v0, 0x20200, v3
	ds_read_b128 v[154:157], v0
	v_pk_mul_f32 v[112:113], v[112:113], v[158:159] op_sel_hi:[1,0]
	v_pk_mul_f32 v[100:101], v[100:101], v[158:159] op_sel_hi:[1,0]
	v_pk_mul_f32 v[108:109], v[108:109], v[158:159] op_sel_hi:[1,0]
	v_pk_mul_f32 v[110:111], v[110:111], v[158:159] op_sel_hi:[1,0]
	s_waitcnt lgkmcnt(0)
	v_mov_b32_e32 v0, v155
	v_mov_b32_e32 v1, v156
	v_mov_b32_e32 v155, v157
	v_pk_add_f32 v[0:1], v[0:1], v[154:155]
	v_pk_mul_f32 v[92:93], v[92:93], v[158:159] op_sel_hi:[1,0]
	v_add_f32_e32 v0, v0, v1
	v_fmamk_f32 v0, v0, 0x3b800000, v213
	v_rsq_f32_e32 v0, v0
	v_pk_mul_f32 v[94:95], v[94:95], v[158:159] op_sel_hi:[1,0]
	v_pk_mul_f32 v[102:103], v[102:103], v[158:159] op_sel_hi:[1,0]
	v_pk_mul_f32 v[114:115], v[114:115], v[158:159] op_sel_hi:[1,0]
	v_mul_f32_e32 v156, v150, v0
	v_add_u32_e32 v0, 0x20300, v3
	ds_read_b128 v[174:177], v0
	v_pk_mul_f32 v[84:85], v[84:85], v[156:157] op_sel_hi:[1,0]
	v_pk_mul_f32 v[96:97], v[96:97], v[156:157] op_sel_hi:[1,0]
	v_pk_mul_f32 v[98:99], v[98:99], v[156:157] op_sel_hi:[1,0]
	v_pk_mul_f32 v[76:77], v[76:77], v[156:157] op_sel_hi:[1,0]
	s_waitcnt lgkmcnt(0)
	v_mov_b32_e32 v0, v175
	v_mov_b32_e32 v1, v176
	v_mov_b32_e32 v175, v177
	v_pk_add_f32 v[0:1], v[0:1], v[174:175]
	v_pk_mul_f32 v[78:79], v[78:79], v[156:157] op_sel_hi:[1,0]
	v_add_f32_e32 v0, v0, v1
	v_fmamk_f32 v0, v0, 0x3b800000, v213
	v_rsq_f32_e32 v0, v0
	v_pk_mul_f32 v[86:87], v[86:87], v[156:157] op_sel_hi:[1,0]
	v_mul_f32_e32 v154, v152, v0
	v_add_u32_e32 v0, 0x20800, v3
	ds_read_b128 v[174:177], v0
	s_waitcnt vmcnt(0)
	v_pk_mul_f32 v[128:129], v[144:145], v[128:129]
	v_pk_mul_f32 v[112:113], v[144:145], v[112:113]
	v_pk_mul_f32 v[120:121], v[140:141], v[120:121]
	v_pk_mul_f32 v[100:101], v[140:141], v[100:101]
	s_waitcnt lgkmcnt(0)
	v_mov_b32_e32 v0, v175
	v_mov_b32_e32 v1, v176
	v_mov_b32_e32 v175, v177
	v_pk_add_f32 v[0:1], v[0:1], v[174:175]
	v_pk_mul_f32 v[84:85], v[140:141], v[84:85]
	v_add_f32_e32 v0, v0, v1
	v_fmamk_f32 v0, v0, 0x3b800000, v213
	v_rsq_f32_e32 v0, v0
	v_pk_mul_f32 v[72:73], v[72:73], v[154:155] op_sel_hi:[1,0]
	v_pk_mul_f32 v[80:81], v[80:81], v[154:155] op_sel_hi:[1,0]
	v_pk_mul_f32 v[82:83], v[82:83], v[154:155] op_sel_hi:[1,0]
	v_mul_f32_e32 v152, v162, v0
	v_add_u32_e32 v0, 0x20900, v3
	ds_read_b128 v[174:177], v0
	v_pk_mul_f32 v[72:73], v[140:141], v[72:73]
	v_pk_mul_f32 v[68:69], v[68:69], v[154:155] op_sel_hi:[1,0]
	v_pk_mul_f32 v[70:71], v[70:71], v[154:155] op_sel_hi:[1,0]
	v_pk_mul_f32 v[102:103], v[142:143], v[102:103]
	s_waitcnt lgkmcnt(0)
	v_mov_b32_e32 v0, v175
	v_mov_b32_e32 v1, v176
	v_mov_b32_e32 v175, v177
	v_pk_add_f32 v[0:1], v[0:1], v[174:175]
	v_pk_mul_f32 v[86:87], v[142:143], v[86:87]
	v_add_f32_e32 v0, v0, v1
	v_fmamk_f32 v0, v0, 0x3b800000, v213
	v_rsq_f32_e32 v0, v0
	v_pk_mul_f32 v[130:131], v[146:147], v[130:131]
	v_pk_mul_f32 v[74:75], v[74:75], v[154:155] op_sel_hi:[1,0]
	v_pk_mul_f32 v[122:123], v[142:143], v[122:123]
	v_mul_f32_e32 v150, v164, v0
	v_add_u32_e32 v0, 0x20a00, v3
	ds_read_b128 v[162:165], v0
	v_pk_mul_f32 v[56:57], v[56:57], v[150:151] op_sel_hi:[1,0]
	v_pk_mul_f32 v[20:21], v[20:21], v[150:151] op_sel_hi:[1,0]
	v_pk_mul_f32 v[22:23], v[22:23], v[150:151] op_sel_hi:[1,0]
	v_pk_mul_f32 v[56:57], v[136:137], v[56:57]
	s_waitcnt lgkmcnt(0)
	v_mov_b32_e32 v0, v163
	v_mov_b32_e32 v1, v164
	v_mov_b32_e32 v163, v165
	v_pk_add_f32 v[0:1], v[0:1], v[162:163]
	v_pk_mul_f32 v[22:23], v[142:143], v[22:23]
	v_add_f32_e32 v0, v0, v1
	v_fmamk_f32 v0, v0, 0x3b800000, v213
	v_rsq_f32_e32 v0, v0
	v_pk_mul_f32 v[20:21], v[140:141], v[20:21]
	v_pk_mul_f32 v[16:17], v[16:17], v[150:151] op_sel_hi:[1,0]
	v_pk_mul_f32 v[18:19], v[18:19], v[150:151] op_sel_hi:[1,0]
	v_mul_f32_e32 v148, v166, v0
	v_add_u32_e32 v0, 0x20b00, v3
	ds_read_b128 v[162:165], v0
	v_mov_b32_e32 v3, v217
	v_pk_mul_f32 v[48:49], v[48:49], v[148:149] op_sel_hi:[1,0]
	v_and_b32_e32 v153, 48, v3
	s_waitcnt lgkmcnt(0)
	v_mov_b32_e32 v0, v163
	v_mov_b32_e32 v1, v164
	v_mov_b32_e32 v163, v165
	v_pk_add_f32 v[0:1], v[0:1], v[162:163]
	v_pk_mul_f32 v[162:163], v[138:139], v[126:127]
	v_pk_mul_f32 v[126:127], v[136:137], v[124:125]
	v_cvt_pk_bf16_f32 v124, v128, v129
	v_pk_mul_f32 v[128:129], v[134:135], v[118:119]
	v_pk_mul_f32 v[118:119], v[132:133], v[116:117]
	v_cvt_pk_bf16_f32 v116, v120, v121
	v_pk_mul_f32 v[120:121], v[138:139], v[110:111]
	v_pk_mul_f32 v[110:111], v[136:137], v[108:109]
	v_cvt_pk_bf16_f32 v108, v112, v113
	v_pk_mul_f32 v[112:113], v[134:135], v[94:95]
	v_pk_mul_f32 v[94:95], v[132:133], v[92:93]
	v_cvt_pk_bf16_f32 v92, v100, v101
	v_pk_mul_f32 v[100:101], v[104:105], v[156:157] op_sel_hi:[1,0]
	v_add_f32_e32 v0, v0, v1
	v_pk_mul_f32 v[100:101], v[144:145], v[100:101]
	v_fmamk_f32 v0, v0, 0x3b800000, v213
	v_pk_mul_f32 v[104:105], v[138:139], v[98:99]
	v_pk_mul_f32 v[98:99], v[136:137], v[96:97]
	v_cvt_pk_bf16_f32 v96, v100, v101
	v_pk_mul_f32 v[100:101], v[134:135], v[78:79]
	v_pk_mul_f32 v[78:79], v[132:133], v[76:77]
	v_cvt_pk_bf16_f32 v76, v84, v85
	v_pk_mul_f32 v[84:85], v[88:89], v[154:155] op_sel_hi:[1,0]
	v_pk_mul_f32 v[64:65], v[64:65], v[152:153] op_sel_hi:[1,0]
	v_pk_mul_f32 v[12:13], v[12:13], v[152:153] op_sel_hi:[1,0]
	v_pk_mul_f32 v[14:15], v[14:15], v[152:153] op_sel_hi:[1,0]
	v_rsq_f32_e32 v0, v0
	v_pk_mul_f32 v[84:85], v[144:145], v[84:85]
	v_pk_mul_f32 v[64:65], v[144:145], v[64:65]
	v_pk_mul_f32 v[4:5], v[4:5], v[152:153] op_sel_hi:[1,0]
	v_pk_mul_f32 v[6:7], v[6:7], v[152:153] op_sel_hi:[1,0]
	v_pk_mul_f32 v[14:15], v[142:143], v[14:15]
	v_pk_mul_f32 v[12:13], v[140:141], v[12:13]
	v_pk_mul_f32 v[8:9], v[8:9], v[152:153] op_sel_hi:[1,0]
	v_pk_mul_f32 v[10:11], v[10:11], v[152:153] op_sel_hi:[1,0]
	v_pk_mul_f32 v[88:89], v[138:139], v[82:83]
	v_pk_mul_f32 v[82:83], v[136:137], v[80:81]
	v_cvt_pk_bf16_f32 v80, v84, v85
	v_pk_mul_f32 v[84:85], v[134:135], v[70:71]
	v_pk_mul_f32 v[70:71], v[132:133], v[68:69]
	v_cvt_pk_bf16_f32 v68, v72, v73
	v_pk_mul_f32 v[72:73], v[138:139], v[6:7]
	v_pk_mul_f32 v[6:7], v[136:137], v[4:5]
	v_cvt_pk_bf16_f32 v4, v64, v65
	v_pk_mul_f32 v[64:65], v[134:135], v[10:11]
	v_pk_mul_f32 v[10:11], v[132:133], v[8:9]
	v_cvt_pk_bf16_f32 v8, v12, v13
	v_cvt_pk_bf16_f32 v9, v14, v15
	v_pk_mul_f32 v[12:13], v[60:61], v[150:151] op_sel_hi:[1,0]
	v_pk_mul_f32 v[14:15], v[62:63], v[150:151] op_sel_hi:[1,0]
	v_pk_mul_f32 v[12:13], v[144:145], v[12:13]
	v_pk_mul_f32 v[14:15], v[146:147], v[14:15]
	v_cvt_pk_bf16_f32 v12, v12, v13
	v_cvt_pk_bf16_f32 v13, v14, v15
	v_cvt_pk_bf16_f32 v14, v56, v57
	v_pk_mul_f32 v[56:57], v[134:135], v[18:19]
	v_pk_mul_f32 v[18:19], v[132:133], v[16:17]
	v_cvt_pk_bf16_f32 v16, v20, v21
	v_cvt_pk_bf16_f32 v17, v22, v23
	v_pk_mul_f32 v[20:21], v[52:53], v[148:149] op_sel_hi:[1,0]
	v_pk_mul_f32 v[22:23], v[54:55], v[148:149] op_sel_hi:[1,0]
	v_pk_mul_f32 v[28:29], v[28:29], v[148:149] op_sel_hi:[1,0]
	v_pk_mul_f32 v[30:31], v[30:31], v[148:149] op_sel_hi:[1,0]
	v_mul_f32_e32 v0, v168, v0
	v_pk_mul_f32 v[22:23], v[146:147], v[22:23]
	v_pk_mul_f32 v[20:21], v[144:145], v[20:21]
	v_pk_mul_f32 v[48:49], v[136:137], v[48:49]
	v_pk_mul_f32 v[30:31], v[142:143], v[30:31]
	v_pk_mul_f32 v[28:29], v[140:141], v[28:29]
	v_pk_mul_f32 v[24:25], v[24:25], v[148:149] op_sel_hi:[1,0]
	v_pk_mul_f32 v[26:27], v[26:27], v[148:149] op_sel_hi:[1,0]
	v_cvt_pk_bf16_f32 v20, v20, v21
	v_cvt_pk_bf16_f32 v21, v22, v23
	v_cvt_pk_bf16_f32 v22, v48, v49
	v_pk_mul_f32 v[48:49], v[134:135], v[26:27]
	v_pk_mul_f32 v[26:27], v[132:133], v[24:25]
	v_cvt_pk_bf16_f32 v24, v28, v29
	v_cvt_pk_bf16_f32 v25, v30, v31
	v_pk_mul_f32 v[28:29], v[44:45], v[0:1] op_sel_hi:[1,0]
	v_pk_mul_f32 v[30:31], v[46:47], v[0:1] op_sel_hi:[1,0]
	v_pk_mul_f32 v[40:41], v[40:41], v[0:1] op_sel_hi:[1,0]
	v_pk_mul_f32 v[42:43], v[42:43], v[0:1] op_sel_hi:[1,0]
	v_pk_mul_f32 v[36:37], v[36:37], v[0:1] op_sel_hi:[1,0]
	v_pk_mul_f32 v[38:39], v[38:39], v[0:1] op_sel_hi:[1,0]
	v_pk_mul_f32 v[32:33], v[32:33], v[0:1] op_sel_hi:[1,0]
	v_pk_mul_f32 v[0:1], v[34:35], v[0:1] op_sel_hi:[1,0]
	v_readfirstlane_b32 s7, v3
	v_pk_mul_f32 v[0:1], v[134:135], v[0:1]
	v_pk_mul_f32 v[34:35], v[132:133], v[32:33]
	s_ashr_i32 s8, s7, 2
	v_pk_mul_f32 v[36:37], v[140:141], v[36:37]
	v_cvt_pk_bf16_f32 v34, v34, v35
	v_cvt_pk_bf16_f32 v35, v0, v1
	v_bfi_b32 v1, -16, s8, v3
	v_cvt_pk_bf16_f32 v32, v36, v37
	v_mul_lo_u32 v36, v1, s16
	v_add3_u32 v175, 0, v36, v153
	v_ashrrev_i32_e32 v36, 3, v3
	v_pk_mul_f32 v[30:31], v[146:147], v[30:31]
	v_pk_mul_f32 v[28:29], v[144:145], v[28:29]
	v_pk_mul_f32 v[40:41], v[136:137], v[40:41]
	v_pk_mul_f32 v[38:39], v[142:143], v[38:39]
	v_ashrrev_i32_e32 v37, 31, v36
	v_cvt_pk_bf16_f32 v28, v28, v29
	v_cvt_pk_bf16_f32 v29, v30, v31
	v_cvt_pk_bf16_f32 v30, v40, v41
	v_cvt_pk_bf16_f32 v33, v38, v39
	v_and_b32_e32 v38, 15, v3
	v_bfe_u32 v39, v3, 4, 2
	v_lshlrev_b64 v[44:45], 13, v[36:37]
	v_lshlrev_b32_e32 v37, 3, v3
	v_lshlrev_b32_e32 v40, 4, v3
	v_bfe_u32 v3, v3, 2, 2
	v_mul_lo_u32 v36, v36, s16
	v_and_b32_e32 v180, 0x70, v40
	v_lshl_or_b32 v3, v39, 2, v3
	s_ashr_i32 s7, s6, 31
	s_lshl_b32 s8, s53, 8
	v_add3_u32 v170, s10, v36, v180
	v_mul_u32_u24_e32 v38, 0x210, v38
	v_add3_u32 v168, s11, v36, v180
	v_mul_u32_u24_e32 v3, 0x210, v3
	v_and_b32_e32 v36, 24, v37
	s_lshl_b64 s[12:13], s[6:7], 21
	s_ashr_i32 s9, s8, 31
	v_add3_u32 v174, s10, v153, v38
	v_add3_u32 v173, s11, v153, v38
	v_add3_u32 v169, s10, v3, v36
	v_add3_u32 v3, s11, v3, v36
	s_lshl_b64 s[10:11], s[6:7], 22
	s_add_u32 s12, s60, s12
	s_addc_u32 s13, s61, s13
	v_lshl_add_u64 v[44:45], s[12:13], 0, v[44:45]
	s_lshl_b32 s12, s0, 11
	s_ashr_i32 s13, s12, 31
	v_cvt_pk_bf16_f32 v93, v102, v103
	v_pk_mul_f32 v[102:103], v[106:107], v[156:157] op_sel_hi:[1,0]
	v_cvt_pk_bf16_f32 v77, v86, v87
	v_pk_mul_f32 v[86:87], v[90:91], v[154:155] op_sel_hi:[1,0]
	v_mul_lo_u32 v36, v149, s16
	v_lshl_add_u64 v[44:45], s[12:13], 1, v[44:45]
	s_lshl_b64 s[8:9], s[8:9], 1
	v_cvt_pk_bf16_f32 v125, v130, v131
	v_cvt_pk_bf16_f32 v126, v126, v127
	v_cvt_pk_bf16_f32 v127, v162, v163
	v_pk_mul_f32 v[114:115], v[146:147], v[114:115]
	v_pk_mul_f32 v[102:103], v[146:147], v[102:103]
	v_pk_mul_f32 v[86:87], v[146:147], v[86:87]
	v_pk_mul_f32 v[74:75], v[142:143], v[74:75]
	v_add3_u32 v176, s15, v151, v36
	v_lshl_add_u64 v[44:45], v[44:45], 0, s[8:9]
	v_cvt_pk_bf16_f32 v117, v122, v123
	v_cvt_pk_bf16_f32 v118, v118, v119
	v_cvt_pk_bf16_f32 v119, v128, v129
	v_cvt_pk_bf16_f32 v109, v114, v115
	v_cvt_pk_bf16_f32 v110, v110, v111
	v_cvt_pk_bf16_f32 v111, v120, v121
	v_cvt_pk_bf16_f32 v94, v94, v95
	v_cvt_pk_bf16_f32 v95, v112, v113
	v_cvt_pk_bf16_f32 v97, v102, v103
	v_cvt_pk_bf16_f32 v98, v98, v99
	v_cvt_pk_bf16_f32 v99, v104, v105
	v_cvt_pk_bf16_f32 v78, v78, v79
	v_cvt_pk_bf16_f32 v79, v100, v101
	v_cvt_pk_bf16_f32 v81, v86, v87
	v_cvt_pk_bf16_f32 v82, v82, v83
	v_cvt_pk_bf16_f32 v83, v88, v89
	v_cvt_pk_bf16_f32 v69, v74, v75
	v_cvt_pk_bf16_f32 v70, v70, v71
	v_cvt_pk_bf16_f32 v71, v84, v85
	s_waitcnt lgkmcnt(0)
	s_barrier
	ds_write_b128 v176, v[124:127]
	ds_write_b128 v176, v[116:119] offset:256
	ds_write_b128 v176, v[108:111] offset:8448
	ds_write_b128 v176, v[92:95] offset:8704
	ds_write_b128 v176, v[96:99] offset:16896
	ds_write_b128 v176, v[76:79] offset:17152
	ds_write_b128 v176, v[80:83] offset:25344
	ds_write_b128 v176, v[68:71] offset:25600
	v_lshl_add_u64 v[166:167], v[44:45], 0, v[180:181]
	s_mov_b32 s7, 0x80000
	v_pk_mul_f32 v[66:67], v[66:67], v[152:153] op_sel_hi:[1,0]
	v_pk_mul_f32 v[58:59], v[58:59], v[150:151] op_sel_hi:[1,0]
	v_pk_mul_f32 v[50:51], v[50:51], v[148:149] op_sel_hi:[1,0]
	v_pk_mul_f32 v[42:43], v[138:139], v[42:43]
	s_waitcnt lgkmcnt(0)
	s_barrier
	v_add_co_u32_e32 v164, vcc, s7, v166
	v_pk_mul_f32 v[66:67], v[146:147], v[66:67]
	v_pk_mul_f32 v[58:59], v[138:139], v[58:59]
	v_pk_mul_f32 v[50:51], v[138:139], v[50:51]
	v_cvt_pk_bf16_f32 v31, v42, v43
	v_lshlrev_b32_e32 v0, 3, v39
	ds_read_b128 v[124:127], v175
	ds_read_b128 v[120:123], v175 offset:64
	ds_read_b128 v[116:119], v175 offset:128
	ds_read_b128 v[108:111], v175 offset:192
	ds_read_b128 v[80:83], v175 offset:256
	ds_read_b128 v[76:79], v175 offset:320
	ds_read_b128 v[40:43], v175 offset:384
	ds_read_b128 v[36:39], v175 offset:448
	global_load_dwordx4 v[60:63], v[166:167], off
	v_addc_co_u32_e32 v165, vcc, 0, v167, vcc
	v_cvt_pk_bf16_f32 v5, v66, v67
	v_cvt_pk_bf16_f32 v6, v6, v7
	v_cvt_pk_bf16_f32 v7, v72, v73
	v_cvt_pk_bf16_f32 v10, v10, v11
	v_cvt_pk_bf16_f32 v11, v64, v65
	v_cvt_pk_bf16_f32 v15, v58, v59
	v_cvt_pk_bf16_f32 v18, v18, v19
	v_cvt_pk_bf16_f32 v19, v56, v57
	v_cvt_pk_bf16_f32 v23, v50, v51
	v_cvt_pk_bf16_f32 v26, v26, v27
	v_cvt_pk_bf16_f32 v27, v48, v49
	global_load_dwordx4 v[44:47], v[164:165], off
	global_load_dwordx4 v[64:67], v[166:167], off offset:128
	global_load_dwordx4 v[48:51], v[164:165], off offset:128
	global_load_dwordx4 v[68:71], v[166:167], off offset:256
	global_load_dwordx4 v[52:55], v[164:165], off offset:256
	global_load_dwordx4 v[72:75], v[166:167], off offset:384
	global_load_dwordx4 v[56:59], v[164:165], off offset:384
	s_mov_b32 s7, 0x100000
	v_add_co_u32_e32 v162, vcc, s7, v166
	s_waitcnt vmcnt(7)
	ds_write_b128 v170, v[60:63]
	s_waitcnt vmcnt(5)
	ds_write_b128 v170, v[64:67] offset:128
	s_waitcnt vmcnt(3)
	ds_write_b128 v170, v[68:71] offset:256
	s_waitcnt vmcnt(1)
	ds_write_b128 v170, v[72:75] offset:384
	v_addc_co_u32_e32 v163, vcc, 0, v167, vcc
	global_load_dwordx4 v[60:63], v[162:163], off
	global_load_dwordx4 v[64:67], v[162:163], off offset:128
	global_load_dwordx4 v[68:71], v[162:163], off offset:256
	global_load_dwordx4 v[72:75], v[162:163], off offset:384
	s_waitcnt lgkmcnt(0)
	s_barrier
	ds_read_b128 v[204:207], v174
	ds_read_b128 v[208:211], v174 offset:8448
	ds_read_b128 v[218:221], v174 offset:16896
	ds_read_b128 v[224:227], v174 offset:25344
	ds_read_b128 v[228:231], v174 offset:64
	ds_read_b128 v[232:235], v174 offset:8512
	ds_read_b128 v[236:239], v174 offset:16960
	ds_read_b128 v[240:243], v174 offset:25408
	s_waitcnt lgkmcnt(7)
	v_mfma_f32_16x16x32_bf16 v[84:87], v[204:207], v[124:127], 0
	ds_read_b128 v[204:207], v174 offset:128
	s_waitcnt lgkmcnt(7)
	v_mfma_f32_16x16x32_bf16 v[88:91], v[208:211], v[124:127], 0
	ds_read_b128 v[208:211], v174 offset:8576
	s_mov_b32 s7, 0x180000
	v_add_co_u32_e32 v160, vcc, s7, v166
	s_nop 1
	s_waitcnt lgkmcnt(7)
	v_mfma_f32_16x16x32_bf16 v[92:95], v[218:221], v[124:127], 0
	ds_read_b128 v[218:221], v174 offset:17024
	v_addc_co_u32_e32 v161, vcc, 0, v167, vcc
	s_nop 1
	s_waitcnt lgkmcnt(7)
	v_mfma_f32_16x16x32_bf16 v[96:99], v[224:227], v[124:127], 0
	ds_read_b128 v[224:227], v174 offset:25472
	s_mov_b32 s7, 0xf149f2ca
	s_waitcnt lgkmcnt(7)
	v_mfma_f32_16x16x32_bf16 v[84:87], v[228:231], v[120:123], v[84:87]
	ds_read_b128 v[228:231], v174 offset:192
	s_waitcnt lgkmcnt(7)
	v_mfma_f32_16x16x32_bf16 v[88:91], v[232:235], v[120:123], v[88:91]
	ds_read_b128 v[232:235], v174 offset:8640
	s_waitcnt lgkmcnt(7)
	v_mfma_f32_16x16x32_bf16 v[92:95], v[236:239], v[120:123], v[92:95]
	ds_read_b128 v[236:239], v174 offset:17088
	s_waitcnt lgkmcnt(7)
	v_mfma_f32_16x16x32_bf16 v[96:99], v[240:243], v[120:123], v[96:99]
	ds_read_b128 v[240:243], v174 offset:25536
	s_waitcnt lgkmcnt(7)
	v_mfma_f32_16x16x32_bf16 v[84:87], v[204:207], v[116:119], v[84:87]
	ds_read_b128 v[204:207], v174 offset:256
	s_waitcnt lgkmcnt(7)
	v_mfma_f32_16x16x32_bf16 v[88:91], v[208:211], v[116:119], v[88:91]
	ds_read_b128 v[208:211], v174 offset:8704
	s_waitcnt lgkmcnt(7)
	v_mfma_f32_16x16x32_bf16 v[92:95], v[218:221], v[116:119], v[92:95]
	ds_read_b128 v[218:221], v174 offset:17152
	s_waitcnt lgkmcnt(7)
	v_mfma_f32_16x16x32_bf16 v[96:99], v[224:227], v[116:119], v[96:99]
	ds_read_b128 v[224:227], v174 offset:25600
	s_waitcnt lgkmcnt(7)
	v_mfma_f32_16x16x32_bf16 v[84:87], v[228:231], v[108:111], v[84:87]
	ds_read_b128 v[228:231], v174 offset:320
	s_waitcnt lgkmcnt(7)
	v_mfma_f32_16x16x32_bf16 v[88:91], v[232:235], v[108:111], v[88:91]
	ds_read_b128 v[232:235], v174 offset:8768
	s_waitcnt lgkmcnt(7)
	v_mfma_f32_16x16x32_bf16 v[92:95], v[236:239], v[108:111], v[92:95]
	ds_read_b128 v[236:239], v174 offset:17216
	s_waitcnt lgkmcnt(7)
	v_mfma_f32_16x16x32_bf16 v[96:99], v[240:243], v[108:111], v[96:99]
	ds_read_b128 v[240:243], v174 offset:25664
	s_waitcnt lgkmcnt(7)
	v_mfma_f32_16x16x32_bf16 v[84:87], v[204:207], v[80:83], v[84:87]
	ds_read_b128 v[204:207], v174 offset:384
	s_waitcnt lgkmcnt(7)
	v_mfma_f32_16x16x32_bf16 v[88:91], v[208:211], v[80:83], v[88:91]
	ds_read_b128 v[208:211], v174 offset:8832
	s_waitcnt lgkmcnt(7)
	v_mfma_f32_16x16x32_bf16 v[92:95], v[218:221], v[80:83], v[92:95]
	ds_read_b128 v[218:221], v174 offset:17280
	s_waitcnt lgkmcnt(7)
	v_mfma_f32_16x16x32_bf16 v[96:99], v[224:227], v[80:83], v[96:99]
	ds_read_b128 v[224:227], v174 offset:25728
	s_waitcnt lgkmcnt(7)
	v_mfma_f32_16x16x32_bf16 v[84:87], v[228:231], v[76:79], v[84:87]
	ds_read_b128 v[228:231], v174 offset:448
	s_waitcnt lgkmcnt(7)
	v_mfma_f32_16x16x32_bf16 v[88:91], v[232:235], v[76:79], v[88:91]
	ds_read_b128 v[232:235], v174 offset:8896
	s_waitcnt lgkmcnt(7)
	v_mfma_f32_16x16x32_bf16 v[92:95], v[236:239], v[76:79], v[92:95]
	ds_read_b128 v[236:239], v174 offset:17344
	s_waitcnt lgkmcnt(7)
	v_mfma_f32_16x16x32_bf16 v[96:99], v[240:243], v[76:79], v[96:99]
	s_waitcnt lgkmcnt(6)
	v_mfma_f32_16x16x32_bf16 v[84:87], v[204:207], v[40:43], v[84:87]
	s_waitcnt lgkmcnt(5)
	v_mfma_f32_16x16x32_bf16 v[88:91], v[208:211], v[40:43], v[88:91]
	s_waitcnt lgkmcnt(4)
	v_mfma_f32_16x16x32_bf16 v[92:95], v[218:221], v[40:43], v[92:95]
	s_waitcnt lgkmcnt(3)
	v_mfma_f32_16x16x32_bf16 v[96:99], v[224:227], v[40:43], v[96:99]
	s_waitcnt lgkmcnt(2)
	v_mfma_f32_16x16x32_bf16 v[84:87], v[228:231], v[36:39], v[84:87]
	s_waitcnt lgkmcnt(1)
	v_mfma_f32_16x16x32_bf16 v[88:91], v[232:235], v[36:39], v[88:91]
	s_waitcnt lgkmcnt(0)
	v_mfma_f32_16x16x32_bf16 v[92:95], v[236:239], v[36:39], v[92:95]
	s_nop 7
	ds_read_b128 v[100:103], v174 offset:25792
	ds_write_b128 v168, v[44:47]
	ds_write_b128 v168, v[48:51] offset:128
	ds_write_b128 v168, v[52:55] offset:256
	s_waitcnt vmcnt(4)
	ds_write_b128 v168, v[56:59] offset:384
	global_load_dwordx4 v[44:47], v[160:161], off
	global_load_dwordx4 v[48:51], v[160:161], off offset:128
	global_load_dwordx4 v[52:55], v[160:161], off offset:256
	global_load_dwordx4 v[56:59], v[160:161], off offset:384
	s_waitcnt lgkmcnt(0)
	s_barrier
	s_waitcnt lgkmcnt(4)
	v_mfma_f32_16x16x32_bf16 v[96:99], v[100:103], v[36:39], v[96:99]
	ds_read_b128 v[204:207], v173
	ds_read_b128 v[208:211], v173 offset:8448
	ds_read_b128 v[218:221], v173 offset:16896
	ds_read_b128 v[224:227], v173 offset:25344
	ds_read_b128 v[228:231], v173 offset:64
	ds_read_b128 v[232:235], v173 offset:8512
	ds_read_b128 v[236:239], v173 offset:16960
	ds_read_b128 v[240:243], v173 offset:25408
	s_waitcnt lgkmcnt(7)
	v_mfma_f32_16x16x32_bf16 v[100:103], v[204:207], v[124:127], 0
	ds_read_b128 v[204:207], v173 offset:128
	s_waitcnt lgkmcnt(7)
	v_mfma_f32_16x16x32_bf16 v[104:107], v[208:211], v[124:127], 0
	ds_read_b128 v[208:211], v173 offset:8576
	s_waitcnt lgkmcnt(7)
	v_mfma_f32_16x16x32_bf16 v[112:115], v[218:221], v[124:127], 0
	ds_read_b128 v[218:221], v173 offset:17024
	s_waitcnt lgkmcnt(7)
	v_mfma_f32_16x16x32_bf16 v[128:131], v[224:227], v[124:127], 0
	ds_read_b128 v[224:227], v173 offset:25472
	s_waitcnt lgkmcnt(7)
	v_mfma_f32_16x16x32_bf16 v[100:103], v[228:231], v[120:123], v[100:103]
	ds_read_b128 v[228:231], v173 offset:192
	s_waitcnt lgkmcnt(7)
	v_mfma_f32_16x16x32_bf16 v[104:107], v[232:235], v[120:123], v[104:107]
	ds_read_b128 v[232:235], v173 offset:8640
	s_waitcnt lgkmcnt(7)
	v_mfma_f32_16x16x32_bf16 v[112:115], v[236:239], v[120:123], v[112:115]
	ds_read_b128 v[236:239], v173 offset:17088
	s_waitcnt lgkmcnt(7)
	v_mfma_f32_16x16x32_bf16 v[128:131], v[240:243], v[120:123], v[128:131]
	ds_read_b128 v[240:243], v173 offset:25536
	s_waitcnt lgkmcnt(7)
	v_mfma_f32_16x16x32_bf16 v[100:103], v[204:207], v[116:119], v[100:103]
	ds_read_b128 v[204:207], v173 offset:256
	s_waitcnt lgkmcnt(7)
	v_mfma_f32_16x16x32_bf16 v[104:107], v[208:211], v[116:119], v[104:107]
	ds_read_b128 v[208:211], v173 offset:8704
	s_waitcnt lgkmcnt(7)
	v_mfma_f32_16x16x32_bf16 v[112:115], v[218:221], v[116:119], v[112:115]
	ds_read_b128 v[218:221], v173 offset:17152
	s_waitcnt lgkmcnt(7)
	v_mfma_f32_16x16x32_bf16 v[128:131], v[224:227], v[116:119], v[128:131]
	ds_read_b128 v[224:227], v173 offset:25600
	s_waitcnt lgkmcnt(7)
	v_mfma_f32_16x16x32_bf16 v[100:103], v[228:231], v[108:111], v[100:103]
	ds_read_b128 v[228:231], v173 offset:320
	s_waitcnt lgkmcnt(7)
	v_mfma_f32_16x16x32_bf16 v[104:107], v[232:235], v[108:111], v[104:107]
	ds_read_b128 v[232:235], v173 offset:8768
	s_waitcnt lgkmcnt(7)
	v_mfma_f32_16x16x32_bf16 v[112:115], v[236:239], v[108:111], v[112:115]
	ds_read_b128 v[236:239], v173 offset:17216
	s_waitcnt lgkmcnt(7)
	v_mfma_f32_16x16x32_bf16 v[128:131], v[240:243], v[108:111], v[128:131]
	ds_read_b128 v[240:243], v173 offset:25664
	s_waitcnt lgkmcnt(7)
	v_mfma_f32_16x16x32_bf16 v[100:103], v[204:207], v[80:83], v[100:103]
	ds_read_b128 v[204:207], v173 offset:384
	s_waitcnt lgkmcnt(7)
	v_mfma_f32_16x16x32_bf16 v[104:107], v[208:211], v[80:83], v[104:107]
	ds_read_b128 v[208:211], v173 offset:8832
	s_waitcnt lgkmcnt(7)
	v_mfma_f32_16x16x32_bf16 v[112:115], v[218:221], v[80:83], v[112:115]
	ds_read_b128 v[218:221], v173 offset:17280
	s_waitcnt lgkmcnt(7)
	v_mfma_f32_16x16x32_bf16 v[128:131], v[224:227], v[80:83], v[128:131]
	ds_read_b128 v[224:227], v173 offset:25728
	s_waitcnt lgkmcnt(7)
	v_mfma_f32_16x16x32_bf16 v[100:103], v[228:231], v[76:79], v[100:103]
	ds_read_b128 v[228:231], v173 offset:448
	s_waitcnt lgkmcnt(7)
	v_mfma_f32_16x16x32_bf16 v[104:107], v[232:235], v[76:79], v[104:107]
	ds_read_b128 v[232:235], v173 offset:8896
	s_waitcnt lgkmcnt(7)
	v_mfma_f32_16x16x32_bf16 v[112:115], v[236:239], v[76:79], v[112:115]
	ds_read_b128 v[236:239], v173 offset:17344
	s_waitcnt lgkmcnt(7)
	v_mfma_f32_16x16x32_bf16 v[128:131], v[240:243], v[76:79], v[128:131]
	s_waitcnt lgkmcnt(6)
	v_mfma_f32_16x16x32_bf16 v[100:103], v[204:207], v[40:43], v[100:103]
	s_waitcnt lgkmcnt(5)
	v_mfma_f32_16x16x32_bf16 v[104:107], v[208:211], v[40:43], v[104:107]
	s_waitcnt lgkmcnt(4)
	v_mfma_f32_16x16x32_bf16 v[112:115], v[218:221], v[40:43], v[112:115]
	s_waitcnt lgkmcnt(3)
	v_mfma_f32_16x16x32_bf16 v[128:131], v[224:227], v[40:43], v[128:131]
	s_waitcnt lgkmcnt(2)
	v_mfma_f32_16x16x32_bf16 v[100:103], v[228:231], v[36:39], v[100:103]
	s_waitcnt lgkmcnt(1)
	v_mfma_f32_16x16x32_bf16 v[104:107], v[232:235], v[36:39], v[104:107]
	s_waitcnt lgkmcnt(0)
	v_mfma_f32_16x16x32_bf16 v[112:115], v[236:239], v[36:39], v[112:115]
	s_nop 7
	ds_read_b128 v[132:135], v173 offset:25792
	s_waitcnt vmcnt(7)
	ds_write_b128 v170, v[60:63]
	s_waitcnt vmcnt(6)
	ds_write_b128 v170, v[64:67] offset:128
	s_waitcnt vmcnt(5)
	ds_write_b128 v170, v[68:71] offset:256
	s_waitcnt vmcnt(4)
	ds_write_b128 v170, v[72:75] offset:384
	global_load_dwordx4 v[60:63], v[166:167], off offset:2048
	global_load_dwordx4 v[64:67], v[166:167], off offset:2176
	global_load_dwordx4 v[68:71], v[166:167], off offset:2304
	global_load_dwordx4 v[72:75], v[166:167], off offset:2432
	s_waitcnt lgkmcnt(0)
	s_barrier
	s_waitcnt lgkmcnt(4)
	v_mfma_f32_16x16x32_bf16 v[128:131], v[132:135], v[36:39], v[128:131]
	ds_read_b128 v[204:207], v174
	ds_read_b128 v[208:211], v174 offset:8448
	ds_read_b128 v[218:221], v174 offset:16896
	ds_read_b128 v[224:227], v174 offset:25344
	ds_read_b128 v[228:231], v174 offset:64
	ds_read_b128 v[232:235], v174 offset:8512
	ds_read_b128 v[236:239], v174 offset:16960
	ds_read_b128 v[240:243], v174 offset:25408
	s_waitcnt lgkmcnt(7)
	v_mfma_f32_16x16x32_bf16 v[132:135], v[204:207], v[124:127], 0
	ds_read_b128 v[204:207], v174 offset:128
	s_waitcnt lgkmcnt(7)
	v_mfma_f32_16x16x32_bf16 v[136:139], v[208:211], v[124:127], 0
	ds_read_b128 v[208:211], v174 offset:8576
	s_waitcnt lgkmcnt(7)
	v_mfma_f32_16x16x32_bf16 v[140:143], v[218:221], v[124:127], 0
	ds_read_b128 v[218:221], v174 offset:17024
	s_waitcnt lgkmcnt(7)
	v_mfma_f32_16x16x32_bf16 v[144:147], v[224:227], v[124:127], 0
	ds_read_b128 v[224:227], v174 offset:25472
	s_waitcnt lgkmcnt(7)
	v_mfma_f32_16x16x32_bf16 v[132:135], v[228:231], v[120:123], v[132:135]
	ds_read_b128 v[228:231], v174 offset:192
	s_waitcnt lgkmcnt(7)
	v_mfma_f32_16x16x32_bf16 v[136:139], v[232:235], v[120:123], v[136:139]
	ds_read_b128 v[232:235], v174 offset:8640
	s_waitcnt lgkmcnt(7)
	v_mfma_f32_16x16x32_bf16 v[140:143], v[236:239], v[120:123], v[140:143]
	ds_read_b128 v[236:239], v174 offset:17088
	s_waitcnt lgkmcnt(7)
	v_mfma_f32_16x16x32_bf16 v[144:147], v[240:243], v[120:123], v[144:147]
	ds_read_b128 v[240:243], v174 offset:25536
	s_waitcnt lgkmcnt(7)
	v_mfma_f32_16x16x32_bf16 v[132:135], v[204:207], v[116:119], v[132:135]
	ds_read_b128 v[204:207], v174 offset:256
	s_waitcnt lgkmcnt(7)
	v_mfma_f32_16x16x32_bf16 v[136:139], v[208:211], v[116:119], v[136:139]
	ds_read_b128 v[208:211], v174 offset:8704
	s_waitcnt lgkmcnt(7)
	v_mfma_f32_16x16x32_bf16 v[140:143], v[218:221], v[116:119], v[140:143]
	ds_read_b128 v[218:221], v174 offset:17152
	s_waitcnt lgkmcnt(7)
	v_mfma_f32_16x16x32_bf16 v[144:147], v[224:227], v[116:119], v[144:147]
	ds_read_b128 v[224:227], v174 offset:25600
	s_waitcnt lgkmcnt(7)
	v_mfma_f32_16x16x32_bf16 v[132:135], v[228:231], v[108:111], v[132:135]
	ds_read_b128 v[228:231], v174 offset:320
	s_waitcnt lgkmcnt(7)
	v_mfma_f32_16x16x32_bf16 v[136:139], v[232:235], v[108:111], v[136:139]
	ds_read_b128 v[232:235], v174 offset:8768
	s_waitcnt lgkmcnt(7)
	v_mfma_f32_16x16x32_bf16 v[140:143], v[236:239], v[108:111], v[140:143]
	ds_read_b128 v[236:239], v174 offset:17216
	s_waitcnt lgkmcnt(7)
	v_mfma_f32_16x16x32_bf16 v[144:147], v[240:243], v[108:111], v[144:147]
	ds_read_b128 v[240:243], v174 offset:25664
	s_waitcnt lgkmcnt(7)
	v_mfma_f32_16x16x32_bf16 v[132:135], v[204:207], v[80:83], v[132:135]
	ds_read_b128 v[204:207], v174 offset:384
	s_waitcnt lgkmcnt(7)
	v_mfma_f32_16x16x32_bf16 v[136:139], v[208:211], v[80:83], v[136:139]
	ds_read_b128 v[208:211], v174 offset:8832
	s_waitcnt lgkmcnt(7)
	v_mfma_f32_16x16x32_bf16 v[140:143], v[218:221], v[80:83], v[140:143]
	ds_read_b128 v[218:221], v174 offset:17280
	s_waitcnt lgkmcnt(7)
	v_mfma_f32_16x16x32_bf16 v[144:147], v[224:227], v[80:83], v[144:147]
	ds_read_b128 v[224:227], v174 offset:25728
	s_waitcnt lgkmcnt(7)
	v_mfma_f32_16x16x32_bf16 v[132:135], v[228:231], v[76:79], v[132:135]
	ds_read_b128 v[228:231], v174 offset:448
	s_waitcnt lgkmcnt(7)
	v_mfma_f32_16x16x32_bf16 v[136:139], v[232:235], v[76:79], v[136:139]
	ds_read_b128 v[232:235], v174 offset:8896
	s_waitcnt lgkmcnt(7)
	v_mfma_f32_16x16x32_bf16 v[140:143], v[236:239], v[76:79], v[140:143]
	ds_read_b128 v[236:239], v174 offset:17344
	s_waitcnt lgkmcnt(7)
	v_mfma_f32_16x16x32_bf16 v[144:147], v[240:243], v[76:79], v[144:147]
	s_waitcnt lgkmcnt(6)
	v_mfma_f32_16x16x32_bf16 v[132:135], v[204:207], v[40:43], v[132:135]
	s_waitcnt lgkmcnt(5)
	v_mfma_f32_16x16x32_bf16 v[136:139], v[208:211], v[40:43], v[136:139]
	s_waitcnt lgkmcnt(4)
	v_mfma_f32_16x16x32_bf16 v[140:143], v[218:221], v[40:43], v[140:143]
	s_waitcnt lgkmcnt(3)
	v_mfma_f32_16x16x32_bf16 v[144:147], v[224:227], v[40:43], v[144:147]
	s_waitcnt lgkmcnt(2)
	v_mfma_f32_16x16x32_bf16 v[132:135], v[228:231], v[36:39], v[132:135]
	s_waitcnt lgkmcnt(1)
	v_mfma_f32_16x16x32_bf16 v[136:139], v[232:235], v[36:39], v[136:139]
	s_waitcnt lgkmcnt(0)
	v_mfma_f32_16x16x32_bf16 v[140:143], v[236:239], v[36:39], v[140:143]
	s_nop 7
	ds_read_b128 v[148:151], v174 offset:25792
	s_waitcnt vmcnt(7)
	ds_write_b128 v168, v[44:47]
	s_waitcnt vmcnt(6)
	ds_write_b128 v168, v[48:51] offset:128
	s_waitcnt vmcnt(5)
	ds_write_b128 v168, v[52:55] offset:256
	s_waitcnt vmcnt(4)
	ds_write_b128 v168, v[56:59] offset:384
	global_load_dwordx4 v[44:47], v[164:165], off offset:2048
	global_load_dwordx4 v[48:51], v[164:165], off offset:2176
	global_load_dwordx4 v[52:55], v[164:165], off offset:2304
	global_load_dwordx4 v[56:59], v[164:165], off offset:2432
	s_waitcnt lgkmcnt(0)
	s_barrier
	s_waitcnt lgkmcnt(4)
	v_mfma_f32_16x16x32_bf16 v[144:147], v[148:151], v[36:39], v[144:147]
	ds_read_b128 v[204:207], v173
	ds_read_b128 v[208:211], v173 offset:64
	ds_read_b128 v[218:221], v173 offset:128
	ds_read_b128 v[224:227], v173 offset:192
	ds_read_b128 v[228:231], v173 offset:256
	ds_read_b128 v[232:235], v173 offset:320
	ds_read_b128 v[236:239], v173 offset:384
	ds_read_b128 v[240:243], v173 offset:448
	s_waitcnt lgkmcnt(7)
	v_mfma_f32_16x16x32_bf16 v[148:151], v[204:207], v[124:127], 0
	ds_read_b128 v[204:207], v173 offset:8448
	s_waitcnt lgkmcnt(7)
	v_mfma_f32_16x16x32_bf16 v[148:151], v[208:211], v[120:123], v[148:151]
	ds_read_b128 v[208:211], v173 offset:8512
	s_waitcnt lgkmcnt(7)
	v_mfma_f32_16x16x32_bf16 v[148:151], v[218:221], v[116:119], v[148:151]
	ds_read_b128 v[218:221], v173 offset:8576
	s_waitcnt lgkmcnt(7)
	v_mfma_f32_16x16x32_bf16 v[148:151], v[224:227], v[108:111], v[148:151]
	ds_read_b128 v[224:227], v173 offset:8640
	s_waitcnt lgkmcnt(7)
	v_mfma_f32_16x16x32_bf16 v[148:151], v[228:231], v[80:83], v[148:151]
	ds_read_b128 v[228:231], v173 offset:8704
	s_waitcnt lgkmcnt(7)
	v_mfma_f32_16x16x32_bf16 v[148:151], v[232:235], v[76:79], v[148:151]
	ds_read_b128 v[232:235], v173 offset:8768
	s_waitcnt lgkmcnt(7)
	v_mfma_f32_16x16x32_bf16 v[148:151], v[236:239], v[40:43], v[148:151]
	ds_read_b128 v[236:239], v173 offset:8832
	s_waitcnt lgkmcnt(7)
	v_mfma_f32_16x16x32_bf16 v[148:151], v[240:243], v[36:39], v[148:151]
	ds_read_b128 v[240:243], v173 offset:8896
	s_waitcnt lgkmcnt(7)
	v_mfma_f32_16x16x32_bf16 v[152:155], v[204:207], v[124:127], 0
	ds_read_b128 v[204:207], v173 offset:16896
	s_waitcnt lgkmcnt(7)
	v_mfma_f32_16x16x32_bf16 v[152:155], v[208:211], v[120:123], v[152:155]
	ds_read_b128 v[208:211], v173 offset:16960
	s_waitcnt lgkmcnt(7)
	v_mfma_f32_16x16x32_bf16 v[152:155], v[218:221], v[116:119], v[152:155]
	ds_read_b128 v[218:221], v173 offset:17024
	s_waitcnt lgkmcnt(7)
	v_mfma_f32_16x16x32_bf16 v[152:155], v[224:227], v[108:111], v[152:155]
	ds_read_b128 v[224:227], v173 offset:17088
	s_waitcnt lgkmcnt(7)
	v_mfma_f32_16x16x32_bf16 v[152:155], v[228:231], v[80:83], v[152:155]
	ds_read_b128 v[228:231], v173 offset:17152
	s_waitcnt lgkmcnt(7)
	v_mfma_f32_16x16x32_bf16 v[152:155], v[232:235], v[76:79], v[152:155]
	ds_read_b128 v[232:235], v173 offset:17216
	s_waitcnt lgkmcnt(7)
	v_mfma_f32_16x16x32_bf16 v[152:155], v[236:239], v[40:43], v[152:155]
	ds_read_b128 v[236:239], v173 offset:17280
	s_waitcnt lgkmcnt(7)
	v_mfma_f32_16x16x32_bf16 v[152:155], v[240:243], v[36:39], v[152:155]
	ds_read_b128 v[240:243], v173 offset:17344
	s_waitcnt lgkmcnt(7)
	v_mfma_f32_16x16x32_bf16 v[156:159], v[204:207], v[124:127], 0
	ds_read_b128 v[204:207], v173 offset:25344
	s_waitcnt lgkmcnt(7)
	v_mfma_f32_16x16x32_bf16 v[156:159], v[208:211], v[120:123], v[156:159]
	ds_read_b128 v[208:211], v173 offset:25408
	s_waitcnt lgkmcnt(7)
	v_mfma_f32_16x16x32_bf16 v[156:159], v[218:221], v[116:119], v[156:159]
	ds_read_b128 v[218:221], v173 offset:25472
	s_waitcnt lgkmcnt(7)
	v_mfma_f32_16x16x32_bf16 v[156:159], v[224:227], v[108:111], v[156:159]
	ds_read_b128 v[224:227], v173 offset:25536
	s_waitcnt lgkmcnt(7)
	v_mfma_f32_16x16x32_bf16 v[156:159], v[228:231], v[80:83], v[156:159]
	ds_read_b128 v[228:231], v173 offset:25600
	s_waitcnt lgkmcnt(7)
	v_mfma_f32_16x16x32_bf16 v[156:159], v[232:235], v[76:79], v[156:159]
	ds_read_b128 v[232:235], v173 offset:25664
	s_waitcnt lgkmcnt(7)
	v_mfma_f32_16x16x32_bf16 v[156:159], v[236:239], v[40:43], v[156:159]
	ds_read_b128 v[236:239], v173 offset:25728
	s_waitcnt lgkmcnt(7)
	v_mfma_f32_16x16x32_bf16 v[156:159], v[240:243], v[36:39], v[156:159]
	ds_read_b128 v[240:243], v173 offset:25792
	s_waitcnt lgkmcnt(7)
	v_mfma_f32_16x16x32_bf16 v[124:127], v[204:207], v[124:127], 0
	s_waitcnt lgkmcnt(6)
	v_mfma_f32_16x16x32_bf16 v[120:123], v[208:211], v[120:123], v[124:127]
	s_nop 4
	s_waitcnt lgkmcnt(5)
	v_mfma_f32_16x16x32_bf16 v[116:119], v[218:221], v[116:119], v[120:123]
	s_nop 2
	s_waitcnt lgkmcnt(4)
	v_mfma_f32_16x16x32_bf16 v[108:111], v[224:227], v[108:111], v[116:119]
	s_nop 2
	s_waitcnt lgkmcnt(3)
	v_mfma_f32_16x16x32_bf16 v[80:83], v[228:231], v[80:83], v[108:111]
	s_nop 2
	s_waitcnt lgkmcnt(2)
	v_mfma_f32_16x16x32_bf16 v[76:79], v[232:235], v[76:79], v[80:83]
	s_nop 2
	s_waitcnt lgkmcnt(1)
	v_mfma_f32_16x16x32_bf16 v[40:43], v[236:239], v[40:43], v[76:79]
	s_nop 2
	s_waitcnt vmcnt(7)
	ds_write_b128 v170, v[60:63]
	s_waitcnt vmcnt(6)
	ds_write_b128 v170, v[64:67] offset:128
	s_waitcnt vmcnt(5)
	ds_write_b128 v170, v[68:71] offset:256
	s_waitcnt vmcnt(4)
	ds_write_b128 v170, v[72:75] offset:384
	global_load_dwordx4 v[60:63], v[162:163], off offset:2048
	global_load_dwordx4 v[64:67], v[162:163], off offset:2176
	global_load_dwordx4 v[68:71], v[162:163], off offset:2304
	global_load_dwordx4 v[72:75], v[162:163], off offset:2432
	s_waitcnt lgkmcnt(4)
	v_mfma_f32_16x16x32_bf16 v[36:39], v[240:243], v[36:39], v[40:43]
	s_nop 7
	s_nop 2
	v_max_f32_e32 v40, v87, v87
	v_max_f32_e32 v41, v86, v86
	v_max_f32_e32 v40, v41, v40
	v_max_f32_e32 v41, v91, v91
	v_max_f32_e32 v42, v90, v90
	v_max_f32_e32 v41, v42, v41
	v_max3_f32 v40, v84, v85, v40
	v_max3_f32 v41, v88, v89, v41
	v_max3_f32 v40, v40, s7, v41
	v_max_f32_e32 v41, v95, v95
	v_max_f32_e32 v42, v94, v94
	v_max_f32_e32 v41, v42, v41
	v_max_f32_e32 v42, v99, v99
	v_max_f32_e32 v43, v98, v98
	v_max_f32_e32 v42, v43, v42
	v_max3_f32 v41, v92, v93, v41
	v_max3_f32 v42, v96, v97, v42
	v_max3_f32 v40, v40, v41, v42
	v_max_f32_e32 v41, v103, v103
	v_max_f32_e32 v42, v102, v102
	v_max_f32_e32 v41, v42, v41
	v_max_f32_e32 v42, v107, v107
	v_max_f32_e32 v43, v106, v106
	v_max_f32_e32 v42, v43, v42
	v_max3_f32 v41, v100, v101, v41
	v_max3_f32 v42, v104, v105, v42
	v_max3_f32 v40, v40, v41, v42
	v_max_f32_e32 v41, v115, v115
	v_max_f32_e32 v42, v114, v114
	v_max_f32_e32 v41, v42, v41
	v_max_f32_e32 v42, v131, v131
	v_max_f32_e32 v43, v130, v130
	v_max_f32_e32 v42, v43, v42
	v_max3_f32 v41, v112, v113, v41
	v_max3_f32 v42, v128, v129, v42
	v_max3_f32 v40, v40, v41, v42
	v_max_f32_e32 v41, v135, v135
	v_max_f32_e32 v42, v134, v134
	v_max_f32_e32 v41, v42, v41
	v_max_f32_e32 v42, v139, v139
	v_max_f32_e32 v43, v138, v138
	v_max_f32_e32 v42, v43, v42
	v_max3_f32 v41, v132, v133, v41
	v_max3_f32 v42, v136, v137, v42
	v_max3_f32 v40, v40, v41, v42
	v_max_f32_e32 v41, v143, v143
	v_max_f32_e32 v42, v142, v142
	v_max_f32_e32 v41, v42, v41
	v_max_f32_e32 v42, v147, v147
	v_max_f32_e32 v43, v146, v146
	v_max_f32_e32 v42, v43, v42
	v_max3_f32 v41, v140, v141, v41
	v_max3_f32 v42, v144, v145, v42
	v_max3_f32 v40, v40, v41, v42
	v_max_f32_e32 v41, v151, v151
	v_max_f32_e32 v42, v150, v150
	v_max_f32_e32 v41, v42, v41
	v_max_f32_e32 v42, v155, v155
	v_max_f32_e32 v43, v154, v154
	v_max_f32_e32 v42, v43, v42
	v_max3_f32 v41, v148, v149, v41
	v_max3_f32 v42, v152, v153, v42
	v_max3_f32 v40, v40, v41, v42
	v_max_f32_e32 v41, v159, v159
	v_max_f32_e32 v42, v158, v158
	v_max_f32_e32 v41, v42, v41
	v_max_f32_e32 v42, v39, v39
	v_max_f32_e32 v43, v38, v38
	v_max_f32_e32 v42, v43, v42
	v_max3_f32 v41, v156, v157, v41
	v_max3_f32 v42, v36, v37, v42
	v_max3_f32 v40, v40, v41, v42
	ds_bpermute_b32 v41, v171, v40
	s_waitcnt lgkmcnt(0)
	s_barrier
	s_waitcnt lgkmcnt(0)
	v_max_f32_e32 v41, v41, v41
	v_max_f32_e32 v40, v40, v41
	ds_bpermute_b32 v41, v172, v40
	s_waitcnt lgkmcnt(0)
	v_max_f32_e32 v41, v41, v41
	v_max_f32_e32 v182, v40, v41
	v_sub_f32_e32 v40, v84, v182
	v_mul_f32_e32 v40, 0x3d800000, v40
	v_sub_f32_e32 v41, v85, v182
	v_mul_f32_e32 v40, 0x3fb8aa3b, v40
	v_mul_f32_e32 v41, 0x3d800000, v41
	v_exp_f32_e32 v40, v40
	v_mul_f32_e32 v41, 0x3fb8aa3b, v41
	v_exp_f32_e32 v41, v41
	v_sub_f32_e32 v85, v96, v182
	v_add_f32_e32 v42, 0, v40
	v_mul_f32_e32 v85, 0x3d800000, v85
	v_add_f32_e32 v43, v41, v42
	v_sub_f32_e32 v42, v86, v182
	v_mul_f32_e32 v42, 0x3d800000, v42
	v_mul_f32_e32 v42, 0x3fb8aa3b, v42
	v_exp_f32_e32 v42, v42
	v_mul_f32_e32 v85, 0x3fb8aa3b, v85
	v_sub_f32_e32 v36, v36, v182
	v_mul_f32_e32 v36, 0x3d800000, v36
	v_add_f32_e32 v76, v42, v43
	v_sub_f32_e32 v43, v87, v182
	v_mul_f32_e32 v43, 0x3d800000, v43
	v_mul_f32_e32 v43, 0x3fb8aa3b, v43
	v_exp_f32_e32 v43, v43
	v_mul_f32_e32 v36, 0x3fb8aa3b, v36
	v_exp_f32_e32 v195, v36
	v_sub_f32_e32 v37, v37, v182
	v_add_f32_e32 v77, v43, v76
	v_sub_f32_e32 v76, v88, v182
	v_mul_f32_e32 v76, 0x3d800000, v76
	v_mul_f32_e32 v76, 0x3fb8aa3b, v76
	v_exp_f32_e32 v76, v76
	v_exp_f32_e32 v88, v85
	v_sub_f32_e32 v85, v97, v182
	v_mul_f32_e32 v85, 0x3d800000, v85
	v_add_f32_e32 v78, v76, v77
	v_sub_f32_e32 v77, v89, v182
	v_mul_f32_e32 v77, 0x3d800000, v77
	v_mul_f32_e32 v77, 0x3fb8aa3b, v77
	v_exp_f32_e32 v77, v77
	v_mul_f32_e32 v85, 0x3fb8aa3b, v85
	v_exp_f32_e32 v89, v85
	v_sub_f32_e32 v85, v98, v182
	v_add_f32_e32 v79, v77, v78
	v_sub_f32_e32 v78, v90, v182
	v_mul_f32_e32 v78, 0x3d800000, v78
	v_mul_f32_e32 v78, 0x3fb8aa3b, v78
	v_mul_f32_e32 v85, 0x3d800000, v85
	v_exp_f32_e32 v78, v78
	v_mul_f32_e32 v85, 0x3fb8aa3b, v85
	v_exp_f32_e32 v90, v85
	v_sub_f32_e32 v85, v99, v182
	v_mul_f32_e32 v85, 0x3d800000, v85
	v_mul_f32_e32 v85, 0x3fb8aa3b, v85
	v_add_f32_e32 v80, v78, v79
	v_sub_f32_e32 v79, v91, v182
	v_exp_f32_e32 v91, v85
	v_sub_f32_e32 v85, v100, v182
	v_mul_f32_e32 v85, 0x3d800000, v85
	v_mul_f32_e32 v85, 0x3fb8aa3b, v85
	v_exp_f32_e32 v96, v85
	v_sub_f32_e32 v85, v101, v182
	v_mul_f32_e32 v85, 0x3d800000, v85
	v_mul_f32_e32 v85, 0x3fb8aa3b, v85
	v_exp_f32_e32 v97, v85
	v_sub_f32_e32 v85, v102, v182
	v_mul_f32_e32 v85, 0x3d800000, v85
	v_mul_f32_e32 v85, 0x3fb8aa3b, v85
	v_exp_f32_e32 v98, v85
	v_sub_f32_e32 v85, v103, v182
	v_mul_f32_e32 v85, 0x3d800000, v85
	v_mul_f32_e32 v85, 0x3fb8aa3b, v85
	v_exp_f32_e32 v99, v85
	v_sub_f32_e32 v85, v104, v182
	v_mul_f32_e32 v85, 0x3d800000, v85
	v_mul_f32_e32 v85, 0x3fb8aa3b, v85
	v_exp_f32_e32 v100, v85
	v_sub_f32_e32 v85, v105, v182
	v_mul_f32_e32 v85, 0x3d800000, v85
	v_mul_f32_e32 v85, 0x3fb8aa3b, v85
	v_exp_f32_e32 v101, v85
	v_sub_f32_e32 v85, v106, v182
	v_mul_f32_e32 v85, 0x3d800000, v85
	v_mul_f32_e32 v85, 0x3fb8aa3b, v85
	v_exp_f32_e32 v102, v85
	v_sub_f32_e32 v85, v107, v182
	v_mul_f32_e32 v85, 0x3d800000, v85
	v_mul_f32_e32 v85, 0x3fb8aa3b, v85
	v_exp_f32_e32 v103, v85
	v_sub_f32_e32 v85, v112, v182
	v_mul_f32_e32 v85, 0x3d800000, v85
	v_mul_f32_e32 v85, 0x3fb8aa3b, v85
	v_exp_f32_e32 v104, v85
	v_sub_f32_e32 v85, v113, v182
	v_mul_f32_e32 v85, 0x3d800000, v85
	v_mul_f32_e32 v85, 0x3fb8aa3b, v85
	v_exp_f32_e32 v105, v85
	v_sub_f32_e32 v85, v114, v182
	v_mul_f32_e32 v85, 0x3d800000, v85
	v_mul_f32_e32 v85, 0x3fb8aa3b, v85
	v_exp_f32_e32 v106, v85
	v_sub_f32_e32 v85, v115, v182
	v_mul_f32_e32 v85, 0x3d800000, v85
	v_mul_f32_e32 v85, 0x3fb8aa3b, v85
	v_exp_f32_e32 v107, v85
	v_sub_f32_e32 v85, v128, v182
	v_mul_f32_e32 v85, 0x3d800000, v85
	v_mul_f32_e32 v85, 0x3fb8aa3b, v85
	v_exp_f32_e32 v108, v85
	v_sub_f32_e32 v85, v129, v182
	v_mul_f32_e32 v85, 0x3d800000, v85
	v_mul_f32_e32 v85, 0x3fb8aa3b, v85
	v_exp_f32_e32 v109, v85
	v_sub_f32_e32 v85, v130, v182
	v_mul_f32_e32 v85, 0x3d800000, v85
	v_mul_f32_e32 v85, 0x3fb8aa3b, v85
	v_exp_f32_e32 v110, v85
	v_sub_f32_e32 v85, v131, v182
	v_mul_f32_e32 v85, 0x3d800000, v85
	v_mul_f32_e32 v85, 0x3fb8aa3b, v85
	v_exp_f32_e32 v111, v85
	v_sub_f32_e32 v85, v132, v182
	v_mul_f32_e32 v85, 0x3d800000, v85
	v_mul_f32_e32 v85, 0x3fb8aa3b, v85
	v_exp_f32_e32 v112, v85
	v_sub_f32_e32 v85, v133, v182
	v_mul_f32_e32 v85, 0x3d800000, v85
	v_mul_f32_e32 v85, 0x3fb8aa3b, v85
	v_mul_f32_e32 v79, 0x3d800000, v79
	v_exp_f32_e32 v113, v85
	v_sub_f32_e32 v85, v134, v182
	v_mul_f32_e32 v79, 0x3fb8aa3b, v79
	v_mul_f32_e32 v85, 0x3d800000, v85
	v_exp_f32_e32 v79, v79
	v_mul_f32_e32 v85, 0x3fb8aa3b, v85
	v_exp_f32_e32 v114, v85
	v_sub_f32_e32 v85, v135, v182
	v_mul_f32_e32 v85, 0x3d800000, v85
	v_mul_f32_e32 v85, 0x3fb8aa3b, v85
	v_add_f32_e32 v81, v79, v80
	v_sub_f32_e32 v80, v92, v182
	v_exp_f32_e32 v115, v85
	v_sub_f32_e32 v85, v136, v182
	v_mul_f32_e32 v80, 0x3d800000, v80
	v_mul_f32_e32 v85, 0x3d800000, v85
	v_mul_f32_e32 v80, 0x3fb8aa3b, v80
	v_mul_f32_e32 v85, 0x3fb8aa3b, v85
	v_exp_f32_e32 v80, v80
	v_exp_f32_e32 v116, v85
	v_sub_f32_e32 v85, v137, v182
	v_mul_f32_e32 v85, 0x3d800000, v85
	v_mul_f32_e32 v85, 0x3fb8aa3b, v85
	v_exp_f32_e32 v117, v85
	v_sub_f32_e32 v85, v138, v182
	v_add_f32_e32 v82, v80, v81
	v_sub_f32_e32 v81, v93, v182
	v_mul_f32_e32 v85, 0x3d800000, v85
	v_mul_f32_e32 v81, 0x3d800000, v81
	v_mul_f32_e32 v85, 0x3fb8aa3b, v85
	v_mul_f32_e32 v81, 0x3fb8aa3b, v81
	v_exp_f32_e32 v118, v85
	v_sub_f32_e32 v85, v139, v182
	v_exp_f32_e32 v81, v81
	v_mul_f32_e32 v85, 0x3d800000, v85
	v_mul_f32_e32 v85, 0x3fb8aa3b, v85
	v_exp_f32_e32 v119, v85
	v_sub_f32_e32 v85, v140, v182
	v_mul_f32_e32 v85, 0x3d800000, v85
	v_add_f32_e32 v83, v81, v82
	v_sub_f32_e32 v82, v94, v182
	v_mul_f32_e32 v85, 0x3fb8aa3b, v85
	v_mul_f32_e32 v82, 0x3d800000, v82
	v_exp_f32_e32 v120, v85
	v_sub_f32_e32 v85, v141, v182
	v_mul_f32_e32 v82, 0x3fb8aa3b, v82
	v_mul_f32_e32 v85, 0x3d800000, v85
	v_exp_f32_e32 v82, v82
	v_mul_f32_e32 v85, 0x3fb8aa3b, v85
	v_exp_f32_e32 v121, v85
	v_sub_f32_e32 v85, v142, v182
	v_mul_f32_e32 v85, 0x3d800000, v85
	v_mul_f32_e32 v85, 0x3fb8aa3b, v85
	v_add_f32_e32 v84, v82, v83
	v_sub_f32_e32 v83, v95, v182
	v_exp_f32_e32 v122, v85
	v_sub_f32_e32 v85, v143, v182
	v_mul_f32_e32 v83, 0x3d800000, v83
	v_mul_f32_e32 v85, 0x3d800000, v85
	v_mul_f32_e32 v83, 0x3fb8aa3b, v83
	v_mul_f32_e32 v85, 0x3fb8aa3b, v85
	v_exp_f32_e32 v83, v83
	v_exp_f32_e32 v123, v85
	v_sub_f32_e32 v85, v144, v182
	v_mul_f32_e32 v85, 0x3d800000, v85
	v_mul_f32_e32 v85, 0x3fb8aa3b, v85
	v_exp_f32_e32 v124, v85
	v_sub_f32_e32 v85, v145, v182
	v_add_f32_e32 v84, v83, v84
	v_mul_f32_e32 v85, 0x3d800000, v85
	v_add_f32_e32 v84, v88, v84
	v_mul_f32_e32 v85, 0x3fb8aa3b, v85
	v_add_f32_e32 v84, v89, v84
	v_exp_f32_e32 v125, v85
	v_sub_f32_e32 v85, v146, v182
	v_add_f32_e32 v84, v90, v84
	v_mul_f32_e32 v85, 0x3d800000, v85
	v_add_f32_e32 v84, v91, v84
	v_mul_f32_e32 v85, 0x3fb8aa3b, v85
	v_add_f32_e32 v84, v96, v84
	v_exp_f32_e32 v126, v85
	v_sub_f32_e32 v85, v147, v182
	v_add_f32_e32 v84, v97, v84
	v_mul_f32_e32 v85, 0x3d800000, v85
	v_add_f32_e32 v84, v98, v84
	v_mul_f32_e32 v85, 0x3fb8aa3b, v85
	v_add_f32_e32 v84, v99, v84
	v_exp_f32_e32 v127, v85
	v_sub_f32_e32 v85, v148, v182
	v_add_f32_e32 v84, v100, v84
	v_mul_f32_e32 v85, 0x3d800000, v85
	v_add_f32_e32 v84, v101, v84
	v_mul_f32_e32 v85, 0x3fb8aa3b, v85
	v_add_f32_e32 v84, v102, v84
	v_exp_f32_e32 v177, v85
	v_sub_f32_e32 v85, v149, v182
	v_add_f32_e32 v84, v103, v84
	v_mul_f32_e32 v85, 0x3d800000, v85
	v_add_f32_e32 v84, v104, v84
	v_mul_f32_e32 v85, 0x3fb8aa3b, v85
	v_add_f32_e32 v84, v105, v84
	v_exp_f32_e32 v178, v85
	v_sub_f32_e32 v85, v150, v182
	v_add_f32_e32 v84, v106, v84
	v_mul_f32_e32 v85, 0x3d800000, v85
	v_add_f32_e32 v84, v107, v84
	v_mul_f32_e32 v85, 0x3fb8aa3b, v85
	v_add_f32_e32 v84, v108, v84
	v_exp_f32_e32 v179, v85
	v_sub_f32_e32 v85, v151, v182
	v_add_f32_e32 v84, v109, v84
	v_mul_f32_e32 v85, 0x3d800000, v85
	v_add_f32_e32 v84, v110, v84
	v_mul_f32_e32 v85, 0x3fb8aa3b, v85
	v_add_f32_e32 v84, v111, v84
	v_exp_f32_e32 v180, v85
	v_sub_f32_e32 v85, v152, v182
	v_add_f32_e32 v84, v112, v84
	v_mul_f32_e32 v85, 0x3d800000, v85
	v_add_f32_e32 v84, v113, v84
	v_mul_f32_e32 v85, 0x3fb8aa3b, v85
	v_add_f32_e32 v84, v114, v84
	v_exp_f32_e32 v187, v85
	v_sub_f32_e32 v85, v153, v182
	v_add_f32_e32 v84, v115, v84
	v_mul_f32_e32 v85, 0x3d800000, v85
	v_add_f32_e32 v84, v116, v84
	v_mul_f32_e32 v85, 0x3fb8aa3b, v85
	v_add_f32_e32 v84, v117, v84
	v_exp_f32_e32 v190, v85
	v_sub_f32_e32 v85, v154, v182
	v_add_f32_e32 v84, v118, v84
	v_mul_f32_e32 v85, 0x3d800000, v85
	v_add_f32_e32 v84, v119, v84
	v_mul_f32_e32 v85, 0x3fb8aa3b, v85
	v_add_f32_e32 v84, v120, v84
	v_exp_f32_e32 v191, v85
	v_sub_f32_e32 v85, v155, v182
	v_add_f32_e32 v84, v121, v84
	v_mul_f32_e32 v85, 0x3d800000, v85
	v_add_f32_e32 v84, v122, v84
	v_mul_f32_e32 v85, 0x3fb8aa3b, v85
	v_add_f32_e32 v84, v123, v84
	v_exp_f32_e32 v192, v85
	v_sub_f32_e32 v85, v156, v182
	v_add_f32_e32 v84, v124, v84
	v_mul_f32_e32 v85, 0x3d800000, v85
	v_add_f32_e32 v84, v125, v84
	v_mul_f32_e32 v85, 0x3fb8aa3b, v85
	v_add_f32_e32 v84, v126, v84
	v_exp_f32_e32 v193, v85
	v_sub_f32_e32 v85, v157, v182
	v_add_f32_e32 v84, v127, v84
	v_mul_f32_e32 v85, 0x3d800000, v85
	v_add_f32_e32 v84, v177, v84
	v_mul_f32_e32 v85, 0x3fb8aa3b, v85
	v_add_f32_e32 v84, v178, v84
	v_exp_f32_e32 v194, v85
	v_sub_f32_e32 v85, v158, v182
	v_add_f32_e32 v84, v179, v84
	v_mul_f32_e32 v85, 0x3d800000, v85
	v_add_f32_e32 v84, v180, v84
	v_mul_f32_e32 v85, 0x3fb8aa3b, v85
	v_add_f32_e32 v84, v187, v84
	v_exp_f32_e32 v158, v85
	v_sub_f32_e32 v85, v159, v182
	v_add_f32_e32 v84, v190, v84
	v_mul_f32_e32 v85, 0x3d800000, v85
	v_add_f32_e32 v84, v191, v84
	v_mul_f32_e32 v85, 0x3fb8aa3b, v85
	v_add_f32_e32 v84, v192, v84
	v_exp_f32_e32 v159, v85
	v_add_f32_e32 v84, v193, v84
	v_add_f32_e32 v84, v194, v84
	v_add_f32_e32 v84, v158, v84
	v_cvt_pk_bf16_f32 v92, v80, v81
	v_cvt_pk_bf16_f32 v93, v82, v83
	v_cvt_pk_bf16_f32 v94, v88, v89
	v_cvt_pk_bf16_f32 v95, v90, v91
	v_cvt_pk_bf16_f32 v80, v96, v97
	v_cvt_pk_bf16_f32 v81, v98, v99
	v_cvt_pk_bf16_f32 v82, v100, v101
	ds_read_b64_tr_b16 v[204:205], v169
	ds_read_b64_tr_b16 v[206:207], v169 offset:8448
	ds_read_b64_tr_b16 v[208:209], v169 offset:16896
	ds_read_b64_tr_b16 v[210:211], v169 offset:25344
	ds_read_b64_tr_b16 v[218:219], v169 offset:32
	ds_read_b64_tr_b16 v[220:221], v169 offset:8480
	ds_read_b64_tr_b16 v[224:225], v169 offset:16928
	ds_read_b64_tr_b16 v[226:227], v169 offset:25376
	ds_read_b64_tr_b16 v[228:229], v169 offset:64
	ds_read_b64_tr_b16 v[230:231], v169 offset:8512
	ds_read_b64_tr_b16 v[232:233], v169 offset:16960
	ds_read_b64_tr_b16 v[234:235], v169 offset:25408
	ds_read_b64_tr_b16 v[236:237], v169 offset:96
	ds_read_b64_tr_b16 v[238:239], v169 offset:8544
	ds_read_b64_tr_b16 v[240:241], v169 offset:16992
	ds_read_b64_tr_b16 v[242:243], v169 offset:25440
	v_add_f32_e32 v84, v159, v84
	v_add_f32_e32 v36, v195, v84
	v_cvt_pk_bf16_f32 v84, v40, v41
	v_cvt_pk_bf16_f32 v85, v42, v43
	v_cvt_pk_bf16_f32 v86, v76, v77
	v_cvt_pk_bf16_f32 v87, v78, v79
	v_cvt_pk_bf16_f32 v83, v102, v103
	v_mul_f32_e32 v37, 0x3d800000, v37
	s_nop 1
	s_waitcnt lgkmcnt(14)
	v_mfma_f32_16x16x32_bf16 v[88:91], v[204:207], v[84:87], 0
	ds_read_b64_tr_b16 v[204:205], v169 offset:128
	ds_read_b64_tr_b16 v[206:207], v169 offset:8576
	v_mul_f32_e32 v37, 0x3fb8aa3b, v37
	v_exp_f32_e32 v196, v37
	v_sub_f32_e32 v37, v38, v182
	s_nop 1
	s_waitcnt lgkmcnt(14)
	v_mfma_f32_16x16x32_bf16 v[152:155], v[208:211], v[92:95], v[88:91]
	ds_read_b64_tr_b16 v[208:209], v169 offset:17024
	ds_read_b64_tr_b16 v[210:211], v169 offset:25472
	s_nop 1
	v_mul_f32_e32 v37, 0x3d800000, v37
	v_mul_f32_e32 v37, 0x3fb8aa3b, v37
	s_nop 1
	s_waitcnt lgkmcnt(14)
	v_mfma_f32_16x16x32_bf16 v[96:99], v[218:221], v[84:87], 0
	ds_read_b64_tr_b16 v[218:219], v169 offset:160
	ds_read_b64_tr_b16 v[220:221], v169 offset:8608
	v_cvt_pk_bf16_f32 v76, v104, v105
	v_cvt_pk_bf16_f32 v77, v106, v107
	v_exp_f32_e32 v197, v37
	s_nop 1
	s_waitcnt lgkmcnt(14)
	v_mfma_f32_16x16x32_bf16 v[88:91], v[224:227], v[92:95], v[96:99]
	ds_read_b64_tr_b16 v[224:225], v169 offset:17056
	ds_read_b64_tr_b16 v[226:227], v169 offset:25504
	s_nop 2
	v_sub_f32_e32 v37, v39, v182
	v_mul_f32_e32 v37, 0x3d800000, v37
	s_nop 1
	s_waitcnt lgkmcnt(14)
	v_mfma_f32_16x16x32_bf16 v[96:99], v[228:231], v[84:87], 0
	ds_read_b64_tr_b16 v[228:229], v169 offset:192
	ds_read_b64_tr_b16 v[230:231], v169 offset:8640
	v_mul_f32_e32 v37, 0x3fb8aa3b, v37
	v_exp_f32_e32 v198, v37
	v_add_f32_e32 v36, v196, v36
	s_nop 1
	s_waitcnt lgkmcnt(14)
	v_mfma_f32_16x16x32_bf16 v[128:131], v[232:235], v[92:95], v[96:99]
	ds_read_b64_tr_b16 v[232:233], v169 offset:17088
	ds_read_b64_tr_b16 v[234:235], v169 offset:25536
	s_nop 2
	v_add_f32_e32 v36, v197, v36
	v_add_f32_e32 v36, v198, v36
	s_nop 1
	s_waitcnt lgkmcnt(14)
	v_mfma_f32_16x16x32_bf16 v[96:99], v[236:239], v[84:87], 0
	ds_read_b64_tr_b16 v[236:237], v169 offset:224
	ds_read_b64_tr_b16 v[238:239], v169 offset:8672
	ds_bpermute_b32 v37, v171, v36
	v_cvt_pk_bf16_f32 v38, v124, v125
	v_cvt_pk_bf16_f32 v39, v126, v127
	s_nop 1
	s_waitcnt lgkmcnt(15)
	v_mfma_f32_16x16x32_bf16 v[104:107], v[240:243], v[92:95], v[96:99]
	ds_read_b64_tr_b16 v[240:241], v169 offset:17120
	ds_read_b64_tr_b16 v[242:243], v169 offset:25568
	s_nop 2
	s_waitcnt lgkmcnt(2)
	v_add_f32_e32 v156, v36, v37
	v_cvt_pk_bf16_f32 v36, v120, v121
	s_nop 1
	s_waitcnt lgkmcnt(15)
	v_mfma_f32_16x16x32_bf16 v[96:99], v[204:207], v[84:87], 0
	ds_read_b64_tr_b16 v[204:205], v169 offset:256
	ds_read_b64_tr_b16 v[206:207], v169 offset:8704
	v_cvt_pk_bf16_f32 v37, v122, v123
	v_cvt_pk_bf16_f32 v78, v108, v109
	v_cvt_pk_bf16_f32 v79, v110, v111
	s_nop 1
	s_waitcnt lgkmcnt(15)
	v_mfma_f32_16x16x32_bf16 v[148:151], v[208:211], v[92:95], v[96:99]
	ds_read_b64_tr_b16 v[208:209], v169 offset:17152
	ds_read_b64_tr_b16 v[210:211], v169 offset:25600
	s_nop 2
	v_cvt_pk_bf16_f32 v40, v112, v113
	v_cvt_pk_bf16_f32 v41, v114, v115
	s_nop 1
	s_waitcnt lgkmcnt(15)
	v_mfma_f32_16x16x32_bf16 v[96:99], v[218:221], v[84:87], 0
	ds_read_b64_tr_b16 v[218:219], v169 offset:288
	ds_read_b64_tr_b16 v[220:221], v169 offset:8736
	v_cvt_pk_bf16_f32 v42, v116, v117
	v_cvt_pk_bf16_f32 v43, v118, v119
	ds_bpermute_b32 v157, v172, v156
	s_waitcnt lgkmcnt(15)
	v_mfma_f32_16x16x32_bf16 v[120:123], v[224:227], v[92:95], v[96:99]
	ds_read_b64_tr_b16 v[224:225], v169 offset:17184
	ds_read_b64_tr_b16 v[226:227], v169 offset:25632
	s_nop 2
	s_waitcnt lgkmcnt(15)
	v_mfma_f32_16x16x32_bf16 v[96:99], v[228:231], v[84:87], 0
	ds_read_b64_tr_b16 v[228:229], v169 offset:320
	ds_read_b64_tr_b16 v[230:231], v169 offset:8768
	s_waitcnt lgkmcnt(15)
	v_mfma_f32_16x16x32_bf16 v[124:127], v[232:235], v[92:95], v[96:99]
	ds_read_b64_tr_b16 v[232:233], v169 offset:17216
	ds_read_b64_tr_b16 v[234:235], v169 offset:25664
	s_nop 5
	s_waitcnt lgkmcnt(15)
	v_mfma_f32_16x16x32_bf16 v[96:99], v[236:239], v[84:87], 0
	ds_read_b64_tr_b16 v[236:237], v169 offset:352
	ds_read_b64_tr_b16 v[238:239], v169 offset:8800
	s_waitcnt lgkmcnt(15)
	v_mfma_f32_16x16x32_bf16 v[108:111], v[240:243], v[92:95], v[96:99]
	ds_read_b64_tr_b16 v[240:241], v169 offset:17248
	ds_read_b64_tr_b16 v[242:243], v169 offset:25696
	s_nop 5
	s_waitcnt lgkmcnt(15)
	v_mfma_f32_16x16x32_bf16 v[96:99], v[204:207], v[84:87], 0
	ds_read_b64_tr_b16 v[204:205], v169 offset:384
	ds_read_b64_tr_b16 v[206:207], v169 offset:8832
	s_waitcnt lgkmcnt(15)
	v_mfma_f32_16x16x32_bf16 v[100:103], v[208:211], v[92:95], v[96:99]
	ds_read_b64_tr_b16 v[208:209], v169 offset:17280
	ds_read_b64_tr_b16 v[210:211], v169 offset:25728
	s_nop 5
	s_waitcnt lgkmcnt(15)
	v_mfma_f32_16x16x32_bf16 v[96:99], v[218:221], v[84:87], 0
	ds_read_b64_tr_b16 v[218:219], v169 offset:416
	ds_read_b64_tr_b16 v[220:221], v169 offset:8864
	s_waitcnt lgkmcnt(14)
	v_mfma_f32_16x16x32_bf16 v[112:115], v[224:227], v[92:95], v[96:99]
	ds_read_b64_tr_b16 v[224:225], v169 offset:17312
	ds_read_b64_tr_b16 v[226:227], v169 offset:25760
	s_nop 5
	s_waitcnt lgkmcnt(14)
	v_mfma_f32_16x16x32_bf16 v[96:99], v[228:231], v[84:87], 0
	ds_read_b64_tr_b16 v[228:229], v169 offset:448
	ds_read_b64_tr_b16 v[230:231], v169 offset:8896
	s_waitcnt lgkmcnt(14)
	v_mfma_f32_16x16x32_bf16 v[116:119], v[232:235], v[92:95], v[96:99]
	ds_read_b64_tr_b16 v[232:233], v169 offset:17344
	ds_read_b64_tr_b16 v[234:235], v169 offset:25792
	s_nop 5
	s_waitcnt lgkmcnt(14)
	v_mfma_f32_16x16x32_bf16 v[96:99], v[236:239], v[84:87], 0
	ds_read_b64_tr_b16 v[236:237], v169 offset:480
	ds_read_b64_tr_b16 v[238:239], v169 offset:8928
	s_waitcnt lgkmcnt(14)
	v_mfma_f32_16x16x32_bf16 v[132:135], v[240:243], v[92:95], v[96:99]
	s_nop 5
	s_waitcnt lgkmcnt(12)
	v_mfma_f32_16x16x32_bf16 v[96:99], v[204:207], v[84:87], 0
	s_waitcnt lgkmcnt(10)
	v_mfma_f32_16x16x32_bf16 v[136:139], v[208:211], v[92:95], v[96:99]
	s_nop 5
	s_waitcnt lgkmcnt(8)
	v_mfma_f32_16x16x32_bf16 v[96:99], v[218:221], v[84:87], 0
	s_waitcnt lgkmcnt(6)
	v_mfma_f32_16x16x32_bf16 v[140:143], v[224:227], v[92:95], v[96:99]
	s_nop 5
	s_waitcnt lgkmcnt(4)
	v_mfma_f32_16x16x32_bf16 v[96:99], v[228:231], v[84:87], 0
	s_waitcnt lgkmcnt(2)
	v_mfma_f32_16x16x32_bf16 v[144:147], v[232:235], v[92:95], v[96:99]
	s_nop 5
	ds_read_b64_tr_b16 v[200:201], v169 offset:17376
	ds_read_b64_tr_b16 v[202:203], v169 offset:25824
	s_waitcnt vmcnt(7)
	ds_write_b128 v168, v[44:47]
	s_waitcnt vmcnt(6)
	ds_write_b128 v168, v[48:51] offset:128
	s_waitcnt vmcnt(5)
	ds_write_b128 v168, v[52:55] offset:256
	s_waitcnt vmcnt(4)
	ds_write_b128 v168, v[56:59] offset:384
	global_load_dwordx4 v[44:47], v[160:161], off offset:2048
	global_load_dwordx4 v[48:51], v[160:161], off offset:2176
	global_load_dwordx4 v[52:55], v[160:161], off offset:2304
	global_load_dwordx4 v[56:59], v[160:161], off offset:2432
	s_waitcnt lgkmcnt(6)
	v_mfma_f32_16x16x32_bf16 v[84:87], v[236:239], v[84:87], 0
	s_nop 7
	s_waitcnt lgkmcnt(0)
	s_barrier
	s_waitcnt lgkmcnt(4)
	v_mfma_f32_16x16x32_bf16 v[96:99], v[200:203], v[92:95], v[84:87]
	s_nop 4
	ds_read_b64_tr_b16 v[204:205], v3
	ds_read_b64_tr_b16 v[206:207], v3 offset:8448
	ds_read_b64_tr_b16 v[208:209], v3 offset:32
	ds_read_b64_tr_b16 v[210:211], v3 offset:8480
	ds_read_b64_tr_b16 v[218:219], v3 offset:16928
	ds_read_b64_tr_b16 v[220:221], v3 offset:25376
	ds_read_b64_tr_b16 v[224:225], v3 offset:64
	ds_read_b64_tr_b16 v[226:227], v3 offset:8512
	ds_read_b64_tr_b16 v[228:229], v3 offset:16960
	ds_read_b64_tr_b16 v[230:231], v3 offset:25408
	ds_read_b64_tr_b16 v[232:233], v3 offset:96
	ds_read_b64_tr_b16 v[234:235], v3 offset:8544
	ds_read_b64_tr_b16 v[236:237], v3 offset:16992
	ds_read_b64_tr_b16 v[238:239], v3 offset:25440
	ds_read_b64_tr_b16 v[240:241], v3 offset:128
	ds_read_b64_tr_b16 v[242:243], v3 offset:8576
	s_waitcnt lgkmcnt(14)
	v_mfma_f32_16x16x32_bf16 v[84:87], v[204:207], v[80:83], v[152:155]
	ds_read_b64_tr_b16 v[204:205], v3 offset:17024
	ds_read_b64_tr_b16 v[206:207], v3 offset:25472
	s_nop 1
	s_waitcnt lgkmcnt(14)
	v_mfma_f32_16x16x32_bf16 v[88:91], v[208:211], v[80:83], v[88:91]
	ds_read_b64_tr_b16 v[208:209], v3 offset:160
	ds_read_b64_tr_b16 v[210:211], v3 offset:8608
	s_waitcnt lgkmcnt(14)
	v_mfma_f32_16x16x32_bf16 v[92:95], v[218:221], v[76:79], v[88:91]
	ds_read_b64_tr_b16 v[218:219], v3 offset:17056
	ds_read_b64_tr_b16 v[220:221], v3 offset:25504
	s_nop 5
	s_waitcnt lgkmcnt(14)
	v_mfma_f32_16x16x32_bf16 v[88:91], v[224:227], v[80:83], v[128:131]
	ds_read_b64_tr_b16 v[224:225], v3 offset:192
	ds_read_b64_tr_b16 v[226:227], v3 offset:8640
	s_waitcnt lgkmcnt(14)
	v_mfma_f32_16x16x32_bf16 v[88:91], v[228:231], v[76:79], v[88:91]
	ds_read_b64_tr_b16 v[228:229], v3 offset:17088
	ds_read_b64_tr_b16 v[230:231], v3 offset:25536
	s_nop 0
	s_waitcnt lgkmcnt(14)
	v_mfma_f32_16x16x32_bf16 v[104:107], v[232:235], v[80:83], v[104:107]
	ds_read_b64_tr_b16 v[232:233], v3 offset:224
	ds_read_b64_tr_b16 v[234:235], v3 offset:8672
	s_waitcnt lgkmcnt(14)
	v_mfma_f32_16x16x32_bf16 v[128:131], v[236:239], v[76:79], v[104:107]
	ds_read_b64_tr_b16 v[236:237], v3 offset:17120
	ds_read_b64_tr_b16 v[238:239], v3 offset:25568
	s_nop 5
	s_waitcnt lgkmcnt(14)
	v_mfma_f32_16x16x32_bf16 v[104:107], v[240:243], v[80:83], v[148:151]
	ds_read_b64_tr_b16 v[240:241], v3 offset:256
	ds_read_b64_tr_b16 v[242:243], v3 offset:8704
	s_waitcnt lgkmcnt(14)
	v_mfma_f32_16x16x32_bf16 v[104:107], v[204:207], v[76:79], v[104:107]
	ds_read_b64_tr_b16 v[204:205], v3 offset:17152
	ds_read_b64_tr_b16 v[206:207], v3 offset:25600
	s_nop 0
	s_waitcnt lgkmcnt(14)
	v_mfma_f32_16x16x32_bf16 v[120:123], v[208:211], v[80:83], v[120:123]
	ds_read_b64_tr_b16 v[208:209], v3 offset:288
	ds_read_b64_tr_b16 v[210:211], v3 offset:8736
	s_waitcnt lgkmcnt(14)
	v_mfma_f32_16x16x32_bf16 v[120:123], v[218:221], v[76:79], v[120:123]
	ds_read_b64_tr_b16 v[218:219], v3 offset:17184
	ds_read_b64_tr_b16 v[220:221], v3 offset:25632
	s_waitcnt lgkmcnt(14)
	v_mfma_f32_16x16x32_bf16 v[124:127], v[224:227], v[80:83], v[124:127]
	ds_read_b64_tr_b16 v[224:225], v3 offset:320
	ds_read_b64_tr_b16 v[226:227], v3 offset:8768
	s_waitcnt lgkmcnt(14)
	v_mfma_f32_16x16x32_bf16 v[124:127], v[228:231], v[76:79], v[124:127]
	ds_read_b64_tr_b16 v[228:229], v3 offset:17216
	ds_read_b64_tr_b16 v[230:231], v3 offset:25664
	s_waitcnt lgkmcnt(14)
	v_mfma_f32_16x16x32_bf16 v[108:111], v[232:235], v[80:83], v[108:111]
	ds_read_b64_tr_b16 v[232:233], v3 offset:352
	ds_read_b64_tr_b16 v[234:235], v3 offset:8800
	s_waitcnt lgkmcnt(14)
	v_mfma_f32_16x16x32_bf16 v[108:111], v[236:239], v[76:79], v[108:111]
	ds_read_b64_tr_b16 v[236:237], v3 offset:17248
	ds_read_b64_tr_b16 v[238:239], v3 offset:25696
	s_waitcnt lgkmcnt(14)
	v_mfma_f32_16x16x32_bf16 v[100:103], v[240:243], v[80:83], v[100:103]
	ds_read_b64_tr_b16 v[240:241], v3 offset:384
	ds_read_b64_tr_b16 v[242:243], v3 offset:8832
	s_waitcnt lgkmcnt(14)
	v_mfma_f32_16x16x32_bf16 v[100:103], v[204:207], v[76:79], v[100:103]
	ds_read_b64_tr_b16 v[204:205], v3 offset:17280
	ds_read_b64_tr_b16 v[206:207], v3 offset:25728
	s_waitcnt lgkmcnt(14)
	v_mfma_f32_16x16x32_bf16 v[112:115], v[208:211], v[80:83], v[112:115]
	ds_read_b64_tr_b16 v[208:209], v3 offset:416
	ds_read_b64_tr_b16 v[210:211], v3 offset:8864
	s_waitcnt lgkmcnt(14)
	v_mfma_f32_16x16x32_bf16 v[112:115], v[218:221], v[76:79], v[112:115]
	ds_read_b64_tr_b16 v[218:219], v3 offset:17312
	ds_read_b64_tr_b16 v[220:221], v3 offset:25760
	s_waitcnt lgkmcnt(14)
	v_mfma_f32_16x16x32_bf16 v[116:119], v[224:227], v[80:83], v[116:119]
	ds_read_b64_tr_b16 v[224:225], v3 offset:448
	ds_read_b64_tr_b16 v[226:227], v3 offset:8896
	s_waitcnt lgkmcnt(14)
	v_mfma_f32_16x16x32_bf16 v[116:119], v[228:231], v[76:79], v[116:119]
	ds_read_b64_tr_b16 v[228:229], v3 offset:17344
	ds_read_b64_tr_b16 v[230:231], v3 offset:25792
	s_waitcnt lgkmcnt(14)
	v_mfma_f32_16x16x32_bf16 v[132:135], v[232:235], v[80:83], v[132:135]
	ds_read_b64_tr_b16 v[232:233], v3 offset:16896
	ds_read_b64_tr_b16 v[234:235], v3 offset:25344
	s_waitcnt lgkmcnt(14)
	v_mfma_f32_16x16x32_bf16 v[132:135], v[236:239], v[76:79], v[132:135]
	s_waitcnt lgkmcnt(12)
	v_mfma_f32_16x16x32_bf16 v[136:139], v[240:243], v[80:83], v[136:139]
	s_waitcnt lgkmcnt(10)
	v_mfma_f32_16x16x32_bf16 v[136:139], v[204:207], v[76:79], v[136:139]
	s_waitcnt lgkmcnt(8)
	v_mfma_f32_16x16x32_bf16 v[140:143], v[208:211], v[80:83], v[140:143]
	s_waitcnt lgkmcnt(6)
	v_mfma_f32_16x16x32_bf16 v[140:143], v[218:221], v[76:79], v[140:143]
	s_waitcnt lgkmcnt(4)
	v_mfma_f32_16x16x32_bf16 v[144:147], v[224:227], v[80:83], v[144:147]
	s_waitcnt lgkmcnt(2)
	v_mfma_f32_16x16x32_bf16 v[144:147], v[228:231], v[76:79], v[144:147]
	ds_read_b64_tr_b16 v[152:153], v3 offset:480
	ds_read_b64_tr_b16 v[154:155], v3 offset:8928
	ds_read_b64_tr_b16 v[148:149], v3 offset:17376
	ds_read_b64_tr_b16 v[150:151], v3 offset:25824
	s_waitcnt vmcnt(7)
	ds_write_b128 v170, v[60:63]
	s_waitcnt vmcnt(6)
	ds_write_b128 v170, v[64:67] offset:128
	s_waitcnt vmcnt(5)
	ds_write_b128 v170, v[68:71] offset:256
	s_waitcnt vmcnt(4)
	ds_write_b128 v170, v[72:75] offset:384
	s_waitcnt lgkmcnt(0)
	s_waitcnt lgkmcnt(8)
	v_mfma_f32_16x16x32_bf16 v[84:87], v[232:235], v[76:79], v[84:87]
	s_nop 7
	s_barrier
	ds_read_b64_tr_b16 v[204:205], v169
	ds_read_b64_tr_b16 v[206:207], v169 offset:8448
	ds_read_b64_tr_b16 v[208:209], v169 offset:16896
	ds_read_b64_tr_b16 v[210:211], v169 offset:25344
	ds_read_b64_tr_b16 v[218:219], v169 offset:32
	ds_read_b64_tr_b16 v[220:221], v169 offset:8480
	ds_read_b64_tr_b16 v[224:225], v169 offset:16928
	ds_read_b64_tr_b16 v[226:227], v169 offset:25376
	ds_read_b64_tr_b16 v[228:229], v169 offset:64
	ds_read_b64_tr_b16 v[230:231], v169 offset:8512
	ds_read_b64_tr_b16 v[232:233], v169 offset:16960
	ds_read_b64_tr_b16 v[234:235], v169 offset:25408
	ds_read_b64_tr_b16 v[236:237], v169 offset:96
	ds_read_b64_tr_b16 v[238:239], v169 offset:8544
	ds_read_b64_tr_b16 v[240:241], v169 offset:16992
	ds_read_b64_tr_b16 v[242:243], v169 offset:25440
	s_waitcnt lgkmcnt(14)
	v_mfma_f32_16x16x32_bf16 v[60:63], v[204:207], v[40:43], v[84:87]
	ds_read_b64_tr_b16 v[204:205], v169 offset:128
	ds_read_b64_tr_b16 v[206:207], v169 offset:8576
	s_waitcnt lgkmcnt(14)
	v_mfma_f32_16x16x32_bf16 v[60:63], v[208:211], v[36:39], v[60:63]
	ds_read_b64_tr_b16 v[208:209], v169 offset:17024
	ds_read_b64_tr_b16 v[210:211], v169 offset:25472
	s_waitcnt lgkmcnt(14)
	v_mfma_f32_16x16x32_bf16 v[64:67], v[218:221], v[40:43], v[92:95]
	ds_read_b64_tr_b16 v[218:219], v169 offset:160
	ds_read_b64_tr_b16 v[220:221], v169 offset:8608
	s_waitcnt lgkmcnt(14)
	v_mfma_f32_16x16x32_bf16 v[64:67], v[224:227], v[36:39], v[64:67]
	ds_read_b64_tr_b16 v[224:225], v169 offset:17056
	ds_read_b64_tr_b16 v[226:227], v169 offset:25504
	v_mfma_f32_16x16x32_bf16 v[80:83], v[152:155], v[80:83], v[96:99]
	v_mov_b32_e32 v155, 0xa00000
	s_nop 1
	s_waitcnt lgkmcnt(14)
	v_mfma_f32_16x16x32_bf16 v[68:71], v[228:231], v[40:43], v[88:91]
	ds_read_b64_tr_b16 v[228:229], v169 offset:192
	ds_read_b64_tr_b16 v[230:231], v169 offset:8640
	v_mfma_f32_16x16x32_bf16 v[76:79], v[148:151], v[76:79], v[80:83]
	s_waitcnt lgkmcnt(14)
	v_mfma_f32_16x16x32_bf16 v[68:71], v[232:235], v[36:39], v[68:71]
	ds_read_b64_tr_b16 v[232:233], v169 offset:17088
	ds_read_b64_tr_b16 v[234:235], v169 offset:25536
	s_waitcnt lgkmcnt(14)
	v_mfma_f32_16x16x32_bf16 v[72:75], v[236:239], v[40:43], v[128:131]
	ds_read_b64_tr_b16 v[236:237], v169 offset:224
	ds_read_b64_tr_b16 v[238:239], v169 offset:8672
	s_waitcnt lgkmcnt(14)
	v_mfma_f32_16x16x32_bf16 v[128:131], v[240:243], v[36:39], v[72:75]
	ds_read_b64_tr_b16 v[240:241], v169 offset:17120
	ds_read_b64_tr_b16 v[242:243], v169 offset:25568
	s_nop 5
	s_waitcnt lgkmcnt(14)
	v_mfma_f32_16x16x32_bf16 v[72:75], v[204:207], v[40:43], v[104:107]
	ds_read_b64_tr_b16 v[204:205], v169 offset:256
	ds_read_b64_tr_b16 v[206:207], v169 offset:8704
	s_waitcnt lgkmcnt(14)
	v_mfma_f32_16x16x32_bf16 v[72:75], v[208:211], v[36:39], v[72:75]
	ds_read_b64_tr_b16 v[208:209], v169 offset:17152
	ds_read_b64_tr_b16 v[210:211], v169 offset:25600
	s_waitcnt lgkmcnt(14)
	v_mfma_f32_16x16x32_bf16 v[80:83], v[218:221], v[40:43], v[120:123]
	ds_read_b64_tr_b16 v[218:219], v169 offset:288
	ds_read_b64_tr_b16 v[220:221], v169 offset:8736
	s_waitcnt lgkmcnt(14)
	v_mfma_f32_16x16x32_bf16 v[80:83], v[224:227], v[36:39], v[80:83]
	ds_read_b64_tr_b16 v[224:225], v169 offset:17184
	ds_read_b64_tr_b16 v[226:227], v169 offset:25632
	s_waitcnt lgkmcnt(14)
	v_mfma_f32_16x16x32_bf16 v[84:87], v[228:231], v[40:43], v[124:127]
	ds_read_b64_tr_b16 v[228:229], v169 offset:320
	ds_read_b64_tr_b16 v[230:231], v169 offset:8768
	s_waitcnt lgkmcnt(14)
	v_mfma_f32_16x16x32_bf16 v[84:87], v[232:235], v[36:39], v[84:87]
	ds_read_b64_tr_b16 v[232:233], v169 offset:17216
	ds_read_b64_tr_b16 v[234:235], v169 offset:25664
	s_waitcnt lgkmcnt(14)
	v_mfma_f32_16x16x32_bf16 v[88:91], v[236:239], v[40:43], v[108:111]
	ds_read_b64_tr_b16 v[236:237], v169 offset:352
	ds_read_b64_tr_b16 v[238:239], v169 offset:8800
	s_waitcnt lgkmcnt(14)
	v_mfma_f32_16x16x32_bf16 v[120:123], v[240:243], v[36:39], v[88:91]
	ds_read_b64_tr_b16 v[240:241], v169 offset:17248
	ds_read_b64_tr_b16 v[242:243], v169 offset:25696
	s_nop 5
	s_waitcnt lgkmcnt(14)
	v_mfma_f32_16x16x32_bf16 v[88:91], v[204:207], v[40:43], v[100:103]
	ds_read_b64_tr_b16 v[204:205], v169 offset:384
	ds_read_b64_tr_b16 v[206:207], v169 offset:8832
	s_waitcnt lgkmcnt(14)
	v_mfma_f32_16x16x32_bf16 v[88:91], v[208:211], v[36:39], v[88:91]
	ds_read_b64_tr_b16 v[208:209], v169 offset:17280
	ds_read_b64_tr_b16 v[210:211], v169 offset:25728
	s_waitcnt lgkmcnt(14)
	v_mfma_f32_16x16x32_bf16 v[92:95], v[218:221], v[40:43], v[112:115]
	ds_read_b64_tr_b16 v[218:219], v169 offset:416
	ds_read_b64_tr_b16 v[220:221], v169 offset:8864
	s_waitcnt lgkmcnt(14)
	v_mfma_f32_16x16x32_bf16 v[92:95], v[224:227], v[36:39], v[92:95]
	ds_read_b64_tr_b16 v[224:225], v169 offset:17312
	ds_read_b64_tr_b16 v[226:227], v169 offset:25760
	s_waitcnt lgkmcnt(14)
	v_mfma_f32_16x16x32_bf16 v[96:99], v[228:231], v[40:43], v[116:119]
	ds_read_b64_tr_b16 v[228:229], v169 offset:448
	ds_read_b64_tr_b16 v[230:231], v169 offset:8896
	s_waitcnt lgkmcnt(14)
	v_mfma_f32_16x16x32_bf16 v[96:99], v[232:235], v[36:39], v[96:99]
	ds_read_b64_tr_b16 v[232:233], v169 offset:17344
	ds_read_b64_tr_b16 v[234:235], v169 offset:25792
	s_waitcnt lgkmcnt(14)
	v_mfma_f32_16x16x32_bf16 v[100:103], v[236:239], v[40:43], v[132:135]
	ds_read_b64_tr_b16 v[236:237], v169 offset:480
	ds_read_b64_tr_b16 v[238:239], v169 offset:8928
	s_waitcnt lgkmcnt(14)
	v_mfma_f32_16x16x32_bf16 v[112:115], v[240:243], v[36:39], v[100:103]
	s_nop 5
	s_waitcnt lgkmcnt(12)
	v_mfma_f32_16x16x32_bf16 v[100:103], v[204:207], v[40:43], v[136:139]
	s_waitcnt lgkmcnt(10)
	v_mfma_f32_16x16x32_bf16 v[100:103], v[208:211], v[36:39], v[100:103]
	v_add_u32_e32 v136, s14, v1
	v_add_f32_e32 v1, v156, v157
	s_nop 1
	s_waitcnt lgkmcnt(8)
	v_mfma_f32_16x16x32_bf16 v[104:107], v[218:221], v[40:43], v[140:143]
	v_ashrrev_i32_e32 v137, 31, v136
	s_nop 1
	s_waitcnt lgkmcnt(6)
	v_mfma_f32_16x16x32_bf16 v[104:107], v[224:227], v[36:39], v[104:107]
	s_waitcnt lgkmcnt(4)
	v_mfma_f32_16x16x32_bf16 v[108:111], v[228:231], v[40:43], v[144:147]
	s_waitcnt lgkmcnt(2)
	v_mfma_f32_16x16x32_bf16 v[108:111], v[232:235], v[36:39], v[108:111]
	ds_read_b64_tr_b16 v[124:125], v169 offset:17376
	ds_read_b64_tr_b16 v[126:127], v169 offset:25824
	s_waitcnt vmcnt(3)
	ds_write_b128 v168, v[44:47]
	s_waitcnt vmcnt(2)
	ds_write_b128 v168, v[48:51] offset:128
	s_waitcnt vmcnt(1)
	ds_write_b128 v168, v[52:55] offset:256
	s_waitcnt vmcnt(0)
	ds_write_b128 v168, v[56:59] offset:384
	s_waitcnt lgkmcnt(0)
	s_waitcnt lgkmcnt(6)
	v_mfma_f32_16x16x32_bf16 v[40:43], v[236:239], v[40:43], v[76:79]
	s_nop 7
	s_barrier
	v_cvt_pk_bf16_f32 v52, v177, v178
	s_waitcnt lgkmcnt(4)
	v_mfma_f32_16x16x32_bf16 v[36:39], v[124:127], v[36:39], v[40:43]
	s_nop 3
	ds_read_b64_tr_b16 v[204:205], v3
	ds_read_b64_tr_b16 v[206:207], v3 offset:8448
	ds_read_b64_tr_b16 v[208:209], v3 offset:16896
	ds_read_b64_tr_b16 v[210:211], v3 offset:25344
	ds_read_b64_tr_b16 v[218:219], v3 offset:32
	ds_read_b64_tr_b16 v[220:221], v3 offset:8480
	ds_read_b64_tr_b16 v[224:225], v3 offset:16928
	ds_read_b64_tr_b16 v[226:227], v3 offset:25376
	ds_read_b64_tr_b16 v[228:229], v3 offset:64
	ds_read_b64_tr_b16 v[230:231], v3 offset:8512
	ds_read_b64_tr_b16 v[232:233], v3 offset:16960
	ds_read_b64_tr_b16 v[234:235], v3 offset:25408
	ds_read_b64_tr_b16 v[236:237], v3 offset:96
	ds_read_b64_tr_b16 v[238:239], v3 offset:8544
	ds_read_b64_tr_b16 v[240:241], v3 offset:16992
	ds_read_b64_tr_b16 v[242:243], v3 offset:25440
	v_cvt_pk_bf16_f32 v53, v179, v180
	v_cvt_pk_bf16_f32 v54, v187, v190
	v_cvt_pk_bf16_f32 v55, v191, v192
	v_cvt_pk_bf16_f32 v48, v193, v194
	v_cvt_pk_bf16_f32 v49, v158, v159
	s_nop 1
	s_waitcnt lgkmcnt(14)
	v_mfma_f32_16x16x32_bf16 v[40:43], v[204:207], v[52:55], v[60:63]
	ds_read_b64_tr_b16 v[204:205], v3 offset:128
	ds_read_b64_tr_b16 v[206:207], v3 offset:8576
	v_cvt_pk_bf16_f32 v50, v195, v196
	v_cvt_pk_bf16_f32 v51, v197, v198
	s_nop 0
	s_waitcnt lgkmcnt(14)
	v_mfma_f32_16x16x32_bf16 v[44:47], v[208:211], v[48:51], v[40:43]
	ds_read_b64_tr_b16 v[208:209], v3 offset:17024
	ds_read_b64_tr_b16 v[210:211], v3 offset:25472
	s_nop 1
	s_waitcnt lgkmcnt(14)
	v_mfma_f32_16x16x32_bf16 v[56:59], v[218:221], v[52:55], v[64:67]
	ds_read_b64_tr_b16 v[218:219], v3 offset:160
	ds_read_b64_tr_b16 v[220:221], v3 offset:8608
	s_waitcnt lgkmcnt(14)
	v_mfma_f32_16x16x32_bf16 v[40:43], v[224:227], v[48:51], v[56:59]
	ds_read_b64_tr_b16 v[224:225], v3 offset:17056
	ds_read_b64_tr_b16 v[226:227], v3 offset:25504
	s_nop 5
	s_waitcnt lgkmcnt(14)
	v_mfma_f32_16x16x32_bf16 v[56:59], v[228:231], v[52:55], v[68:71]
	ds_read_b64_tr_b16 v[228:229], v3 offset:192
	ds_read_b64_tr_b16 v[230:231], v3 offset:8640
	s_waitcnt lgkmcnt(14)
	v_mfma_f32_16x16x32_bf16 v[56:59], v[232:235], v[48:51], v[56:59]
	ds_read_b64_tr_b16 v[232:233], v3 offset:17088
	ds_read_b64_tr_b16 v[234:235], v3 offset:25536
	s_waitcnt lgkmcnt(14)
	v_mfma_f32_16x16x32_bf16 v[60:63], v[236:239], v[52:55], v[128:131]
	ds_read_b64_tr_b16 v[236:237], v3 offset:224
	ds_read_b64_tr_b16 v[238:239], v3 offset:8672
	s_waitcnt lgkmcnt(14)
	v_mfma_f32_16x16x32_bf16 v[60:63], v[240:243], v[48:51], v[60:63]
	ds_read_b64_tr_b16 v[240:241], v3 offset:17120
	ds_read_b64_tr_b16 v[242:243], v3 offset:25568
	s_waitcnt lgkmcnt(14)
	v_mfma_f32_16x16x32_bf16 v[64:67], v[204:207], v[52:55], v[72:75]
	ds_read_b64_tr_b16 v[204:205], v3 offset:256
	ds_read_b64_tr_b16 v[206:207], v3 offset:8704
	s_waitcnt lgkmcnt(14)
	v_mfma_f32_16x16x32_bf16 v[64:67], v[208:211], v[48:51], v[64:67]
	ds_read_b64_tr_b16 v[208:209], v3 offset:17152
	ds_read_b64_tr_b16 v[210:211], v3 offset:25600
	s_waitcnt lgkmcnt(14)
	v_mfma_f32_16x16x32_bf16 v[68:71], v[218:221], v[52:55], v[80:83]
	ds_read_b64_tr_b16 v[218:219], v3 offset:288
	ds_read_b64_tr_b16 v[220:221], v3 offset:8736
	s_waitcnt lgkmcnt(14)
	v_mfma_f32_16x16x32_bf16 v[68:71], v[224:227], v[48:51], v[68:71]
	ds_read_b64_tr_b16 v[224:225], v3 offset:17184
	ds_read_b64_tr_b16 v[226:227], v3 offset:25632
	s_waitcnt lgkmcnt(14)
	v_mfma_f32_16x16x32_bf16 v[72:75], v[228:231], v[52:55], v[84:87]
	ds_read_b64_tr_b16 v[228:229], v3 offset:320
	ds_read_b64_tr_b16 v[230:231], v3 offset:8768
	s_waitcnt lgkmcnt(14)
	v_mfma_f32_16x16x32_bf16 v[72:75], v[232:235], v[48:51], v[72:75]
	ds_read_b64_tr_b16 v[232:233], v3 offset:17216
	ds_read_b64_tr_b16 v[234:235], v3 offset:25664
	s_waitcnt lgkmcnt(14)
	v_mfma_f32_16x16x32_bf16 v[76:79], v[236:239], v[52:55], v[120:123]
	ds_read_b64_tr_b16 v[236:237], v3 offset:352
	ds_read_b64_tr_b16 v[238:239], v3 offset:8800
	s_waitcnt lgkmcnt(14)
	v_mfma_f32_16x16x32_bf16 v[76:79], v[240:243], v[48:51], v[76:79]
	ds_read_b64_tr_b16 v[240:241], v3 offset:17248
	ds_read_b64_tr_b16 v[242:243], v3 offset:25696
	s_waitcnt lgkmcnt(14)
	v_mfma_f32_16x16x32_bf16 v[80:83], v[204:207], v[52:55], v[88:91]
	ds_read_b64_tr_b16 v[204:205], v3 offset:384
	ds_read_b64_tr_b16 v[206:207], v3 offset:8832
	s_waitcnt lgkmcnt(14)
	v_mfma_f32_16x16x32_bf16 v[80:83], v[208:211], v[48:51], v[80:83]
	ds_read_b64_tr_b16 v[208:209], v3 offset:17280
	ds_read_b64_tr_b16 v[210:211], v3 offset:25728
	s_waitcnt lgkmcnt(14)
	v_mfma_f32_16x16x32_bf16 v[84:87], v[218:221], v[52:55], v[92:95]
	ds_read_b64_tr_b16 v[218:219], v3 offset:416
	ds_read_b64_tr_b16 v[220:221], v3 offset:8864
	s_waitcnt lgkmcnt(14)
	v_mfma_f32_16x16x32_bf16 v[84:87], v[224:227], v[48:51], v[84:87]
	ds_read_b64_tr_b16 v[224:225], v3 offset:17312
	ds_read_b64_tr_b16 v[226:227], v3 offset:25760
	s_waitcnt lgkmcnt(14)
	v_mfma_f32_16x16x32_bf16 v[88:91], v[228:231], v[52:55], v[96:99]
	ds_read_b64_tr_b16 v[228:229], v3 offset:448
	ds_read_b64_tr_b16 v[230:231], v3 offset:8896
	s_waitcnt lgkmcnt(14)
	v_mfma_f32_16x16x32_bf16 v[88:91], v[232:235], v[48:51], v[88:91]
	ds_read_b64_tr_b16 v[232:233], v3 offset:17344
	ds_read_b64_tr_b16 v[234:235], v3 offset:25792
	s_waitcnt lgkmcnt(14)
	v_mfma_f32_16x16x32_bf16 v[92:95], v[236:239], v[52:55], v[112:115]
	ds_read_b64_tr_b16 v[236:237], v3 offset:480
	ds_read_b64_tr_b16 v[238:239], v3 offset:8928
	s_waitcnt lgkmcnt(14)
	v_mfma_f32_16x16x32_bf16 v[92:95], v[240:243], v[48:51], v[92:95]
	ds_read_b64_tr_b16 v[240:241], v3 offset:17376
	ds_read_b64_tr_b16 v[242:243], v3 offset:25824
	s_waitcnt lgkmcnt(14)
	v_mfma_f32_16x16x32_bf16 v[96:99], v[204:207], v[52:55], v[100:103]
	s_waitcnt lgkmcnt(12)
	v_mfma_f32_16x16x32_bf16 v[96:99], v[208:211], v[48:51], v[96:99]
	s_nop 0
	s_waitcnt lgkmcnt(10)
	v_mfma_f32_16x16x32_bf16 v[100:103], v[218:221], v[52:55], v[104:107]
	s_waitcnt lgkmcnt(8)
	v_mfma_f32_16x16x32_bf16 v[100:103], v[224:227], v[48:51], v[100:103]
	s_nop 0
	s_waitcnt lgkmcnt(6)
	v_mfma_f32_16x16x32_bf16 v[104:107], v[228:231], v[52:55], v[108:111]
	s_waitcnt lgkmcnt(4)
	v_mfma_f32_16x16x32_bf16 v[104:107], v[232:235], v[48:51], v[104:107]
	s_nop 0
	s_waitcnt lgkmcnt(2)
	v_mfma_f32_16x16x32_bf16 v[36:39], v[236:239], v[52:55], v[36:39]
	s_waitcnt lgkmcnt(0)
	v_mfma_f32_16x16x32_bf16 v[36:39], v[240:243], v[48:51], v[36:39]
	s_nop 7
	v_div_scale_f32 v48, s[12:13], v1, v1, 1.0
	v_rcp_f32_e32 v49, v48
	v_readlane_b32 s12, v253, 35
	v_readlane_b32 s13, v253, 36
	s_add_u32 s10, s12, s10
	v_fma_f32 v50, -v48, v49, 1.0
	v_fmac_f32_e32 v49, v50, v49
	v_div_scale_f32 v50, vcc, 1.0, v1, 1.0
	v_mul_f32_e32 v51, v50, v49
	v_fma_f32 v52, -v48, v51, v50
	v_fmac_f32_e32 v51, v52, v49
	v_fma_f32 v48, -v48, v51, v50
	v_div_fmas_f32 v48, v48, v49, v51
	s_addc_u32 s11, s13, s11
	v_lshlrev_b64 v[50:51], 11, v[136:137]
	v_lshl_add_u64 v[50:51], s[10:11], 0, v[50:51]
	v_div_fixup_f32 v48, v48, v1, 1.0
	v_mad_i64_i32 v[50:51], s[12:13], s6, v155, v[50:51]
	v_lshl_add_u64 v[50:51], v[50:51], 0, s[8:9]
	v_mov_b32_e32 v1, v181
	v_pk_mul_f32 v[40:41], v[48:49], v[40:41] op_sel_hi:[0,1]
	v_pk_mul_f32 v[42:43], v[48:49], v[42:43] op_sel_hi:[0,1]
	v_lshl_add_u64 v[50:51], v[50:51], 0, v[0:1]
	v_cvt_pk_bf16_f32 v40, v40, v41
	v_cvt_pk_bf16_f32 v41, v42, v43
	global_store_dwordx2 v[50:51], v[40:41], off offset:32
	v_pk_mul_f32 v[40:41], v[48:49], v[56:57] op_sel_hi:[0,1]
	v_pk_mul_f32 v[42:43], v[48:49], v[58:59] op_sel_hi:[0,1]
	v_cvt_pk_bf16_f32 v40, v40, v41
	v_cvt_pk_bf16_f32 v41, v42, v43
	global_store_dwordx2 v[50:51], v[40:41], off offset:64
	v_pk_mul_f32 v[40:41], v[48:49], v[60:61] op_sel_hi:[0,1]
	v_pk_mul_f32 v[42:43], v[48:49], v[62:63] op_sel_hi:[0,1]
	v_cvt_pk_bf16_f32 v40, v40, v41
	v_cvt_pk_bf16_f32 v41, v42, v43
	global_store_dwordx2 v[50:51], v[40:41], off offset:96
	v_pk_mul_f32 v[40:41], v[48:49], v[64:65] op_sel_hi:[0,1]
	v_pk_mul_f32 v[42:43], v[48:49], v[66:67] op_sel_hi:[0,1]
	v_cvt_pk_bf16_f32 v40, v40, v41
	v_cvt_pk_bf16_f32 v41, v42, v43
	global_store_dwordx2 v[50:51], v[40:41], off offset:128
	v_pk_mul_f32 v[40:41], v[48:49], v[68:69] op_sel_hi:[0,1]
	v_pk_mul_f32 v[42:43], v[48:49], v[70:71] op_sel_hi:[0,1]
	v_cvt_pk_bf16_f32 v40, v40, v41
	v_cvt_pk_bf16_f32 v41, v42, v43
	global_store_dwordx2 v[50:51], v[40:41], off offset:160
	v_pk_mul_f32 v[40:41], v[48:49], v[72:73] op_sel_hi:[0,1]
	v_pk_mul_f32 v[42:43], v[48:49], v[74:75] op_sel_hi:[0,1]
	v_cvt_pk_bf16_f32 v40, v40, v41
	v_cvt_pk_bf16_f32 v41, v42, v43
	global_store_dwordx2 v[50:51], v[40:41], off offset:192
	v_pk_mul_f32 v[40:41], v[48:49], v[76:77] op_sel_hi:[0,1]
	v_pk_mul_f32 v[42:43], v[48:49], v[78:79] op_sel_hi:[0,1]
	v_cvt_pk_bf16_f32 v40, v40, v41
	v_cvt_pk_bf16_f32 v41, v42, v43
	global_store_dwordx2 v[50:51], v[40:41], off offset:224
	v_pk_mul_f32 v[40:41], v[48:49], v[80:81] op_sel_hi:[0,1]
	v_pk_mul_f32 v[42:43], v[48:49], v[82:83] op_sel_hi:[0,1]
	v_cvt_pk_bf16_f32 v40, v40, v41
	v_cvt_pk_bf16_f32 v41, v42, v43
	global_store_dwordx2 v[50:51], v[40:41], off offset:256
	v_pk_mul_f32 v[40:41], v[48:49], v[84:85] op_sel_hi:[0,1]
	v_pk_mul_f32 v[42:43], v[48:49], v[86:87] op_sel_hi:[0,1]
	v_cvt_pk_bf16_f32 v40, v40, v41
	v_cvt_pk_bf16_f32 v41, v42, v43
	global_store_dwordx2 v[50:51], v[40:41], off offset:288
	v_pk_mul_f32 v[40:41], v[48:49], v[88:89] op_sel_hi:[0,1]
	v_pk_mul_f32 v[42:43], v[48:49], v[90:91] op_sel_hi:[0,1]
	v_cvt_pk_bf16_f32 v40, v40, v41
	v_cvt_pk_bf16_f32 v41, v42, v43
	global_store_dwordx2 v[50:51], v[40:41], off offset:320
	v_pk_mul_f32 v[40:41], v[48:49], v[92:93] op_sel_hi:[0,1]
	v_pk_mul_f32 v[42:43], v[48:49], v[94:95] op_sel_hi:[0,1]
	v_cvt_pk_bf16_f32 v40, v40, v41
	v_cvt_pk_bf16_f32 v41, v42, v43
	global_store_dwordx2 v[50:51], v[40:41], off offset:352
	v_pk_mul_f32 v[40:41], v[48:49], v[96:97] op_sel_hi:[0,1]
	v_pk_mul_f32 v[42:43], v[48:49], v[98:99] op_sel_hi:[0,1]
	v_cvt_pk_bf16_f32 v40, v40, v41
	v_cvt_pk_bf16_f32 v41, v42, v43
	global_store_dwordx2 v[50:51], v[40:41], off offset:384
	v_pk_mul_f32 v[40:41], v[48:49], v[100:101] op_sel_hi:[0,1]
	v_pk_mul_f32 v[42:43], v[48:49], v[102:103] op_sel_hi:[0,1]
	v_cvt_pk_bf16_f32 v40, v40, v41
	v_cvt_pk_bf16_f32 v41, v42, v43
	v_pk_mul_f32 v[44:45], v[48:49], v[44:45] op_sel_hi:[0,1]
	v_pk_mul_f32 v[46:47], v[48:49], v[46:47] op_sel_hi:[0,1]
	global_store_dwordx2 v[50:51], v[40:41], off offset:416
	v_pk_mul_f32 v[40:41], v[48:49], v[104:105] op_sel_hi:[0,1]
	v_pk_mul_f32 v[42:43], v[48:49], v[106:107] op_sel_hi:[0,1]
	v_pk_mul_f32 v[36:37], v[48:49], v[36:37] op_sel_hi:[0,1]
	v_pk_mul_f32 v[38:39], v[48:49], v[38:39] op_sel_hi:[0,1]
	v_cvt_pk_bf16_f32 v44, v44, v45
	v_cvt_pk_bf16_f32 v45, v46, v47
	v_cvt_pk_bf16_f32 v40, v40, v41
	v_cvt_pk_bf16_f32 v41, v42, v43
	v_cvt_pk_bf16_f32 v36, v36, v37
	v_cvt_pk_bf16_f32 v37, v38, v39
	global_store_dwordx2 v[50:51], v[44:45], off
	global_store_dwordx2 v[50:51], v[40:41], off offset:448
	global_store_dwordx2 v[50:51], v[36:37], off offset:480
	s_waitcnt lgkmcnt(0)
	s_barrier
	s_waitcnt lgkmcnt(0)
	s_barrier
	ds_write_b128 v176, v[4:7]
	ds_write_b128 v176, v[8:11] offset:256
	ds_write_b128 v176, v[12:15] offset:8448
	ds_write_b128 v176, v[16:19] offset:8704
	ds_write_b128 v176, v[20:23] offset:16896
	ds_write_b128 v176, v[24:27] offset:17152
	ds_write_b128 v176, v[28:31] offset:25344
	ds_write_b128 v176, v[32:35] offset:25600
	s_waitcnt lgkmcnt(0)
	s_barrier
	ds_read_b128 v[64:67], v175
	ds_read_b128 v[60:63], v175 offset:64
	ds_read_b128 v[56:59], v175 offset:128
	ds_read_b128 v[52:55], v175 offset:192
	ds_read_b128 v[48:51], v175 offset:256
	ds_read_b128 v[44:47], v175 offset:320
	ds_read_b128 v[8:11], v175 offset:384
	ds_read_b128 v[4:7], v175 offset:448
	global_load_dwordx4 v[28:31], v[166:167], off
	global_load_dwordx4 v[12:15], v[164:165], off
	global_load_dwordx4 v[32:35], v[166:167], off offset:128
	global_load_dwordx4 v[16:19], v[164:165], off offset:128
	global_load_dwordx4 v[36:39], v[166:167], off offset:256
	global_load_dwordx4 v[20:23], v[164:165], off offset:256
	global_load_dwordx4 v[40:43], v[166:167], off offset:384
	global_load_dwordx4 v[24:27], v[164:165], off offset:384
	s_waitcnt vmcnt(7)
	ds_write_b128 v170, v[28:31]
	s_waitcnt vmcnt(5)
	ds_write_b128 v170, v[32:35] offset:128
	s_waitcnt vmcnt(3)
	ds_write_b128 v170, v[36:39] offset:256
	s_waitcnt vmcnt(1)
	ds_write_b128 v170, v[40:43] offset:384
	global_load_dwordx4 v[28:31], v[162:163], off
	global_load_dwordx4 v[32:35], v[162:163], off offset:128
	global_load_dwordx4 v[36:39], v[162:163], off offset:256
	global_load_dwordx4 v[40:43], v[162:163], off offset:384
	s_waitcnt lgkmcnt(0)
	s_barrier
	ds_read_b128 v[204:207], v174
	ds_read_b128 v[208:211], v174 offset:8448
	ds_read_b128 v[218:221], v174 offset:16896
	ds_read_b128 v[224:227], v174 offset:25344
	ds_read_b128 v[228:231], v174 offset:64
	ds_read_b128 v[232:235], v174 offset:8512
	ds_read_b128 v[236:239], v174 offset:16960
	ds_read_b128 v[240:243], v174 offset:25408
	s_waitcnt lgkmcnt(7)
	v_mfma_f32_16x16x32_bf16 v[68:71], v[204:207], v[64:67], 0
	ds_read_b128 v[204:207], v174 offset:128
	s_waitcnt lgkmcnt(7)
	v_mfma_f32_16x16x32_bf16 v[72:75], v[208:211], v[64:67], 0
	ds_read_b128 v[208:211], v174 offset:8576
	s_waitcnt lgkmcnt(7)
	v_mfma_f32_16x16x32_bf16 v[76:79], v[218:221], v[64:67], 0
	ds_read_b128 v[218:221], v174 offset:17024
	s_waitcnt lgkmcnt(7)
	v_mfma_f32_16x16x32_bf16 v[80:83], v[224:227], v[64:67], 0
	ds_read_b128 v[224:227], v174 offset:25472
	s_waitcnt lgkmcnt(7)
	v_mfma_f32_16x16x32_bf16 v[68:71], v[228:231], v[60:63], v[68:71]
	ds_read_b128 v[228:231], v174 offset:192
	s_waitcnt lgkmcnt(7)
	v_mfma_f32_16x16x32_bf16 v[72:75], v[232:235], v[60:63], v[72:75]
	ds_read_b128 v[232:235], v174 offset:8640
	s_waitcnt lgkmcnt(7)
	v_mfma_f32_16x16x32_bf16 v[76:79], v[236:239], v[60:63], v[76:79]
	ds_read_b128 v[236:239], v174 offset:17088
	s_waitcnt lgkmcnt(7)
	v_mfma_f32_16x16x32_bf16 v[80:83], v[240:243], v[60:63], v[80:83]
	ds_read_b128 v[240:243], v174 offset:25536
	s_waitcnt lgkmcnt(7)
	v_mfma_f32_16x16x32_bf16 v[68:71], v[204:207], v[56:59], v[68:71]
	ds_read_b128 v[204:207], v174 offset:256
	s_waitcnt lgkmcnt(7)
	v_mfma_f32_16x16x32_bf16 v[72:75], v[208:211], v[56:59], v[72:75]
	ds_read_b128 v[208:211], v174 offset:8704
	s_waitcnt lgkmcnt(7)
	v_mfma_f32_16x16x32_bf16 v[76:79], v[218:221], v[56:59], v[76:79]
	ds_read_b128 v[218:221], v174 offset:17152
	s_waitcnt lgkmcnt(7)
	v_mfma_f32_16x16x32_bf16 v[80:83], v[224:227], v[56:59], v[80:83]
	ds_read_b128 v[224:227], v174 offset:25600
	s_waitcnt lgkmcnt(7)
	v_mfma_f32_16x16x32_bf16 v[68:71], v[228:231], v[52:55], v[68:71]
	ds_read_b128 v[228:231], v174 offset:320
	s_waitcnt lgkmcnt(7)
	v_mfma_f32_16x16x32_bf16 v[72:75], v[232:235], v[52:55], v[72:75]
	ds_read_b128 v[232:235], v174 offset:8768
	s_waitcnt lgkmcnt(7)
	v_mfma_f32_16x16x32_bf16 v[76:79], v[236:239], v[52:55], v[76:79]
	ds_read_b128 v[236:239], v174 offset:17216
	s_waitcnt lgkmcnt(7)
	v_mfma_f32_16x16x32_bf16 v[80:83], v[240:243], v[52:55], v[80:83]
	ds_read_b128 v[240:243], v174 offset:25664
	s_waitcnt lgkmcnt(7)
	v_mfma_f32_16x16x32_bf16 v[68:71], v[204:207], v[48:51], v[68:71]
	ds_read_b128 v[204:207], v174 offset:384
	s_waitcnt lgkmcnt(7)
	v_mfma_f32_16x16x32_bf16 v[72:75], v[208:211], v[48:51], v[72:75]
	ds_read_b128 v[208:211], v174 offset:8832
	s_waitcnt lgkmcnt(7)
	v_mfma_f32_16x16x32_bf16 v[76:79], v[218:221], v[48:51], v[76:79]
	ds_read_b128 v[218:221], v174 offset:17280
	s_waitcnt lgkmcnt(7)
	v_mfma_f32_16x16x32_bf16 v[80:83], v[224:227], v[48:51], v[80:83]
	ds_read_b128 v[224:227], v174 offset:25728
	s_waitcnt lgkmcnt(7)
	v_mfma_f32_16x16x32_bf16 v[68:71], v[228:231], v[44:47], v[68:71]
	ds_read_b128 v[228:231], v174 offset:448
	s_waitcnt lgkmcnt(7)
	v_mfma_f32_16x16x32_bf16 v[72:75], v[232:235], v[44:47], v[72:75]
	ds_read_b128 v[232:235], v174 offset:8896
	s_waitcnt lgkmcnt(7)
	v_mfma_f32_16x16x32_bf16 v[76:79], v[236:239], v[44:47], v[76:79]
	ds_read_b128 v[236:239], v174 offset:17344
	s_waitcnt lgkmcnt(7)
	v_mfma_f32_16x16x32_bf16 v[80:83], v[240:243], v[44:47], v[80:83]
	s_waitcnt lgkmcnt(6)
	v_mfma_f32_16x16x32_bf16 v[68:71], v[204:207], v[8:11], v[68:71]
	s_waitcnt lgkmcnt(5)
	v_mfma_f32_16x16x32_bf16 v[72:75], v[208:211], v[8:11], v[72:75]
	s_waitcnt lgkmcnt(4)
	v_mfma_f32_16x16x32_bf16 v[76:79], v[218:221], v[8:11], v[76:79]
	s_waitcnt lgkmcnt(3)
	v_mfma_f32_16x16x32_bf16 v[80:83], v[224:227], v[8:11], v[80:83]
	s_waitcnt lgkmcnt(2)
	v_mfma_f32_16x16x32_bf16 v[68:71], v[228:231], v[4:7], v[68:71]
	s_waitcnt lgkmcnt(1)
	v_mfma_f32_16x16x32_bf16 v[72:75], v[232:235], v[4:7], v[72:75]
	s_waitcnt lgkmcnt(0)
	v_mfma_f32_16x16x32_bf16 v[76:79], v[236:239], v[4:7], v[76:79]
	s_nop 7
	ds_read_b128 v[84:87], v174 offset:25792
	ds_write_b128 v168, v[12:15]
	ds_write_b128 v168, v[16:19] offset:128
	ds_write_b128 v168, v[20:23] offset:256
	s_waitcnt vmcnt(4)
	ds_write_b128 v168, v[24:27] offset:384
	global_load_dwordx4 v[12:15], v[160:161], off
	global_load_dwordx4 v[16:19], v[160:161], off offset:128
	global_load_dwordx4 v[20:23], v[160:161], off offset:256
	global_load_dwordx4 v[24:27], v[160:161], off offset:384
	s_waitcnt lgkmcnt(0)
	s_barrier
	s_waitcnt lgkmcnt(4)
	v_mfma_f32_16x16x32_bf16 v[80:83], v[84:87], v[4:7], v[80:83]
	ds_read_b128 v[204:207], v173
	ds_read_b128 v[208:211], v173 offset:8448
	ds_read_b128 v[218:221], v173 offset:16896
	ds_read_b128 v[224:227], v173 offset:25344
	ds_read_b128 v[228:231], v173 offset:64
	ds_read_b128 v[232:235], v173 offset:8512
	ds_read_b128 v[236:239], v173 offset:16960
	ds_read_b128 v[240:243], v173 offset:25408
	s_waitcnt lgkmcnt(7)
	v_mfma_f32_16x16x32_bf16 v[84:87], v[204:207], v[64:67], 0
	ds_read_b128 v[204:207], v173 offset:128
	s_waitcnt lgkmcnt(7)
	v_mfma_f32_16x16x32_bf16 v[88:91], v[208:211], v[64:67], 0
	ds_read_b128 v[208:211], v173 offset:8576
	s_waitcnt lgkmcnt(7)
	v_mfma_f32_16x16x32_bf16 v[92:95], v[218:221], v[64:67], 0
	ds_read_b128 v[218:221], v173 offset:17024
	s_waitcnt lgkmcnt(7)
	v_mfma_f32_16x16x32_bf16 v[96:99], v[224:227], v[64:67], 0
	ds_read_b128 v[224:227], v173 offset:25472
	s_waitcnt lgkmcnt(7)
	v_mfma_f32_16x16x32_bf16 v[84:87], v[228:231], v[60:63], v[84:87]
	ds_read_b128 v[228:231], v173 offset:192
	s_waitcnt lgkmcnt(7)
	v_mfma_f32_16x16x32_bf16 v[88:91], v[232:235], v[60:63], v[88:91]
	ds_read_b128 v[232:235], v173 offset:8640
	s_waitcnt lgkmcnt(7)
	v_mfma_f32_16x16x32_bf16 v[92:95], v[236:239], v[60:63], v[92:95]
	ds_read_b128 v[236:239], v173 offset:17088
	s_waitcnt lgkmcnt(7)
	v_mfma_f32_16x16x32_bf16 v[96:99], v[240:243], v[60:63], v[96:99]
	ds_read_b128 v[240:243], v173 offset:25536
	s_waitcnt lgkmcnt(7)
	v_mfma_f32_16x16x32_bf16 v[84:87], v[204:207], v[56:59], v[84:87]
	ds_read_b128 v[204:207], v173 offset:256
	s_waitcnt lgkmcnt(7)
	v_mfma_f32_16x16x32_bf16 v[88:91], v[208:211], v[56:59], v[88:91]
	ds_read_b128 v[208:211], v173 offset:8704
	s_waitcnt lgkmcnt(7)
	v_mfma_f32_16x16x32_bf16 v[92:95], v[218:221], v[56:59], v[92:95]
	ds_read_b128 v[218:221], v173 offset:17152
	s_waitcnt lgkmcnt(7)
	v_mfma_f32_16x16x32_bf16 v[96:99], v[224:227], v[56:59], v[96:99]
	ds_read_b128 v[224:227], v173 offset:25600
	s_waitcnt lgkmcnt(7)
	v_mfma_f32_16x16x32_bf16 v[84:87], v[228:231], v[52:55], v[84:87]
	ds_read_b128 v[228:231], v173 offset:320
	s_waitcnt lgkmcnt(7)
	v_mfma_f32_16x16x32_bf16 v[88:91], v[232:235], v[52:55], v[88:91]
	ds_read_b128 v[232:235], v173 offset:8768
	s_waitcnt lgkmcnt(7)
	v_mfma_f32_16x16x32_bf16 v[92:95], v[236:239], v[52:55], v[92:95]
	ds_read_b128 v[236:239], v173 offset:17216
	s_waitcnt lgkmcnt(7)
	v_mfma_f32_16x16x32_bf16 v[96:99], v[240:243], v[52:55], v[96:99]
	ds_read_b128 v[240:243], v173 offset:25664
	s_waitcnt lgkmcnt(7)
	v_mfma_f32_16x16x32_bf16 v[84:87], v[204:207], v[48:51], v[84:87]
	ds_read_b128 v[204:207], v173 offset:384
	s_waitcnt lgkmcnt(7)
	v_mfma_f32_16x16x32_bf16 v[88:91], v[208:211], v[48:51], v[88:91]
	ds_read_b128 v[208:211], v173 offset:8832
	s_waitcnt lgkmcnt(7)
	v_mfma_f32_16x16x32_bf16 v[92:95], v[218:221], v[48:51], v[92:95]
	ds_read_b128 v[218:221], v173 offset:17280
	s_waitcnt lgkmcnt(7)
	v_mfma_f32_16x16x32_bf16 v[96:99], v[224:227], v[48:51], v[96:99]
	ds_read_b128 v[224:227], v173 offset:25728
	s_waitcnt lgkmcnt(7)
	v_mfma_f32_16x16x32_bf16 v[84:87], v[228:231], v[44:47], v[84:87]
	ds_read_b128 v[228:231], v173 offset:448
	s_waitcnt lgkmcnt(7)
	v_mfma_f32_16x16x32_bf16 v[88:91], v[232:235], v[44:47], v[88:91]
	ds_read_b128 v[232:235], v173 offset:8896
	s_waitcnt lgkmcnt(7)
	v_mfma_f32_16x16x32_bf16 v[92:95], v[236:239], v[44:47], v[92:95]
	ds_read_b128 v[236:239], v173 offset:17344
	s_waitcnt lgkmcnt(7)
	v_mfma_f32_16x16x32_bf16 v[96:99], v[240:243], v[44:47], v[96:99]
	s_waitcnt lgkmcnt(6)
	v_mfma_f32_16x16x32_bf16 v[84:87], v[204:207], v[8:11], v[84:87]
	s_waitcnt lgkmcnt(5)
	v_mfma_f32_16x16x32_bf16 v[88:91], v[208:211], v[8:11], v[88:91]
	s_waitcnt lgkmcnt(4)
	v_mfma_f32_16x16x32_bf16 v[92:95], v[218:221], v[8:11], v[92:95]
	s_waitcnt lgkmcnt(3)
	v_mfma_f32_16x16x32_bf16 v[96:99], v[224:227], v[8:11], v[96:99]
	s_waitcnt lgkmcnt(2)
	v_mfma_f32_16x16x32_bf16 v[84:87], v[228:231], v[4:7], v[84:87]
	s_waitcnt lgkmcnt(1)
	v_mfma_f32_16x16x32_bf16 v[88:91], v[232:235], v[4:7], v[88:91]
	s_waitcnt lgkmcnt(0)
	v_mfma_f32_16x16x32_bf16 v[92:95], v[236:239], v[4:7], v[92:95]
	s_nop 7
	ds_read_b128 v[100:103], v173 offset:25792
	s_waitcnt vmcnt(7)
	ds_write_b128 v170, v[28:31]
	s_waitcnt vmcnt(6)
	ds_write_b128 v170, v[32:35] offset:128
	s_waitcnt vmcnt(5)
	ds_write_b128 v170, v[36:39] offset:256
	s_waitcnt vmcnt(4)
	ds_write_b128 v170, v[40:43] offset:384
	global_load_dwordx4 v[28:31], v[166:167], off offset:2048
	global_load_dwordx4 v[32:35], v[166:167], off offset:2176
	global_load_dwordx4 v[36:39], v[166:167], off offset:2304
	global_load_dwordx4 v[40:43], v[166:167], off offset:2432
	s_waitcnt lgkmcnt(0)
	s_barrier
	s_waitcnt lgkmcnt(4)
	v_mfma_f32_16x16x32_bf16 v[96:99], v[100:103], v[4:7], v[96:99]
	ds_read_b128 v[204:207], v174
	ds_read_b128 v[208:211], v174 offset:8448
	ds_read_b128 v[218:221], v174 offset:16896
	ds_read_b128 v[224:227], v174 offset:25344
	ds_read_b128 v[228:231], v174 offset:64
	ds_read_b128 v[232:235], v174 offset:8512
	ds_read_b128 v[236:239], v174 offset:16960
	ds_read_b128 v[240:243], v174 offset:25408
	s_waitcnt lgkmcnt(7)
	v_mfma_f32_16x16x32_bf16 v[100:103], v[204:207], v[64:67], 0
	ds_read_b128 v[204:207], v174 offset:128
	s_waitcnt lgkmcnt(7)
	v_mfma_f32_16x16x32_bf16 v[104:107], v[208:211], v[64:67], 0
	ds_read_b128 v[208:211], v174 offset:8576
	s_waitcnt lgkmcnt(7)
	v_mfma_f32_16x16x32_bf16 v[108:111], v[218:221], v[64:67], 0
	ds_read_b128 v[218:221], v174 offset:17024
	s_waitcnt lgkmcnt(7)
	v_mfma_f32_16x16x32_bf16 v[112:115], v[224:227], v[64:67], 0
	ds_read_b128 v[224:227], v174 offset:25472
	s_waitcnt lgkmcnt(7)
	v_mfma_f32_16x16x32_bf16 v[100:103], v[228:231], v[60:63], v[100:103]
	ds_read_b128 v[228:231], v174 offset:192
	s_waitcnt lgkmcnt(7)
	v_mfma_f32_16x16x32_bf16 v[104:107], v[232:235], v[60:63], v[104:107]
	ds_read_b128 v[232:235], v174 offset:8640
	s_waitcnt lgkmcnt(7)
	v_mfma_f32_16x16x32_bf16 v[108:111], v[236:239], v[60:63], v[108:111]
	ds_read_b128 v[236:239], v174 offset:17088
	s_waitcnt lgkmcnt(7)
	v_mfma_f32_16x16x32_bf16 v[112:115], v[240:243], v[60:63], v[112:115]
	ds_read_b128 v[240:243], v174 offset:25536
	s_waitcnt lgkmcnt(7)
	v_mfma_f32_16x16x32_bf16 v[100:103], v[204:207], v[56:59], v[100:103]
	ds_read_b128 v[204:207], v174 offset:256
	s_waitcnt lgkmcnt(7)
	v_mfma_f32_16x16x32_bf16 v[104:107], v[208:211], v[56:59], v[104:107]
	ds_read_b128 v[208:211], v174 offset:8704
	s_waitcnt lgkmcnt(7)
	v_mfma_f32_16x16x32_bf16 v[108:111], v[218:221], v[56:59], v[108:111]
	ds_read_b128 v[218:221], v174 offset:17152
	s_waitcnt lgkmcnt(7)
	v_mfma_f32_16x16x32_bf16 v[112:115], v[224:227], v[56:59], v[112:115]
	ds_read_b128 v[224:227], v174 offset:25600
	s_waitcnt lgkmcnt(7)
	v_mfma_f32_16x16x32_bf16 v[100:103], v[228:231], v[52:55], v[100:103]
	ds_read_b128 v[228:231], v174 offset:320
	s_waitcnt lgkmcnt(7)
	v_mfma_f32_16x16x32_bf16 v[104:107], v[232:235], v[52:55], v[104:107]
	ds_read_b128 v[232:235], v174 offset:8768
	s_waitcnt lgkmcnt(7)
	v_mfma_f32_16x16x32_bf16 v[108:111], v[236:239], v[52:55], v[108:111]
	ds_read_b128 v[236:239], v174 offset:17216
	s_waitcnt lgkmcnt(7)
	v_mfma_f32_16x16x32_bf16 v[112:115], v[240:243], v[52:55], v[112:115]
	ds_read_b128 v[240:243], v174 offset:25664
	s_waitcnt lgkmcnt(7)
	v_mfma_f32_16x16x32_bf16 v[100:103], v[204:207], v[48:51], v[100:103]
	ds_read_b128 v[204:207], v174 offset:384
	s_waitcnt lgkmcnt(7)
	v_mfma_f32_16x16x32_bf16 v[104:107], v[208:211], v[48:51], v[104:107]
	ds_read_b128 v[208:211], v174 offset:8832
	s_waitcnt lgkmcnt(7)
	v_mfma_f32_16x16x32_bf16 v[108:111], v[218:221], v[48:51], v[108:111]
	ds_read_b128 v[218:221], v174 offset:17280
	s_waitcnt lgkmcnt(7)
	v_mfma_f32_16x16x32_bf16 v[112:115], v[224:227], v[48:51], v[112:115]
	ds_read_b128 v[224:227], v174 offset:25728
	s_waitcnt lgkmcnt(7)
	v_mfma_f32_16x16x32_bf16 v[100:103], v[228:231], v[44:47], v[100:103]
	ds_read_b128 v[228:231], v174 offset:448
	s_waitcnt lgkmcnt(7)
	v_mfma_f32_16x16x32_bf16 v[104:107], v[232:235], v[44:47], v[104:107]
	ds_read_b128 v[232:235], v174 offset:8896
	s_waitcnt lgkmcnt(7)
	v_mfma_f32_16x16x32_bf16 v[108:111], v[236:239], v[44:47], v[108:111]
	ds_read_b128 v[236:239], v174 offset:17344
	s_waitcnt lgkmcnt(7)
	v_mfma_f32_16x16x32_bf16 v[112:115], v[240:243], v[44:47], v[112:115]
	s_waitcnt lgkmcnt(6)
	v_mfma_f32_16x16x32_bf16 v[100:103], v[204:207], v[8:11], v[100:103]
	s_waitcnt lgkmcnt(5)
	v_mfma_f32_16x16x32_bf16 v[104:107], v[208:211], v[8:11], v[104:107]
	s_waitcnt lgkmcnt(4)
	v_mfma_f32_16x16x32_bf16 v[108:111], v[218:221], v[8:11], v[108:111]
	s_waitcnt lgkmcnt(3)
	v_mfma_f32_16x16x32_bf16 v[112:115], v[224:227], v[8:11], v[112:115]
	s_waitcnt lgkmcnt(2)
	v_mfma_f32_16x16x32_bf16 v[100:103], v[228:231], v[4:7], v[100:103]
	s_waitcnt lgkmcnt(1)
	v_mfma_f32_16x16x32_bf16 v[104:107], v[232:235], v[4:7], v[104:107]
	s_waitcnt lgkmcnt(0)
	v_mfma_f32_16x16x32_bf16 v[108:111], v[236:239], v[4:7], v[108:111]
	s_nop 7
	ds_read_b128 v[116:119], v174 offset:25792
	s_waitcnt vmcnt(7)
	ds_write_b128 v168, v[12:15]
	s_waitcnt vmcnt(6)
	ds_write_b128 v168, v[16:19] offset:128
	s_waitcnt vmcnt(5)
	ds_write_b128 v168, v[20:23] offset:256
	s_waitcnt vmcnt(4)
	ds_write_b128 v168, v[24:27] offset:384
	global_load_dwordx4 v[12:15], v[164:165], off offset:2048
	global_load_dwordx4 v[16:19], v[164:165], off offset:2176
	global_load_dwordx4 v[20:23], v[164:165], off offset:2304
	global_load_dwordx4 v[24:27], v[164:165], off offset:2432
	s_waitcnt lgkmcnt(0)
	s_barrier
	s_waitcnt lgkmcnt(4)
	v_mfma_f32_16x16x32_bf16 v[112:115], v[116:119], v[4:7], v[112:115]
	ds_read_b128 v[204:207], v173
	ds_read_b128 v[208:211], v173 offset:64
	ds_read_b128 v[218:221], v173 offset:128
	ds_read_b128 v[224:227], v173 offset:192
	ds_read_b128 v[228:231], v173 offset:256
	ds_read_b128 v[232:235], v173 offset:320
	ds_read_b128 v[236:239], v173 offset:384
	ds_read_b128 v[240:243], v173 offset:448
	s_waitcnt lgkmcnt(7)
	v_mfma_f32_16x16x32_bf16 v[116:119], v[204:207], v[64:67], 0
	ds_read_b128 v[204:207], v173 offset:8448
	s_waitcnt lgkmcnt(7)
	v_mfma_f32_16x16x32_bf16 v[116:119], v[208:211], v[60:63], v[116:119]
	ds_read_b128 v[208:211], v173 offset:8512
	s_waitcnt lgkmcnt(7)
	v_mfma_f32_16x16x32_bf16 v[116:119], v[218:221], v[56:59], v[116:119]
	ds_read_b128 v[218:221], v173 offset:8576
	s_waitcnt lgkmcnt(7)
	v_mfma_f32_16x16x32_bf16 v[116:119], v[224:227], v[52:55], v[116:119]
	ds_read_b128 v[224:227], v173 offset:8640
	s_waitcnt lgkmcnt(7)
	v_mfma_f32_16x16x32_bf16 v[116:119], v[228:231], v[48:51], v[116:119]
	ds_read_b128 v[228:231], v173 offset:8704
	s_waitcnt lgkmcnt(7)
	v_mfma_f32_16x16x32_bf16 v[116:119], v[232:235], v[44:47], v[116:119]
	ds_read_b128 v[232:235], v173 offset:8768
	s_waitcnt lgkmcnt(7)
	v_mfma_f32_16x16x32_bf16 v[116:119], v[236:239], v[8:11], v[116:119]
	ds_read_b128 v[236:239], v173 offset:8832
	s_waitcnt lgkmcnt(7)
	v_mfma_f32_16x16x32_bf16 v[116:119], v[240:243], v[4:7], v[116:119]
	ds_read_b128 v[240:243], v173 offset:8896
	s_waitcnt lgkmcnt(7)
	v_mfma_f32_16x16x32_bf16 v[120:123], v[204:207], v[64:67], 0
	ds_read_b128 v[204:207], v173 offset:16896
	s_waitcnt lgkmcnt(7)
	v_mfma_f32_16x16x32_bf16 v[120:123], v[208:211], v[60:63], v[120:123]
	ds_read_b128 v[208:211], v173 offset:16960
	s_waitcnt lgkmcnt(7)
	v_mfma_f32_16x16x32_bf16 v[120:123], v[218:221], v[56:59], v[120:123]
	ds_read_b128 v[218:221], v173 offset:17024
	s_waitcnt lgkmcnt(7)
	v_mfma_f32_16x16x32_bf16 v[120:123], v[224:227], v[52:55], v[120:123]
	ds_read_b128 v[224:227], v173 offset:17088
	s_waitcnt lgkmcnt(7)
	v_mfma_f32_16x16x32_bf16 v[120:123], v[228:231], v[48:51], v[120:123]
	ds_read_b128 v[228:231], v173 offset:17152
	s_waitcnt lgkmcnt(7)
	v_mfma_f32_16x16x32_bf16 v[120:123], v[232:235], v[44:47], v[120:123]
	ds_read_b128 v[232:235], v173 offset:17216
	s_waitcnt lgkmcnt(7)
	v_mfma_f32_16x16x32_bf16 v[120:123], v[236:239], v[8:11], v[120:123]
	ds_read_b128 v[236:239], v173 offset:17280
	s_waitcnt lgkmcnt(7)
	v_mfma_f32_16x16x32_bf16 v[120:123], v[240:243], v[4:7], v[120:123]
	ds_read_b128 v[240:243], v173 offset:17344
	s_waitcnt lgkmcnt(7)
	v_mfma_f32_16x16x32_bf16 v[124:127], v[204:207], v[64:67], 0
	ds_read_b128 v[204:207], v173 offset:25344
	s_waitcnt lgkmcnt(7)
	v_mfma_f32_16x16x32_bf16 v[124:127], v[208:211], v[60:63], v[124:127]
	ds_read_b128 v[208:211], v173 offset:25408
	s_waitcnt lgkmcnt(7)
	v_mfma_f32_16x16x32_bf16 v[124:127], v[218:221], v[56:59], v[124:127]
	ds_read_b128 v[218:221], v173 offset:25472
	s_waitcnt lgkmcnt(7)
	v_mfma_f32_16x16x32_bf16 v[124:127], v[224:227], v[52:55], v[124:127]
	ds_read_b128 v[224:227], v173 offset:25536
	s_waitcnt lgkmcnt(7)
	v_mfma_f32_16x16x32_bf16 v[124:127], v[228:231], v[48:51], v[124:127]
	ds_read_b128 v[228:231], v173 offset:25600
	s_waitcnt lgkmcnt(7)
	v_mfma_f32_16x16x32_bf16 v[124:127], v[232:235], v[44:47], v[124:127]
	ds_read_b128 v[232:235], v173 offset:25664
	s_waitcnt lgkmcnt(7)
	v_mfma_f32_16x16x32_bf16 v[124:127], v[236:239], v[8:11], v[124:127]
	ds_read_b128 v[236:239], v173 offset:25728
	s_waitcnt lgkmcnt(7)
	v_mfma_f32_16x16x32_bf16 v[124:127], v[240:243], v[4:7], v[124:127]
	ds_read_b128 v[240:243], v173 offset:25792
	s_waitcnt lgkmcnt(7)
	v_mfma_f32_16x16x32_bf16 v[64:67], v[204:207], v[64:67], 0
	s_waitcnt lgkmcnt(6)
	v_mfma_f32_16x16x32_bf16 v[60:63], v[208:211], v[60:63], v[64:67]
	s_nop 4
	s_waitcnt lgkmcnt(5)
	v_mfma_f32_16x16x32_bf16 v[56:59], v[218:221], v[56:59], v[60:63]
	s_nop 2
	s_waitcnt lgkmcnt(4)
	v_mfma_f32_16x16x32_bf16 v[52:55], v[224:227], v[52:55], v[56:59]
	s_nop 2
	s_waitcnt lgkmcnt(3)
	v_mfma_f32_16x16x32_bf16 v[48:51], v[228:231], v[48:51], v[52:55]
	s_nop 2
	s_waitcnt lgkmcnt(2)
	v_mfma_f32_16x16x32_bf16 v[44:47], v[232:235], v[44:47], v[48:51]
	s_nop 2
	s_waitcnt lgkmcnt(1)
	v_mfma_f32_16x16x32_bf16 v[8:11], v[236:239], v[8:11], v[44:47]
	s_nop 2
	s_waitcnt vmcnt(7)
	ds_write_b128 v170, v[28:31]
	s_waitcnt vmcnt(6)
	ds_write_b128 v170, v[32:35] offset:128
	s_waitcnt vmcnt(5)
	ds_write_b128 v170, v[36:39] offset:256
	s_waitcnt vmcnt(4)
	ds_write_b128 v170, v[40:43] offset:384
	global_load_dwordx4 v[28:31], v[162:163], off offset:2048
	global_load_dwordx4 v[32:35], v[162:163], off offset:2176
	global_load_dwordx4 v[36:39], v[162:163], off offset:2304
	global_load_dwordx4 v[40:43], v[162:163], off offset:2432
	s_waitcnt lgkmcnt(4)
	v_mfma_f32_16x16x32_bf16 v[4:7], v[240:243], v[4:7], v[8:11]
	s_nop 7
	s_nop 2
	v_max_f32_e32 v8, v71, v71
	v_max_f32_e32 v9, v70, v70
	v_max_f32_e32 v8, v9, v8
	v_max_f32_e32 v9, v75, v75
	v_max_f32_e32 v10, v74, v74
	v_max_f32_e32 v9, v10, v9
	v_max3_f32 v8, v68, v69, v8
	v_max3_f32 v9, v72, v73, v9
	v_max3_f32 v8, v8, s7, v9
	v_max_f32_e32 v9, v79, v79
	v_max_f32_e32 v10, v78, v78
	v_max_f32_e32 v9, v10, v9
	v_max_f32_e32 v10, v83, v83
	v_max_f32_e32 v11, v82, v82
	v_max_f32_e32 v10, v11, v10
	v_max3_f32 v9, v76, v77, v9
	v_max3_f32 v10, v80, v81, v10
	v_max3_f32 v8, v8, v9, v10
	v_max_f32_e32 v9, v87, v87
	v_max_f32_e32 v10, v86, v86
	v_max_f32_e32 v9, v10, v9
	v_max_f32_e32 v10, v91, v91
	v_max_f32_e32 v11, v90, v90
	v_max_f32_e32 v10, v11, v10
	v_max3_f32 v9, v84, v85, v9
	v_max3_f32 v10, v88, v89, v10
	v_max3_f32 v8, v8, v9, v10
	v_max_f32_e32 v9, v95, v95
	v_max_f32_e32 v10, v94, v94
	v_max_f32_e32 v9, v10, v9
	v_max_f32_e32 v10, v99, v99
	v_max_f32_e32 v11, v98, v98
	v_max_f32_e32 v10, v11, v10
	v_max3_f32 v9, v92, v93, v9
	v_max3_f32 v10, v96, v97, v10
	v_max3_f32 v8, v8, v9, v10
	v_max_f32_e32 v9, v103, v103
	v_max_f32_e32 v10, v102, v102
	v_max_f32_e32 v9, v10, v9
	v_max_f32_e32 v10, v107, v107
	v_max_f32_e32 v11, v106, v106
	v_max_f32_e32 v10, v11, v10
	v_max3_f32 v9, v100, v101, v9
	v_max3_f32 v10, v104, v105, v10
	v_max3_f32 v8, v8, v9, v10
	v_max_f32_e32 v9, v111, v111
	v_max_f32_e32 v10, v110, v110
	v_max_f32_e32 v9, v10, v9
	v_max_f32_e32 v10, v115, v115
	v_max_f32_e32 v11, v114, v114
	v_max_f32_e32 v10, v11, v10
	v_max3_f32 v9, v108, v109, v9
	v_max3_f32 v10, v112, v113, v10
	v_max3_f32 v8, v8, v9, v10
	v_max_f32_e32 v9, v119, v119
	v_max_f32_e32 v10, v118, v118
	v_max_f32_e32 v9, v10, v9
	v_max_f32_e32 v10, v123, v123
	v_max_f32_e32 v11, v122, v122
	v_max_f32_e32 v10, v11, v10
	v_max3_f32 v9, v116, v117, v9
	v_max3_f32 v10, v120, v121, v10
	v_max3_f32 v8, v8, v9, v10
	v_max_f32_e32 v9, v127, v127
	v_max_f32_e32 v10, v126, v126
	v_max_f32_e32 v9, v10, v9
	v_max_f32_e32 v10, v7, v7
	v_max_f32_e32 v11, v6, v6
	v_max_f32_e32 v10, v11, v10
	v_max3_f32 v9, v124, v125, v9
	v_max3_f32 v10, v4, v5, v10
	v_max3_f32 v8, v8, v9, v10
	ds_bpermute_b32 v9, v171, v8
	s_waitcnt lgkmcnt(0)
	s_barrier
	s_waitcnt lgkmcnt(0)
	v_max_f32_e32 v9, v9, v9
	v_max_f32_e32 v8, v8, v9
	ds_bpermute_b32 v9, v172, v8
	s_waitcnt lgkmcnt(0)
	v_max_f32_e32 v9, v9, v9
	v_max_f32_e32 v52, v8, v9
	v_sub_f32_e32 v8, v68, v52
	v_mul_f32_e32 v8, 0x3d800000, v8
	v_sub_f32_e32 v9, v69, v52
	v_mul_f32_e32 v8, 0x3fb8aa3b, v8
	v_mul_f32_e32 v9, 0x3d800000, v9
	v_exp_f32_e32 v8, v8
	v_mul_f32_e32 v9, 0x3fb8aa3b, v9
	v_exp_f32_e32 v9, v9
	v_sub_f32_e32 v56, v82, v52
	v_add_f32_e32 v10, 0, v8
	v_mul_f32_e32 v56, 0x3d800000, v56
	v_add_f32_e32 v11, v9, v10
	v_sub_f32_e32 v10, v70, v52
	v_mul_f32_e32 v10, 0x3d800000, v10
	v_mul_f32_e32 v10, 0x3fb8aa3b, v10
	v_exp_f32_e32 v10, v10
	v_mul_f32_e32 v56, 0x3fb8aa3b, v56
	v_exp_f32_e32 v60, v56
	v_sub_f32_e32 v56, v83, v52
	v_add_f32_e32 v44, v10, v11
	v_sub_f32_e32 v11, v71, v52
	v_mul_f32_e32 v56, 0x3d800000, v56
	v_mul_f32_e32 v11, 0x3d800000, v11
	v_mul_f32_e32 v56, 0x3fb8aa3b, v56
	v_mul_f32_e32 v11, 0x3fb8aa3b, v11
	v_exp_f32_e32 v61, v56
	v_sub_f32_e32 v56, v84, v52
	v_exp_f32_e32 v11, v11
	v_mul_f32_e32 v56, 0x3d800000, v56
	v_mul_f32_e32 v56, 0x3fb8aa3b, v56
	v_exp_f32_e32 v62, v56
	v_sub_f32_e32 v56, v85, v52
	v_mul_f32_e32 v56, 0x3d800000, v56
	v_add_f32_e32 v45, v11, v44
	v_sub_f32_e32 v44, v72, v52
	v_mul_f32_e32 v56, 0x3fb8aa3b, v56
	v_mul_f32_e32 v44, 0x3d800000, v44
	v_exp_f32_e32 v63, v56
	v_sub_f32_e32 v56, v86, v52
	v_mul_f32_e32 v44, 0x3fb8aa3b, v44
	v_mul_f32_e32 v56, 0x3d800000, v56
	v_exp_f32_e32 v44, v44
	v_mul_f32_e32 v56, 0x3fb8aa3b, v56
	v_exp_f32_e32 v64, v56
	v_sub_f32_e32 v56, v87, v52
	v_mul_f32_e32 v56, 0x3d800000, v56
	v_mul_f32_e32 v56, 0x3fb8aa3b, v56
	v_add_f32_e32 v46, v44, v45
	v_sub_f32_e32 v45, v73, v52
	v_exp_f32_e32 v65, v56
	v_sub_f32_e32 v56, v88, v52
	v_mul_f32_e32 v45, 0x3d800000, v45
	v_mul_f32_e32 v56, 0x3d800000, v56
	v_mul_f32_e32 v45, 0x3fb8aa3b, v45
	v_mul_f32_e32 v56, 0x3fb8aa3b, v56
	v_exp_f32_e32 v45, v45
	v_exp_f32_e32 v66, v56
	v_sub_f32_e32 v56, v89, v52
	v_mul_f32_e32 v56, 0x3d800000, v56
	v_mul_f32_e32 v56, 0x3fb8aa3b, v56
	v_exp_f32_e32 v67, v56
	v_sub_f32_e32 v56, v90, v52
	v_add_f32_e32 v47, v45, v46
	v_sub_f32_e32 v46, v74, v52
	v_mul_f32_e32 v56, 0x3d800000, v56
	v_mul_f32_e32 v46, 0x3d800000, v46
	v_mul_f32_e32 v56, 0x3fb8aa3b, v56
	v_mul_f32_e32 v46, 0x3fb8aa3b, v46
	v_exp_f32_e32 v68, v56
	v_sub_f32_e32 v56, v91, v52
	v_exp_f32_e32 v46, v46
	v_mul_f32_e32 v56, 0x3d800000, v56
	v_mul_f32_e32 v56, 0x3fb8aa3b, v56
	v_exp_f32_e32 v69, v56
	v_sub_f32_e32 v56, v92, v52
	v_mul_f32_e32 v56, 0x3d800000, v56
	v_add_f32_e32 v48, v46, v47
	v_sub_f32_e32 v47, v75, v52
	v_mul_f32_e32 v56, 0x3fb8aa3b, v56
	v_mul_f32_e32 v47, 0x3d800000, v47
	v_exp_f32_e32 v70, v56
	v_sub_f32_e32 v56, v93, v52
	v_mul_f32_e32 v47, 0x3fb8aa3b, v47
	v_mul_f32_e32 v56, 0x3d800000, v56
	v_exp_f32_e32 v47, v47
	v_mul_f32_e32 v56, 0x3fb8aa3b, v56
	v_exp_f32_e32 v71, v56
	v_sub_f32_e32 v56, v94, v52
	v_mul_f32_e32 v56, 0x3d800000, v56
	v_mul_f32_e32 v56, 0x3fb8aa3b, v56
	v_add_f32_e32 v49, v47, v48
	v_sub_f32_e32 v48, v76, v52
	v_exp_f32_e32 v72, v56
	v_sub_f32_e32 v56, v95, v52
	v_mul_f32_e32 v48, 0x3d800000, v48
	v_mul_f32_e32 v56, 0x3d800000, v56
	v_mul_f32_e32 v48, 0x3fb8aa3b, v48
	v_mul_f32_e32 v56, 0x3fb8aa3b, v56
	v_exp_f32_e32 v48, v48
	v_exp_f32_e32 v73, v56
	v_sub_f32_e32 v56, v96, v52
	v_mul_f32_e32 v56, 0x3d800000, v56
	v_mul_f32_e32 v56, 0x3fb8aa3b, v56
	v_exp_f32_e32 v74, v56
	v_sub_f32_e32 v56, v97, v52
	v_add_f32_e32 v50, v48, v49
	v_sub_f32_e32 v49, v77, v52
	v_mul_f32_e32 v56, 0x3d800000, v56
	v_mul_f32_e32 v49, 0x3d800000, v49
	v_mul_f32_e32 v56, 0x3fb8aa3b, v56
	v_mul_f32_e32 v49, 0x3fb8aa3b, v49
	v_exp_f32_e32 v75, v56
	v_sub_f32_e32 v56, v98, v52
	v_exp_f32_e32 v49, v49
	v_mul_f32_e32 v56, 0x3d800000, v56
	v_mul_f32_e32 v56, 0x3fb8aa3b, v56
	v_exp_f32_e32 v76, v56
	v_sub_f32_e32 v56, v99, v52
	v_mul_f32_e32 v56, 0x3d800000, v56
	v_add_f32_e32 v51, v49, v50
	v_sub_f32_e32 v50, v78, v52
	v_mul_f32_e32 v56, 0x3fb8aa3b, v56
	v_mul_f32_e32 v50, 0x3d800000, v50
	v_exp_f32_e32 v77, v56
	v_sub_f32_e32 v56, v100, v52
	v_mul_f32_e32 v50, 0x3fb8aa3b, v50
	v_mul_f32_e32 v56, 0x3d800000, v56
	v_exp_f32_e32 v50, v50
	v_mul_f32_e32 v56, 0x3fb8aa3b, v56
	v_exp_f32_e32 v78, v56
	v_sub_f32_e32 v56, v101, v52
	v_mul_f32_e32 v56, 0x3d800000, v56
	v_mul_f32_e32 v56, 0x3fb8aa3b, v56
	v_add_f32_e32 v53, v50, v51
	v_sub_f32_e32 v51, v79, v52
	v_exp_f32_e32 v79, v56
	v_sub_f32_e32 v56, v102, v52
	v_mul_f32_e32 v56, 0x3d800000, v56
	v_mul_f32_e32 v56, 0x3fb8aa3b, v56
	v_sub_f32_e32 v54, v80, v52
	v_exp_f32_e32 v80, v56
	v_sub_f32_e32 v56, v103, v52
	v_mul_f32_e32 v56, 0x3d800000, v56
	v_mul_f32_e32 v56, 0x3fb8aa3b, v56
	v_sub_f32_e32 v55, v81, v52
	v_exp_f32_e32 v81, v56
	v_sub_f32_e32 v56, v104, v52
	v_mul_f32_e32 v56, 0x3d800000, v56
	v_mul_f32_e32 v56, 0x3fb8aa3b, v56
	v_exp_f32_e32 v82, v56
	v_sub_f32_e32 v56, v105, v52
	v_mul_f32_e32 v56, 0x3d800000, v56
	v_mul_f32_e32 v56, 0x3fb8aa3b, v56
	v_exp_f32_e32 v83, v56
	v_sub_f32_e32 v56, v106, v52
	v_mul_f32_e32 v56, 0x3d800000, v56
	v_mul_f32_e32 v56, 0x3fb8aa3b, v56
	v_exp_f32_e32 v84, v56
	v_sub_f32_e32 v56, v107, v52
	v_mul_f32_e32 v56, 0x3d800000, v56
	v_mul_f32_e32 v56, 0x3fb8aa3b, v56
	v_exp_f32_e32 v85, v56
	v_sub_f32_e32 v56, v108, v52
	v_mul_f32_e32 v56, 0x3d800000, v56
	v_mul_f32_e32 v56, 0x3fb8aa3b, v56
	v_exp_f32_e32 v86, v56
	v_sub_f32_e32 v56, v109, v52
	v_mul_f32_e32 v56, 0x3d800000, v56
	v_mul_f32_e32 v56, 0x3fb8aa3b, v56
	v_exp_f32_e32 v87, v56
	v_sub_f32_e32 v56, v110, v52
	v_mul_f32_e32 v56, 0x3d800000, v56
	v_mul_f32_e32 v56, 0x3fb8aa3b, v56
	v_exp_f32_e32 v88, v56
	v_sub_f32_e32 v56, v111, v52
	v_mul_f32_e32 v51, 0x3d800000, v51
	v_mul_f32_e32 v56, 0x3d800000, v56
	v_mul_f32_e32 v51, 0x3fb8aa3b, v51
	v_mul_f32_e32 v54, 0x3d800000, v54
	v_mul_f32_e32 v56, 0x3fb8aa3b, v56
	v_exp_f32_e32 v51, v51
	v_mul_f32_e32 v54, 0x3fb8aa3b, v54
	v_mul_f32_e32 v55, 0x3d800000, v55
	v_exp_f32_e32 v89, v56
	v_sub_f32_e32 v56, v112, v52
	v_exp_f32_e32 v54, v54
	v_mul_f32_e32 v55, 0x3fb8aa3b, v55
	v_mul_f32_e32 v56, 0x3d800000, v56
	v_exp_f32_e32 v55, v55
	v_mul_f32_e32 v56, 0x3fb8aa3b, v56
	v_exp_f32_e32 v90, v56
	v_sub_f32_e32 v56, v113, v52
	v_add_f32_e32 v53, v51, v53
	v_mul_f32_e32 v56, 0x3d800000, v56
	v_add_f32_e32 v53, v54, v53
	v_mul_f32_e32 v56, 0x3fb8aa3b, v56
	v_add_f32_e32 v53, v55, v53
	v_exp_f32_e32 v91, v56
	v_sub_f32_e32 v56, v114, v52
	v_add_f32_e32 v53, v60, v53
	v_mul_f32_e32 v56, 0x3d800000, v56
	v_add_f32_e32 v53, v61, v53
	v_mul_f32_e32 v56, 0x3fb8aa3b, v56
	v_add_f32_e32 v53, v62, v53
	v_exp_f32_e32 v92, v56
	v_sub_f32_e32 v56, v115, v52
	v_add_f32_e32 v53, v63, v53
	v_mul_f32_e32 v56, 0x3d800000, v56
	v_add_f32_e32 v53, v64, v53
	v_mul_f32_e32 v56, 0x3fb8aa3b, v56
	v_add_f32_e32 v53, v65, v53
	v_exp_f32_e32 v93, v56
	v_sub_f32_e32 v56, v116, v52
	v_add_f32_e32 v53, v66, v53
	v_mul_f32_e32 v56, 0x3d800000, v56
	v_add_f32_e32 v53, v67, v53
	v_mul_f32_e32 v56, 0x3fb8aa3b, v56
	v_add_f32_e32 v53, v68, v53
	v_exp_f32_e32 v139, v56
	v_sub_f32_e32 v56, v117, v52
	v_add_f32_e32 v53, v69, v53
	v_mul_f32_e32 v56, 0x3d800000, v56
	v_add_f32_e32 v53, v70, v53
	v_mul_f32_e32 v56, 0x3fb8aa3b, v56
	v_add_f32_e32 v53, v71, v53
	v_exp_f32_e32 v140, v56
	v_sub_f32_e32 v56, v118, v52
	v_add_f32_e32 v53, v72, v53
	v_mul_f32_e32 v56, 0x3d800000, v56
	v_add_f32_e32 v53, v73, v53
	v_mul_f32_e32 v56, 0x3fb8aa3b, v56
	v_add_f32_e32 v53, v74, v53
	v_exp_f32_e32 v141, v56
	v_sub_f32_e32 v56, v119, v52
	v_add_f32_e32 v53, v75, v53
	v_mul_f32_e32 v56, 0x3d800000, v56
	v_add_f32_e32 v53, v76, v53
	v_mul_f32_e32 v56, 0x3fb8aa3b, v56
	v_add_f32_e32 v53, v77, v53
	v_exp_f32_e32 v142, v56
	v_sub_f32_e32 v56, v120, v52
	v_add_f32_e32 v53, v78, v53
	v_mul_f32_e32 v56, 0x3d800000, v56
	v_add_f32_e32 v53, v79, v53
	v_mul_f32_e32 v56, 0x3fb8aa3b, v56
	v_add_f32_e32 v53, v80, v53
	v_exp_f32_e32 v143, v56
	v_sub_f32_e32 v56, v121, v52
	v_add_f32_e32 v53, v81, v53
	v_mul_f32_e32 v56, 0x3d800000, v56
	v_add_f32_e32 v53, v82, v53
	v_mul_f32_e32 v56, 0x3fb8aa3b, v56
	v_add_f32_e32 v53, v83, v53
	v_exp_f32_e32 v144, v56
	v_sub_f32_e32 v56, v122, v52
	v_add_f32_e32 v53, v84, v53
	v_mul_f32_e32 v56, 0x3d800000, v56
	v_add_f32_e32 v53, v85, v53
	v_mul_f32_e32 v56, 0x3fb8aa3b, v56
	v_add_f32_e32 v53, v86, v53
	v_exp_f32_e32 v145, v56
	v_sub_f32_e32 v56, v123, v52
	v_add_f32_e32 v53, v87, v53
	v_mul_f32_e32 v56, 0x3d800000, v56
	v_add_f32_e32 v53, v88, v53
	v_mul_f32_e32 v56, 0x3fb8aa3b, v56
	v_add_f32_e32 v53, v89, v53
	v_exp_f32_e32 v146, v56
	v_sub_f32_e32 v56, v124, v52
	v_add_f32_e32 v53, v90, v53
	v_mul_f32_e32 v56, 0x3d800000, v56
	v_add_f32_e32 v53, v91, v53
	v_mul_f32_e32 v56, 0x3fb8aa3b, v56
	v_add_f32_e32 v53, v92, v53
	v_exp_f32_e32 v147, v56
	v_sub_f32_e32 v56, v125, v52
	v_add_f32_e32 v53, v93, v53
	v_mul_f32_e32 v56, 0x3d800000, v56
	v_add_f32_e32 v53, v139, v53
	v_mul_f32_e32 v56, 0x3fb8aa3b, v56
	v_add_f32_e32 v53, v140, v53
	v_exp_f32_e32 v148, v56
	v_sub_f32_e32 v56, v126, v52
	v_add_f32_e32 v53, v141, v53
	v_mul_f32_e32 v56, 0x3d800000, v56
	v_add_f32_e32 v53, v142, v53
	v_mul_f32_e32 v56, 0x3fb8aa3b, v56
	v_add_f32_e32 v53, v143, v53
	v_exp_f32_e32 v149, v56
	v_sub_f32_e32 v56, v127, v52
	v_add_f32_e32 v53, v144, v53
	v_mul_f32_e32 v56, 0x3d800000, v56
	v_sub_f32_e32 v4, v4, v52
	v_add_f32_e32 v53, v145, v53
	v_mul_f32_e32 v56, 0x3fb8aa3b, v56
	v_mul_f32_e32 v4, 0x3d800000, v4
	v_sub_f32_e32 v5, v5, v52
	v_add_f32_e32 v53, v146, v53
	v_exp_f32_e32 v150, v56
	v_mul_f32_e32 v4, 0x3fb8aa3b, v4
	v_mul_f32_e32 v5, 0x3d800000, v5
	v_add_f32_e32 v53, v147, v53
	v_exp_f32_e32 v151, v4
	v_mul_f32_e32 v5, 0x3fb8aa3b, v5
	v_add_f32_e32 v53, v148, v53
	v_exp_f32_e32 v152, v5
	v_sub_f32_e32 v5, v6, v52
	v_add_f32_e32 v53, v149, v53
	v_mul_f32_e32 v5, 0x3d800000, v5
	v_add_f32_e32 v53, v150, v53
	v_mul_f32_e32 v5, 0x3fb8aa3b, v5
	v_add_f32_e32 v4, v151, v53
	v_exp_f32_e32 v153, v5
	v_sub_f32_e32 v5, v7, v52
	v_cvt_pk_bf16_f32 v52, v48, v49
	v_cvt_pk_bf16_f32 v53, v50, v51
	v_cvt_pk_bf16_f32 v54, v54, v55
	v_cvt_pk_bf16_f32 v55, v60, v61
	v_cvt_pk_bf16_f32 v48, v62, v63
	v_cvt_pk_bf16_f32 v49, v64, v65
	v_cvt_pk_bf16_f32 v50, v66, v67
	v_cvt_pk_bf16_f32 v51, v68, v69
	ds_read_b64_tr_b16 v[204:205], v169
	ds_read_b64_tr_b16 v[206:207], v169 offset:8448
	ds_read_b64_tr_b16 v[208:209], v169 offset:16896
	ds_read_b64_tr_b16 v[210:211], v169 offset:25344
	ds_read_b64_tr_b16 v[218:219], v169 offset:32
	ds_read_b64_tr_b16 v[220:221], v169 offset:8480
	ds_read_b64_tr_b16 v[224:225], v169 offset:16928
	ds_read_b64_tr_b16 v[226:227], v169 offset:25376
	ds_read_b64_tr_b16 v[228:229], v169 offset:64
	ds_read_b64_tr_b16 v[230:231], v169 offset:8512
	ds_read_b64_tr_b16 v[232:233], v169 offset:16960
	ds_read_b64_tr_b16 v[234:235], v169 offset:25408
	ds_read_b64_tr_b16 v[236:237], v169 offset:96
	ds_read_b64_tr_b16 v[238:239], v169 offset:8544
	ds_read_b64_tr_b16 v[240:241], v169 offset:16992
	ds_read_b64_tr_b16 v[242:243], v169 offset:25440
	v_cvt_pk_bf16_f32 v56, v8, v9
	v_cvt_pk_bf16_f32 v57, v10, v11
	v_cvt_pk_bf16_f32 v58, v44, v45
	v_cvt_pk_bf16_f32 v59, v46, v47
	v_cvt_pk_bf16_f32 v44, v70, v71
	v_cvt_pk_bf16_f32 v45, v72, v73
	s_nop 1
	s_waitcnt lgkmcnt(14)
	v_mfma_f32_16x16x32_bf16 v[60:63], v[204:207], v[56:59], 0
	ds_read_b64_tr_b16 v[204:205], v169 offset:128
	ds_read_b64_tr_b16 v[206:207], v169 offset:8576
	v_cvt_pk_bf16_f32 v46, v74, v75
	v_cvt_pk_bf16_f32 v47, v76, v77
	v_cvt_pk_bf16_f32 v8, v78, v79
	s_nop 1
	s_waitcnt lgkmcnt(14)
	v_mfma_f32_16x16x32_bf16 v[60:63], v[208:211], v[52:55], v[60:63]
	ds_read_b64_tr_b16 v[208:209], v169 offset:17024
	ds_read_b64_tr_b16 v[210:211], v169 offset:25472
	v_mul_f32_e32 v5, 0x3d800000, v5
	v_mul_f32_e32 v5, 0x3fb8aa3b, v5
	s_nop 1
	s_waitcnt lgkmcnt(14)
	v_mfma_f32_16x16x32_bf16 v[64:67], v[218:221], v[56:59], 0
	ds_read_b64_tr_b16 v[218:219], v169 offset:160
	ds_read_b64_tr_b16 v[220:221], v169 offset:8608
	v_exp_f32_e32 v154, v5
	v_add_f32_e32 v4, v152, v4
	v_add_f32_e32 v4, v153, v4
	s_nop 1
	s_waitcnt lgkmcnt(14)
	v_mfma_f32_16x16x32_bf16 v[64:67], v[224:227], v[52:55], v[64:67]
	ds_read_b64_tr_b16 v[224:225], v169 offset:17056
	ds_read_b64_tr_b16 v[226:227], v169 offset:25504
	v_cvt_pk_bf16_f32 v9, v80, v81
	v_cvt_pk_bf16_f32 v10, v82, v83
	s_nop 1
	s_waitcnt lgkmcnt(14)
	v_mfma_f32_16x16x32_bf16 v[68:71], v[228:231], v[56:59], 0
	ds_read_b64_tr_b16 v[228:229], v169 offset:192
	ds_read_b64_tr_b16 v[230:231], v169 offset:8640
	v_add_f32_e32 v4, v154, v4
	ds_bpermute_b32 v5, v171, v4
	v_cvt_pk_bf16_f32 v11, v84, v85
	s_nop 1
	s_waitcnt lgkmcnt(15)
	v_mfma_f32_16x16x32_bf16 v[68:71], v[232:235], v[52:55], v[68:71]
	ds_read_b64_tr_b16 v[232:233], v169 offset:17088
	ds_read_b64_tr_b16 v[234:235], v169 offset:25536
	v_cvt_pk_bf16_f32 v6, v90, v91
	s_waitcnt lgkmcnt(2)
	v_add_f32_e32 v137, v4, v5
	s_nop 1
	s_waitcnt lgkmcnt(15)
	v_mfma_f32_16x16x32_bf16 v[72:75], v[236:239], v[56:59], 0
	ds_read_b64_tr_b16 v[236:237], v169 offset:224
	ds_read_b64_tr_b16 v[238:239], v169 offset:8672
	v_cvt_pk_bf16_f32 v4, v86, v87
	v_cvt_pk_bf16_f32 v5, v88, v89
	v_cvt_pk_bf16_f32 v7, v92, v93
	s_nop 1
	s_waitcnt lgkmcnt(15)
	v_mfma_f32_16x16x32_bf16 v[108:111], v[240:243], v[52:55], v[72:75]
	ds_read_b64_tr_b16 v[240:241], v169 offset:17120
	ds_read_b64_tr_b16 v[242:243], v169 offset:25568
	s_nop 2
	ds_bpermute_b32 v138, v172, v137
	s_waitcnt lgkmcnt(15)
	v_mfma_f32_16x16x32_bf16 v[72:75], v[204:207], v[56:59], 0
	ds_read_b64_tr_b16 v[204:205], v169 offset:256
	ds_read_b64_tr_b16 v[206:207], v169 offset:8704
	s_waitcnt lgkmcnt(15)
	v_mfma_f32_16x16x32_bf16 v[72:75], v[208:211], v[52:55], v[72:75]
	ds_read_b64_tr_b16 v[208:209], v169 offset:17152
	ds_read_b64_tr_b16 v[210:211], v169 offset:25600
	s_waitcnt lgkmcnt(15)
	v_mfma_f32_16x16x32_bf16 v[76:79], v[218:221], v[56:59], 0
	ds_read_b64_tr_b16 v[218:219], v169 offset:288
	ds_read_b64_tr_b16 v[220:221], v169 offset:8736
	s_waitcnt lgkmcnt(15)
	v_mfma_f32_16x16x32_bf16 v[76:79], v[224:227], v[52:55], v[76:79]
	ds_read_b64_tr_b16 v[224:225], v169 offset:17184
	ds_read_b64_tr_b16 v[226:227], v169 offset:25632
	s_waitcnt lgkmcnt(15)
	v_mfma_f32_16x16x32_bf16 v[80:83], v[228:231], v[56:59], 0
	ds_read_b64_tr_b16 v[228:229], v169 offset:320
	ds_read_b64_tr_b16 v[230:231], v169 offset:8768
	s_waitcnt lgkmcnt(15)
	v_mfma_f32_16x16x32_bf16 v[80:83], v[232:235], v[52:55], v[80:83]
	ds_read_b64_tr_b16 v[232:233], v169 offset:17216
	ds_read_b64_tr_b16 v[234:235], v169 offset:25664
	s_waitcnt lgkmcnt(15)
	v_mfma_f32_16x16x32_bf16 v[84:87], v[236:239], v[56:59], 0
	ds_read_b64_tr_b16 v[236:237], v169 offset:352
	ds_read_b64_tr_b16 v[238:239], v169 offset:8800
	s_waitcnt lgkmcnt(15)
	v_mfma_f32_16x16x32_bf16 v[112:115], v[240:243], v[52:55], v[84:87]
	ds_read_b64_tr_b16 v[240:241], v169 offset:17248
	ds_read_b64_tr_b16 v[242:243], v169 offset:25696
	s_nop 5
	s_waitcnt lgkmcnt(14)
	v_mfma_f32_16x16x32_bf16 v[84:87], v[204:207], v[56:59], 0
	ds_read_b64_tr_b16 v[204:205], v169 offset:384
	ds_read_b64_tr_b16 v[206:207], v169 offset:8832
	s_waitcnt lgkmcnt(14)
	v_mfma_f32_16x16x32_bf16 v[84:87], v[208:211], v[52:55], v[84:87]
	ds_read_b64_tr_b16 v[208:209], v169 offset:17280
	ds_read_b64_tr_b16 v[210:211], v169 offset:25728
	s_waitcnt lgkmcnt(14)
	v_mfma_f32_16x16x32_bf16 v[88:91], v[218:221], v[56:59], 0
	ds_read_b64_tr_b16 v[218:219], v169 offset:416
	ds_read_b64_tr_b16 v[220:221], v169 offset:8864
	s_waitcnt lgkmcnt(14)
	v_mfma_f32_16x16x32_bf16 v[88:91], v[224:227], v[52:55], v[88:91]
	ds_read_b64_tr_b16 v[224:225], v169 offset:17312
	ds_read_b64_tr_b16 v[226:227], v169 offset:25760
	s_waitcnt lgkmcnt(14)
	v_mfma_f32_16x16x32_bf16 v[92:95], v[228:231], v[56:59], 0
	ds_read_b64_tr_b16 v[228:229], v169 offset:448
	ds_read_b64_tr_b16 v[230:231], v169 offset:8896
	s_waitcnt lgkmcnt(14)
	v_mfma_f32_16x16x32_bf16 v[92:95], v[232:235], v[52:55], v[92:95]
	ds_read_b64_tr_b16 v[232:233], v169 offset:17344
	ds_read_b64_tr_b16 v[234:235], v169 offset:25792
	s_waitcnt lgkmcnt(14)
	v_mfma_f32_16x16x32_bf16 v[96:99], v[236:239], v[56:59], 0
	ds_read_b64_tr_b16 v[236:237], v169 offset:480
	ds_read_b64_tr_b16 v[238:239], v169 offset:8928
	s_waitcnt lgkmcnt(14)
	v_mfma_f32_16x16x32_bf16 v[116:119], v[240:243], v[52:55], v[96:99]
	s_nop 5
	s_waitcnt lgkmcnt(12)
	v_mfma_f32_16x16x32_bf16 v[96:99], v[204:207], v[56:59], 0
	s_waitcnt lgkmcnt(10)
	v_mfma_f32_16x16x32_bf16 v[96:99], v[208:211], v[52:55], v[96:99]
	s_waitcnt lgkmcnt(8)
	v_mfma_f32_16x16x32_bf16 v[100:103], v[218:221], v[56:59], 0
	s_waitcnt lgkmcnt(6)
	v_mfma_f32_16x16x32_bf16 v[100:103], v[224:227], v[52:55], v[100:103]
	s_waitcnt lgkmcnt(4)
	v_mfma_f32_16x16x32_bf16 v[104:107], v[228:231], v[56:59], 0
	s_waitcnt lgkmcnt(2)
	v_mfma_f32_16x16x32_bf16 v[104:107], v[232:235], v[52:55], v[104:107]
	ds_read_b64_tr_b16 v[124:125], v169 offset:17376
	ds_read_b64_tr_b16 v[126:127], v169 offset:25824
	s_waitcnt vmcnt(7)
	ds_write_b128 v168, v[12:15]
	s_waitcnt vmcnt(6)
	ds_write_b128 v168, v[16:19] offset:128
	s_waitcnt vmcnt(5)
	ds_write_b128 v168, v[20:23] offset:256
	s_waitcnt vmcnt(4)
	ds_write_b128 v168, v[24:27] offset:384
	global_load_dwordx4 v[12:15], v[160:161], off offset:2048
	global_load_dwordx4 v[16:19], v[160:161], off offset:2176
	global_load_dwordx4 v[20:23], v[160:161], off offset:2304
	global_load_dwordx4 v[24:27], v[160:161], off offset:2432
	s_waitcnt lgkmcnt(6)
	v_mfma_f32_16x16x32_bf16 v[56:59], v[236:239], v[56:59], 0
	s_nop 7
	s_waitcnt lgkmcnt(0)
	s_barrier
	s_waitcnt lgkmcnt(4)
	v_mfma_f32_16x16x32_bf16 v[120:123], v[124:127], v[52:55], v[56:59]
	ds_read_b64_tr_b16 v[204:205], v3
	ds_read_b64_tr_b16 v[206:207], v3 offset:8448
	ds_read_b64_tr_b16 v[208:209], v3 offset:32
	ds_read_b64_tr_b16 v[210:211], v3 offset:8480
	ds_read_b64_tr_b16 v[218:219], v3 offset:16928
	ds_read_b64_tr_b16 v[220:221], v3 offset:25376
	ds_read_b64_tr_b16 v[224:225], v3 offset:64
	ds_read_b64_tr_b16 v[226:227], v3 offset:8512
	ds_read_b64_tr_b16 v[228:229], v3 offset:16960
	ds_read_b64_tr_b16 v[230:231], v3 offset:25408
	ds_read_b64_tr_b16 v[232:233], v3 offset:96
	ds_read_b64_tr_b16 v[234:235], v3 offset:8544
	ds_read_b64_tr_b16 v[236:237], v3 offset:16992
	ds_read_b64_tr_b16 v[238:239], v3 offset:25440
	ds_read_b64_tr_b16 v[240:241], v3 offset:128
	ds_read_b64_tr_b16 v[242:243], v3 offset:8576
	s_nop 3
	s_waitcnt lgkmcnt(14)
	v_mfma_f32_16x16x32_bf16 v[52:55], v[204:207], v[48:51], v[60:63]
	ds_read_b64_tr_b16 v[204:205], v3 offset:17024
	ds_read_b64_tr_b16 v[206:207], v3 offset:25472
	s_nop 1
	s_waitcnt lgkmcnt(14)
	v_mfma_f32_16x16x32_bf16 v[56:59], v[208:211], v[48:51], v[64:67]
	ds_read_b64_tr_b16 v[208:209], v3 offset:160
	ds_read_b64_tr_b16 v[210:211], v3 offset:8608
	s_waitcnt lgkmcnt(14)
	v_mfma_f32_16x16x32_bf16 v[56:59], v[218:221], v[44:47], v[56:59]
	ds_read_b64_tr_b16 v[218:219], v3 offset:17056
	ds_read_b64_tr_b16 v[220:221], v3 offset:25504
	s_waitcnt lgkmcnt(14)
	v_mfma_f32_16x16x32_bf16 v[60:63], v[224:227], v[48:51], v[68:71]
	ds_read_b64_tr_b16 v[224:225], v3 offset:192
	ds_read_b64_tr_b16 v[226:227], v3 offset:8640
	s_waitcnt lgkmcnt(14)
	v_mfma_f32_16x16x32_bf16 v[60:63], v[228:231], v[44:47], v[60:63]
	ds_read_b64_tr_b16 v[228:229], v3 offset:16896
	ds_read_b64_tr_b16 v[230:231], v3 offset:25344
	s_waitcnt lgkmcnt(14)
	v_mfma_f32_16x16x32_bf16 v[64:67], v[232:235], v[48:51], v[108:111]
	ds_read_b64_tr_b16 v[232:233], v3 offset:17088
	ds_read_b64_tr_b16 v[234:235], v3 offset:25536
	s_waitcnt lgkmcnt(14)
	v_mfma_f32_16x16x32_bf16 v[64:67], v[236:239], v[44:47], v[64:67]
	ds_read_b64_tr_b16 v[236:237], v3 offset:224
	ds_read_b64_tr_b16 v[238:239], v3 offset:8672
	s_waitcnt lgkmcnt(14)
	v_mfma_f32_16x16x32_bf16 v[68:71], v[240:243], v[48:51], v[72:75]
	ds_read_b64_tr_b16 v[240:241], v3 offset:17120
	ds_read_b64_tr_b16 v[242:243], v3 offset:25568
	s_waitcnt lgkmcnt(14)
	v_mfma_f32_16x16x32_bf16 v[68:71], v[204:207], v[44:47], v[68:71]
	ds_read_b64_tr_b16 v[204:205], v3 offset:256
	ds_read_b64_tr_b16 v[206:207], v3 offset:8704
	s_nop 0
	s_waitcnt lgkmcnt(14)
	v_mfma_f32_16x16x32_bf16 v[72:75], v[208:211], v[48:51], v[76:79]
	ds_read_b64_tr_b16 v[208:209], v3 offset:17152
	ds_read_b64_tr_b16 v[210:211], v3 offset:25600
	s_waitcnt lgkmcnt(14)
	v_mfma_f32_16x16x32_bf16 v[108:111], v[218:221], v[44:47], v[72:75]
	ds_read_b64_tr_b16 v[218:219], v3 offset:288
	ds_read_b64_tr_b16 v[220:221], v3 offset:8736
	s_nop 5
	s_waitcnt lgkmcnt(14)
	v_mfma_f32_16x16x32_bf16 v[72:75], v[224:227], v[48:51], v[80:83]
	ds_read_b64_tr_b16 v[224:225], v3 offset:17184
	ds_read_b64_tr_b16 v[226:227], v3 offset:25632
	s_waitcnt lgkmcnt(14)
	v_mfma_f32_16x16x32_bf16 v[52:55], v[228:231], v[44:47], v[52:55]
	ds_read_b64_tr_b16 v[228:229], v3 offset:320
	ds_read_b64_tr_b16 v[230:231], v3 offset:8768
	s_waitcnt lgkmcnt(14)
	v_mfma_f32_16x16x32_bf16 v[124:127], v[232:235], v[44:47], v[72:75]
	ds_read_b64_tr_b16 v[232:233], v3 offset:17216
	ds_read_b64_tr_b16 v[234:235], v3 offset:25664
	s_nop 4
	s_waitcnt lgkmcnt(14)
	v_mfma_f32_16x16x32_bf16 v[72:75], v[236:239], v[48:51], v[112:115]
	ds_read_b64_tr_b16 v[236:237], v3 offset:352
	ds_read_b64_tr_b16 v[238:239], v3 offset:8800
	s_waitcnt lgkmcnt(14)
	v_mfma_f32_16x16x32_bf16 v[132:135], v[240:243], v[44:47], v[72:75]
	ds_read_b64_tr_b16 v[240:241], v3 offset:17248
	ds_read_b64_tr_b16 v[242:243], v3 offset:25696
	s_nop 5
	s_waitcnt lgkmcnt(14)
	v_mfma_f32_16x16x32_bf16 v[72:75], v[204:207], v[48:51], v[84:87]
	ds_read_b64_tr_b16 v[204:205], v3 offset:384
	ds_read_b64_tr_b16 v[206:207], v3 offset:8832
	s_waitcnt lgkmcnt(14)
	v_mfma_f32_16x16x32_bf16 v[112:115], v[208:211], v[44:47], v[72:75]
	ds_read_b64_tr_b16 v[208:209], v3 offset:17280
	ds_read_b64_tr_b16 v[210:211], v3 offset:25728
	s_nop 5
	s_waitcnt lgkmcnt(14)
	v_mfma_f32_16x16x32_bf16 v[72:75], v[218:221], v[48:51], v[88:91]
	ds_read_b64_tr_b16 v[218:219], v3 offset:416
	ds_read_b64_tr_b16 v[220:221], v3 offset:8864
	s_waitcnt lgkmcnt(14)
	v_mfma_f32_16x16x32_bf16 v[128:131], v[224:227], v[44:47], v[72:75]
	ds_read_b64_tr_b16 v[224:225], v3 offset:17312
	ds_read_b64_tr_b16 v[226:227], v3 offset:25760
	s_nop 5
	s_waitcnt lgkmcnt(14)
	v_mfma_f32_16x16x32_bf16 v[72:75], v[228:231], v[48:51], v[92:95]
	ds_read_b64_tr_b16 v[228:229], v3 offset:448
	ds_read_b64_tr_b16 v[230:231], v3 offset:8896
	s_waitcnt lgkmcnt(14)
	v_mfma_f32_16x16x32_bf16 v[92:95], v[232:235], v[44:47], v[72:75]
	ds_read_b64_tr_b16 v[232:233], v3 offset:17344
	ds_read_b64_tr_b16 v[234:235], v3 offset:25792
	s_nop 5
	s_waitcnt lgkmcnt(14)
	v_mfma_f32_16x16x32_bf16 v[72:75], v[236:239], v[48:51], v[116:119]
	s_waitcnt lgkmcnt(12)
	v_mfma_f32_16x16x32_bf16 v[116:119], v[240:243], v[44:47], v[72:75]
	s_nop 5
	s_waitcnt lgkmcnt(10)
	v_mfma_f32_16x16x32_bf16 v[72:75], v[204:207], v[48:51], v[96:99]
	s_waitcnt lgkmcnt(8)
	v_mfma_f32_16x16x32_bf16 v[96:99], v[208:211], v[44:47], v[72:75]
	s_nop 5
	s_waitcnt lgkmcnt(6)
	v_mfma_f32_16x16x32_bf16 v[72:75], v[218:221], v[48:51], v[100:103]
	s_waitcnt lgkmcnt(4)
	v_mfma_f32_16x16x32_bf16 v[100:103], v[224:227], v[44:47], v[72:75]
	s_nop 5
	s_waitcnt lgkmcnt(2)
	v_mfma_f32_16x16x32_bf16 v[72:75], v[228:231], v[48:51], v[104:107]
	s_waitcnt lgkmcnt(0)
	v_mfma_f32_16x16x32_bf16 v[104:107], v[232:235], v[44:47], v[72:75]
	s_nop 7
	s_nop 5
	ds_read_b64_tr_b16 v[72:73], v3 offset:480
	ds_read_b64_tr_b16 v[74:75], v3 offset:8928
	ds_read_b64_tr_b16 v[76:77], v3 offset:17376
	ds_read_b64_tr_b16 v[78:79], v3 offset:25824
	s_waitcnt vmcnt(7)
	ds_write_b128 v170, v[28:31]
	s_waitcnt vmcnt(6)
	ds_write_b128 v170, v[32:35] offset:128
	s_waitcnt vmcnt(5)
	ds_write_b128 v170, v[36:39] offset:256
	s_waitcnt vmcnt(4)
	ds_write_b128 v170, v[40:43] offset:384
	s_waitcnt lgkmcnt(0)
	s_barrier
	ds_read_b64_tr_b16 v[204:205], v169
	ds_read_b64_tr_b16 v[206:207], v169 offset:8448
	ds_read_b64_tr_b16 v[208:209], v169 offset:16896
	ds_read_b64_tr_b16 v[210:211], v169 offset:25344
	ds_read_b64_tr_b16 v[218:219], v169 offset:32
	ds_read_b64_tr_b16 v[220:221], v169 offset:8480
	ds_read_b64_tr_b16 v[224:225], v169 offset:16928
	ds_read_b64_tr_b16 v[226:227], v169 offset:25376
	ds_read_b64_tr_b16 v[228:229], v169 offset:64
	ds_read_b64_tr_b16 v[230:231], v169 offset:8512
	ds_read_b64_tr_b16 v[232:233], v169 offset:16960
	ds_read_b64_tr_b16 v[234:235], v169 offset:25408
	ds_read_b64_tr_b16 v[236:237], v169 offset:96
	ds_read_b64_tr_b16 v[238:239], v169 offset:8544
	ds_read_b64_tr_b16 v[240:241], v169 offset:16992
	ds_read_b64_tr_b16 v[242:243], v169 offset:25440
	v_mfma_f32_16x16x32_bf16 v[48:51], v[72:75], v[48:51], v[120:123]
	s_waitcnt lgkmcnt(14)
	v_mfma_f32_16x16x32_bf16 v[28:31], v[204:207], v[8:11], v[52:55]
	ds_read_b64_tr_b16 v[204:205], v169 offset:128
	ds_read_b64_tr_b16 v[206:207], v169 offset:8576
	v_mfma_f32_16x16x32_bf16 v[88:91], v[76:79], v[44:47], v[48:51]
	s_waitcnt lgkmcnt(14)
	v_mfma_f32_16x16x32_bf16 v[76:79], v[208:211], v[4:7], v[28:31]
	ds_read_b64_tr_b16 v[208:209], v169 offset:17024
	ds_read_b64_tr_b16 v[210:211], v169 offset:25472
	s_nop 3
	s_waitcnt lgkmcnt(14)
	v_mfma_f32_16x16x32_bf16 v[32:35], v[218:221], v[8:11], v[56:59]
	ds_read_b64_tr_b16 v[218:219], v169 offset:160
	ds_read_b64_tr_b16 v[220:221], v169 offset:8608
	s_waitcnt lgkmcnt(14)
	v_mfma_f32_16x16x32_bf16 v[80:83], v[224:227], v[4:7], v[32:35]
	ds_read_b64_tr_b16 v[224:225], v169 offset:17056
	ds_read_b64_tr_b16 v[226:227], v169 offset:25504
	s_nop 3
	s_waitcnt lgkmcnt(14)
	v_mfma_f32_16x16x32_bf16 v[28:31], v[228:231], v[8:11], v[60:63]
	ds_read_b64_tr_b16 v[228:229], v169 offset:192
	ds_read_b64_tr_b16 v[230:231], v169 offset:8640
	s_waitcnt lgkmcnt(14)
	v_mfma_f32_16x16x32_bf16 v[84:87], v[232:235], v[4:7], v[28:31]
	ds_read_b64_tr_b16 v[232:233], v169 offset:17088
	ds_read_b64_tr_b16 v[234:235], v169 offset:25536
	s_nop 5
	s_waitcnt lgkmcnt(14)
	v_mfma_f32_16x16x32_bf16 v[28:31], v[236:239], v[8:11], v[64:67]
	ds_read_b64_tr_b16 v[236:237], v169 offset:224
	ds_read_b64_tr_b16 v[238:239], v169 offset:8672
	s_waitcnt lgkmcnt(14)
	v_mfma_f32_16x16x32_bf16 v[72:75], v[240:243], v[4:7], v[28:31]
	ds_read_b64_tr_b16 v[240:241], v169 offset:17120
	ds_read_b64_tr_b16 v[242:243], v169 offset:25568
	s_nop 5
	s_waitcnt lgkmcnt(14)
	v_mfma_f32_16x16x32_bf16 v[28:31], v[204:207], v[8:11], v[68:71]
	ds_read_b64_tr_b16 v[204:205], v169 offset:256
	ds_read_b64_tr_b16 v[206:207], v169 offset:8704
	s_waitcnt lgkmcnt(14)
	v_mfma_f32_16x16x32_bf16 v[28:31], v[208:211], v[4:7], v[28:31]
	ds_read_b64_tr_b16 v[208:209], v169 offset:17152
	ds_read_b64_tr_b16 v[210:211], v169 offset:25600
	s_waitcnt lgkmcnt(14)
	v_mfma_f32_16x16x32_bf16 v[32:35], v[218:221], v[8:11], v[108:111]
	ds_read_b64_tr_b16 v[218:219], v169 offset:288
	ds_read_b64_tr_b16 v[220:221], v169 offset:8736
	s_waitcnt lgkmcnt(14)
	v_mfma_f32_16x16x32_bf16 v[32:35], v[224:227], v[4:7], v[32:35]
	ds_read_b64_tr_b16 v[224:225], v169 offset:17184
	ds_read_b64_tr_b16 v[226:227], v169 offset:25632
	s_waitcnt lgkmcnt(14)
	v_mfma_f32_16x16x32_bf16 v[36:39], v[228:231], v[8:11], v[124:127]
	ds_read_b64_tr_b16 v[228:229], v169 offset:320
	ds_read_b64_tr_b16 v[230:231], v169 offset:8768
	s_waitcnt lgkmcnt(14)
	v_mfma_f32_16x16x32_bf16 v[36:39], v[232:235], v[4:7], v[36:39]
	ds_read_b64_tr_b16 v[232:233], v169 offset:17216
	ds_read_b64_tr_b16 v[234:235], v169 offset:25664
	s_waitcnt lgkmcnt(14)
	v_mfma_f32_16x16x32_bf16 v[40:43], v[236:239], v[8:11], v[132:135]
	ds_read_b64_tr_b16 v[236:237], v169 offset:352
	ds_read_b64_tr_b16 v[238:239], v169 offset:8800
	s_waitcnt lgkmcnt(14)
	v_mfma_f32_16x16x32_bf16 v[64:67], v[240:243], v[4:7], v[40:43]
	ds_read_b64_tr_b16 v[240:241], v169 offset:17248
	ds_read_b64_tr_b16 v[242:243], v169 offset:25696
	s_nop 5
	s_waitcnt lgkmcnt(14)
	v_mfma_f32_16x16x32_bf16 v[40:43], v[204:207], v[8:11], v[112:115]
	ds_read_b64_tr_b16 v[204:205], v169 offset:384
	ds_read_b64_tr_b16 v[206:207], v169 offset:8832
	s_waitcnt lgkmcnt(14)
	v_mfma_f32_16x16x32_bf16 v[40:43], v[208:211], v[4:7], v[40:43]
	ds_read_b64_tr_b16 v[208:209], v169 offset:17280
	ds_read_b64_tr_b16 v[210:211], v169 offset:25728
	s_waitcnt lgkmcnt(14)
	v_mfma_f32_16x16x32_bf16 v[44:47], v[218:221], v[8:11], v[128:131]
	ds_read_b64_tr_b16 v[218:219], v169 offset:416
	ds_read_b64_tr_b16 v[220:221], v169 offset:8864
	s_waitcnt lgkmcnt(14)
	v_mfma_f32_16x16x32_bf16 v[44:47], v[224:227], v[4:7], v[44:47]
	ds_read_b64_tr_b16 v[224:225], v169 offset:17312
	ds_read_b64_tr_b16 v[226:227], v169 offset:25760
	s_waitcnt lgkmcnt(14)
	v_mfma_f32_16x16x32_bf16 v[48:51], v[228:231], v[8:11], v[92:95]
	ds_read_b64_tr_b16 v[228:229], v169 offset:448
	ds_read_b64_tr_b16 v[230:231], v169 offset:8896
	s_waitcnt lgkmcnt(14)
	v_mfma_f32_16x16x32_bf16 v[48:51], v[232:235], v[4:7], v[48:51]
	ds_read_b64_tr_b16 v[232:233], v169 offset:17344
	ds_read_b64_tr_b16 v[234:235], v169 offset:25792
	s_waitcnt lgkmcnt(14)
	v_mfma_f32_16x16x32_bf16 v[52:55], v[236:239], v[8:11], v[116:119]
	ds_read_b64_tr_b16 v[236:237], v169 offset:480
	ds_read_b64_tr_b16 v[238:239], v169 offset:8928
	s_waitcnt lgkmcnt(14)
	v_mfma_f32_16x16x32_bf16 v[68:71], v[240:243], v[4:7], v[52:55]
	s_nop 5
	s_waitcnt lgkmcnt(12)
	v_mfma_f32_16x16x32_bf16 v[52:55], v[204:207], v[8:11], v[96:99]
	s_waitcnt lgkmcnt(10)
	v_mfma_f32_16x16x32_bf16 v[52:55], v[208:211], v[4:7], v[52:55]
	s_waitcnt lgkmcnt(8)
	v_mfma_f32_16x16x32_bf16 v[56:59], v[218:221], v[8:11], v[100:103]
	s_waitcnt lgkmcnt(6)
	v_mfma_f32_16x16x32_bf16 v[56:59], v[224:227], v[4:7], v[56:59]
	s_waitcnt lgkmcnt(4)
	v_mfma_f32_16x16x32_bf16 v[60:63], v[228:231], v[8:11], v[104:107]
	s_waitcnt lgkmcnt(2)
	v_mfma_f32_16x16x32_bf16 v[60:63], v[232:235], v[4:7], v[60:63]
	ds_read_b64_tr_b16 v[96:97], v169 offset:17376
	ds_read_b64_tr_b16 v[98:99], v169 offset:25824
	s_waitcnt vmcnt(3)
	ds_write_b128 v168, v[12:15]
	s_waitcnt vmcnt(2)
	ds_write_b128 v168, v[16:19] offset:128
	s_waitcnt vmcnt(1)
	ds_write_b128 v168, v[20:23] offset:256
	s_waitcnt vmcnt(0)
	ds_write_b128 v168, v[24:27] offset:384
	s_waitcnt lgkmcnt(0)
	s_waitcnt lgkmcnt(6)
	v_mfma_f32_16x16x32_bf16 v[8:11], v[236:239], v[8:11], v[88:91]
	s_nop 7
	s_barrier
	v_cvt_pk_bf16_f32 v20, v139, v140
	s_waitcnt lgkmcnt(4)
	v_mfma_f32_16x16x32_bf16 v[4:7], v[96:99], v[4:7], v[8:11]
	s_nop 3
	ds_read_b64_tr_b16 v[204:205], v3
	ds_read_b64_tr_b16 v[206:207], v3 offset:8448
	ds_read_b64_tr_b16 v[208:209], v3 offset:16896
	ds_read_b64_tr_b16 v[210:211], v3 offset:25344
	ds_read_b64_tr_b16 v[218:219], v3 offset:32
	ds_read_b64_tr_b16 v[220:221], v3 offset:8480
	ds_read_b64_tr_b16 v[224:225], v3 offset:16928
	ds_read_b64_tr_b16 v[226:227], v3 offset:25376
	ds_read_b64_tr_b16 v[228:229], v3 offset:64
	ds_read_b64_tr_b16 v[230:231], v3 offset:8512
	ds_read_b64_tr_b16 v[232:233], v3 offset:16960
	ds_read_b64_tr_b16 v[234:235], v3 offset:25408
	ds_read_b64_tr_b16 v[236:237], v3 offset:96
	ds_read_b64_tr_b16 v[238:239], v3 offset:8544
	ds_read_b64_tr_b16 v[240:241], v3 offset:16992
	ds_read_b64_tr_b16 v[242:243], v3 offset:25440
	v_cvt_pk_bf16_f32 v21, v141, v142
	v_cvt_pk_bf16_f32 v22, v143, v144
	v_cvt_pk_bf16_f32 v23, v145, v146
	v_cvt_pk_bf16_f32 v16, v147, v148
	v_cvt_pk_bf16_f32 v17, v149, v150
	s_nop 1
	s_waitcnt lgkmcnt(14)
	v_mfma_f32_16x16x32_bf16 v[8:11], v[204:207], v[20:23], v[76:79]
	ds_read_b64_tr_b16 v[204:205], v3 offset:128
	ds_read_b64_tr_b16 v[206:207], v3 offset:8576
	v_cvt_pk_bf16_f32 v18, v151, v152
	v_cvt_pk_bf16_f32 v19, v153, v154
	v_add_u32_e32 v88, 0x80, v136
	v_ashrrev_i32_e32 v89, 31, v88
	s_nop 1
	s_waitcnt lgkmcnt(14)
	v_mfma_f32_16x16x32_bf16 v[12:15], v[208:211], v[16:19], v[8:11]
	ds_read_b64_tr_b16 v[208:209], v3 offset:17024
	ds_read_b64_tr_b16 v[210:211], v3 offset:25472
	s_nop 1
	s_waitcnt lgkmcnt(14)
	v_mfma_f32_16x16x32_bf16 v[24:27], v[218:221], v[20:23], v[80:83]
	ds_read_b64_tr_b16 v[218:219], v3 offset:160
	ds_read_b64_tr_b16 v[220:221], v3 offset:8608
	s_waitcnt lgkmcnt(14)
	v_mfma_f32_16x16x32_bf16 v[8:11], v[224:227], v[16:19], v[24:27]
	ds_read_b64_tr_b16 v[224:225], v3 offset:17056
	ds_read_b64_tr_b16 v[226:227], v3 offset:25504
	s_nop 5
	s_waitcnt lgkmcnt(14)
	v_mfma_f32_16x16x32_bf16 v[24:27], v[228:231], v[20:23], v[84:87]
	ds_read_b64_tr_b16 v[228:229], v3 offset:192
	ds_read_b64_tr_b16 v[230:231], v3 offset:8640
	s_waitcnt lgkmcnt(14)
	v_mfma_f32_16x16x32_bf16 v[24:27], v[232:235], v[16:19], v[24:27]
	ds_read_b64_tr_b16 v[232:233], v3 offset:17088
	ds_read_b64_tr_b16 v[234:235], v3 offset:25536
	s_waitcnt lgkmcnt(14)
	v_mfma_f32_16x16x32_bf16 v[72:75], v[236:239], v[20:23], v[72:75]
	ds_read_b64_tr_b16 v[236:237], v3 offset:224
	ds_read_b64_tr_b16 v[238:239], v3 offset:8672
	s_waitcnt lgkmcnt(14)
	v_mfma_f32_16x16x32_bf16 v[72:75], v[240:243], v[16:19], v[72:75]
	ds_read_b64_tr_b16 v[240:241], v3 offset:17120
	ds_read_b64_tr_b16 v[242:243], v3 offset:25568
	s_waitcnt lgkmcnt(14)
	v_mfma_f32_16x16x32_bf16 v[28:31], v[204:207], v[20:23], v[28:31]
	ds_read_b64_tr_b16 v[204:205], v3 offset:256
	ds_read_b64_tr_b16 v[206:207], v3 offset:8704
	s_waitcnt lgkmcnt(14)
	v_mfma_f32_16x16x32_bf16 v[28:31], v[208:211], v[16:19], v[28:31]
	ds_read_b64_tr_b16 v[208:209], v3 offset:17152
	ds_read_b64_tr_b16 v[210:211], v3 offset:25600
	s_waitcnt lgkmcnt(14)
	v_mfma_f32_16x16x32_bf16 v[32:35], v[218:221], v[20:23], v[32:35]
	ds_read_b64_tr_b16 v[218:219], v3 offset:288
	ds_read_b64_tr_b16 v[220:221], v3 offset:8736
	s_waitcnt lgkmcnt(14)
	v_mfma_f32_16x16x32_bf16 v[32:35], v[224:227], v[16:19], v[32:35]
	ds_read_b64_tr_b16 v[224:225], v3 offset:17184
	ds_read_b64_tr_b16 v[226:227], v3 offset:25632
	s_waitcnt lgkmcnt(14)
	v_mfma_f32_16x16x32_bf16 v[36:39], v[228:231], v[20:23], v[36:39]
	ds_read_b64_tr_b16 v[228:229], v3 offset:320
	ds_read_b64_tr_b16 v[230:231], v3 offset:8768
	s_waitcnt lgkmcnt(14)
	v_mfma_f32_16x16x32_bf16 v[36:39], v[232:235], v[16:19], v[36:39]
	ds_read_b64_tr_b16 v[232:233], v3 offset:17216
	ds_read_b64_tr_b16 v[234:235], v3 offset:25664
	s_waitcnt lgkmcnt(14)
	v_mfma_f32_16x16x32_bf16 v[64:67], v[236:239], v[20:23], v[64:67]
	ds_read_b64_tr_b16 v[236:237], v3 offset:352
	ds_read_b64_tr_b16 v[238:239], v3 offset:8800
	s_waitcnt lgkmcnt(14)
	v_mfma_f32_16x16x32_bf16 v[64:67], v[240:243], v[16:19], v[64:67]
	ds_read_b64_tr_b16 v[240:241], v3 offset:17248
	ds_read_b64_tr_b16 v[242:243], v3 offset:25696
	s_waitcnt lgkmcnt(14)
	v_mfma_f32_16x16x32_bf16 v[40:43], v[204:207], v[20:23], v[40:43]
	ds_read_b64_tr_b16 v[204:205], v3 offset:384
	ds_read_b64_tr_b16 v[206:207], v3 offset:8832
	s_waitcnt lgkmcnt(14)
	v_mfma_f32_16x16x32_bf16 v[40:43], v[208:211], v[16:19], v[40:43]
	ds_read_b64_tr_b16 v[208:209], v3 offset:17280
	ds_read_b64_tr_b16 v[210:211], v3 offset:25728
	s_waitcnt lgkmcnt(14)
	v_mfma_f32_16x16x32_bf16 v[44:47], v[218:221], v[20:23], v[44:47]
	ds_read_b64_tr_b16 v[218:219], v3 offset:416
	ds_read_b64_tr_b16 v[220:221], v3 offset:8864
	s_waitcnt lgkmcnt(14)
	v_mfma_f32_16x16x32_bf16 v[44:47], v[224:227], v[16:19], v[44:47]
	ds_read_b64_tr_b16 v[224:225], v3 offset:17312
	ds_read_b64_tr_b16 v[226:227], v3 offset:25760
	s_waitcnt lgkmcnt(14)
	v_mfma_f32_16x16x32_bf16 v[48:51], v[228:231], v[20:23], v[48:51]
	ds_read_b64_tr_b16 v[228:229], v3 offset:448
	ds_read_b64_tr_b16 v[230:231], v3 offset:8896
	s_waitcnt lgkmcnt(14)
	v_mfma_f32_16x16x32_bf16 v[48:51], v[232:235], v[16:19], v[48:51]
	ds_read_b64_tr_b16 v[232:233], v3 offset:17344
	ds_read_b64_tr_b16 v[234:235], v3 offset:25792
	s_waitcnt lgkmcnt(14)
	v_mfma_f32_16x16x32_bf16 v[68:71], v[236:239], v[20:23], v[68:71]
	ds_read_b64_tr_b16 v[236:237], v3 offset:480
	ds_read_b64_tr_b16 v[238:239], v3 offset:8928
	s_waitcnt lgkmcnt(14)
	v_mfma_f32_16x16x32_bf16 v[68:71], v[240:243], v[16:19], v[68:71]
	ds_read_b64_tr_b16 v[240:241], v3 offset:17376
	ds_read_b64_tr_b16 v[242:243], v3 offset:25824
	s_waitcnt lgkmcnt(14)
	v_mfma_f32_16x16x32_bf16 v[52:55], v[204:207], v[20:23], v[52:55]
	s_waitcnt lgkmcnt(12)
	v_mfma_f32_16x16x32_bf16 v[52:55], v[208:211], v[16:19], v[52:55]
	s_waitcnt lgkmcnt(10)
	v_mfma_f32_16x16x32_bf16 v[56:59], v[218:221], v[20:23], v[56:59]
	s_waitcnt lgkmcnt(8)
	v_mfma_f32_16x16x32_bf16 v[56:59], v[224:227], v[16:19], v[56:59]
	s_waitcnt lgkmcnt(6)
	v_mfma_f32_16x16x32_bf16 v[60:63], v[228:231], v[20:23], v[60:63]
	s_waitcnt lgkmcnt(4)
	v_mfma_f32_16x16x32_bf16 v[60:63], v[232:235], v[16:19], v[60:63]
	v_add_f32_e32 v3, v137, v138
	s_nop 1
	s_waitcnt lgkmcnt(2)
	v_mfma_f32_16x16x32_bf16 v[4:7], v[236:239], v[20:23], v[4:7]
	s_waitcnt lgkmcnt(0)
	v_mfma_f32_16x16x32_bf16 v[4:7], v[240:243], v[16:19], v[4:7]
	s_nop 7
	v_div_scale_f32 v16, s[12:13], v3, v3, 1.0
	v_rcp_f32_e32 v17, v16
	s_nop 0
	v_fma_f32 v18, -v16, v17, 1.0
	v_fmac_f32_e32 v17, v18, v17
	v_div_scale_f32 v18, vcc, 1.0, v3, 1.0
	v_mul_f32_e32 v19, v18, v17
	v_fma_f32 v20, -v16, v19, v18
	v_fmac_f32_e32 v19, v20, v17
	v_fma_f32 v16, -v16, v19, v18
	v_div_fmas_f32 v16, v16, v17, v19
	v_lshlrev_b64 v[18:19], 11, v[88:89]
	v_lshl_add_u64 v[18:19], s[10:11], 0, v[18:19]
	v_div_fixup_f32 v16, v16, v3, 1.0
	v_mad_i64_i32 v[18:19], s[6:7], s6, v155, v[18:19]
	v_lshl_add_u64 v[18:19], v[18:19], 0, s[8:9]
	v_pk_mul_f32 v[8:9], v[16:17], v[8:9] op_sel_hi:[0,1]
	v_pk_mul_f32 v[10:11], v[16:17], v[10:11] op_sel_hi:[0,1]
	v_lshl_add_u64 v[0:1], v[18:19], 0, v[0:1]
	v_cvt_pk_bf16_f32 v8, v8, v9
	v_cvt_pk_bf16_f32 v9, v10, v11
	global_store_dwordx2 v[0:1], v[8:9], off offset:32
	v_pk_mul_f32 v[8:9], v[16:17], v[24:25] op_sel_hi:[0,1]
	v_pk_mul_f32 v[10:11], v[16:17], v[26:27] op_sel_hi:[0,1]
	v_cvt_pk_bf16_f32 v8, v8, v9
	v_cvt_pk_bf16_f32 v9, v10, v11
	global_store_dwordx2 v[0:1], v[8:9], off offset:64
	v_pk_mul_f32 v[8:9], v[16:17], v[72:73] op_sel_hi:[0,1]
	v_pk_mul_f32 v[10:11], v[16:17], v[74:75] op_sel_hi:[0,1]
	v_cvt_pk_bf16_f32 v8, v8, v9
	v_cvt_pk_bf16_f32 v9, v10, v11
	global_store_dwordx2 v[0:1], v[8:9], off offset:96
	v_pk_mul_f32 v[8:9], v[16:17], v[28:29] op_sel_hi:[0,1]
	v_pk_mul_f32 v[10:11], v[16:17], v[30:31] op_sel_hi:[0,1]
	v_cvt_pk_bf16_f32 v8, v8, v9
	v_cvt_pk_bf16_f32 v9, v10, v11
	global_store_dwordx2 v[0:1], v[8:9], off offset:128
	v_pk_mul_f32 v[8:9], v[16:17], v[32:33] op_sel_hi:[0,1]
	v_pk_mul_f32 v[10:11], v[16:17], v[34:35] op_sel_hi:[0,1]
	v_cvt_pk_bf16_f32 v8, v8, v9
	v_cvt_pk_bf16_f32 v9, v10, v11
	global_store_dwordx2 v[0:1], v[8:9], off offset:160
	v_pk_mul_f32 v[8:9], v[16:17], v[36:37] op_sel_hi:[0,1]
	v_pk_mul_f32 v[10:11], v[16:17], v[38:39] op_sel_hi:[0,1]
	v_cvt_pk_bf16_f32 v8, v8, v9
	v_cvt_pk_bf16_f32 v9, v10, v11
	global_store_dwordx2 v[0:1], v[8:9], off offset:192
	v_pk_mul_f32 v[8:9], v[16:17], v[64:65] op_sel_hi:[0,1]
	v_pk_mul_f32 v[10:11], v[16:17], v[66:67] op_sel_hi:[0,1]
	v_cvt_pk_bf16_f32 v8, v8, v9
	v_cvt_pk_bf16_f32 v9, v10, v11
	global_store_dwordx2 v[0:1], v[8:9], off offset:224
	v_pk_mul_f32 v[8:9], v[16:17], v[40:41] op_sel_hi:[0,1]
	v_pk_mul_f32 v[10:11], v[16:17], v[42:43] op_sel_hi:[0,1]
	v_cvt_pk_bf16_f32 v8, v8, v9
	v_cvt_pk_bf16_f32 v9, v10, v11
	global_store_dwordx2 v[0:1], v[8:9], off offset:256
	v_pk_mul_f32 v[8:9], v[16:17], v[44:45] op_sel_hi:[0,1]
	v_pk_mul_f32 v[10:11], v[16:17], v[46:47] op_sel_hi:[0,1]
	v_cvt_pk_bf16_f32 v8, v8, v9
	v_cvt_pk_bf16_f32 v9, v10, v11
	global_store_dwordx2 v[0:1], v[8:9], off offset:288
	v_pk_mul_f32 v[8:9], v[16:17], v[48:49] op_sel_hi:[0,1]
	v_pk_mul_f32 v[10:11], v[16:17], v[50:51] op_sel_hi:[0,1]
	v_cvt_pk_bf16_f32 v8, v8, v9
	v_cvt_pk_bf16_f32 v9, v10, v11
	global_store_dwordx2 v[0:1], v[8:9], off offset:320
	v_pk_mul_f32 v[8:9], v[16:17], v[68:69] op_sel_hi:[0,1]
	v_pk_mul_f32 v[10:11], v[16:17], v[70:71] op_sel_hi:[0,1]
	v_cvt_pk_bf16_f32 v8, v8, v9
	v_cvt_pk_bf16_f32 v9, v10, v11
	global_store_dwordx2 v[0:1], v[8:9], off offset:352
	v_pk_mul_f32 v[8:9], v[16:17], v[52:53] op_sel_hi:[0,1]
	v_pk_mul_f32 v[10:11], v[16:17], v[54:55] op_sel_hi:[0,1]
	v_cvt_pk_bf16_f32 v8, v8, v9
	v_cvt_pk_bf16_f32 v9, v10, v11
	global_store_dwordx2 v[0:1], v[8:9], off offset:384
	v_pk_mul_f32 v[8:9], v[16:17], v[56:57] op_sel_hi:[0,1]
	v_pk_mul_f32 v[10:11], v[16:17], v[58:59] op_sel_hi:[0,1]
	v_cvt_pk_bf16_f32 v8, v8, v9
	v_cvt_pk_bf16_f32 v9, v10, v11
	v_pk_mul_f32 v[12:13], v[16:17], v[12:13] op_sel_hi:[0,1]
	v_pk_mul_f32 v[14:15], v[16:17], v[14:15] op_sel_hi:[0,1]
	global_store_dwordx2 v[0:1], v[8:9], off offset:416
	v_pk_mul_f32 v[8:9], v[16:17], v[60:61] op_sel_hi:[0,1]
	v_pk_mul_f32 v[10:11], v[16:17], v[62:63] op_sel_hi:[0,1]
	v_pk_mul_f32 v[4:5], v[16:17], v[4:5] op_sel_hi:[0,1]
	v_pk_mul_f32 v[6:7], v[16:17], v[6:7] op_sel_hi:[0,1]
	v_cvt_pk_bf16_f32 v12, v12, v13
	v_cvt_pk_bf16_f32 v13, v14, v15
	v_cvt_pk_bf16_f32 v8, v8, v9
	v_cvt_pk_bf16_f32 v9, v10, v11
	v_cvt_pk_bf16_f32 v4, v4, v5
	v_cvt_pk_bf16_f32 v5, v6, v7
	global_store_dwordx2 v[0:1], v[12:13], off
	global_store_dwordx2 v[0:1], v[8:9], off offset:448
	global_store_dwordx2 v[0:1], v[4:5], off offset:480
	s_waitcnt lgkmcnt(0)
	s_barrier
